# GEMM k-steps: tail MFMAs of each stage issued before the DMA-landing wait and stage barrier instead of after (43 sites)
# speedup vs baseline: 1.0006x; 1.0006x over previous
; #define WAIT_V0() asm volatile("s_waitcnt vmcnt(0)" ::: "memory")
; DI int glds_row(int i) { const int tid = ltid(); return ((tid >> 6) * 4 + i) * 8 + ((tid & 63) >> 3); }
; DI int glds_chunk(int row) { return (ltid() & 7) ^ ((row >> 1) & 7); }
; DI void gemm_core(char* smem, int nk, const char* Ab, const char* Bb, const unsigned (&aoff)[4], const unsigned (&boff)[4],
;                   f32x16 (&acc)[2][2]) {
;     ...
;   auto stage = [&](int buf, int kt) __attribute__((always_inline)) {
;     const char* ak = Ab + kt * 128;
;     const char* bk = Bb + kt * 128;
;     char* sa = smem + buf * STAGE_B + w * 4096;
; #pragma unroll
;     for (int i = 0; i < 4; ++i) {
;       __builtin_amdgcn_global_load_lds((const unsigned*)(ak + aoff[i]), (unsigned*)(sa + i * 1024), 16, 0, 0);
;       __builtin_amdgcn_global_load_lds((const unsigned*)(bk + boff[i]), (unsigned*)(sa + 16384 + i * 1024), 16, 0, 0);
;     }
;   };
;   stage(0, 0);
;   WAIT_V0();
;   __syncthreads();
; DI void phase_up(const Params& P, int layer, char* smem) {
;     ...
;   for (int t0 = blockIdx.x; t0 < MT * NT; t0 += gridDim.x) {
;     const int tl = xcd_tile(t0, MT * NT) - (t0 & 7) * ((MT * NT) >> 3);
;     const int mt = (t0 & 1) * 131 + tl / 11, nt = ((t0 & 7) >> 1) * 11 + tl % 11;
;     const int b = mt / 131, i = mt % 131;
;     const int tb0 = i * 126 - 2;
;     unsigned aoff[4], boff[4];
;     const char* Abase = (const char*)(hn + (size_t)b * S_ * 1024);
;     const unsigned zoff = (unsigned)((P.ws + OFF_ZPAGE) - Abase);
; #pragma unroll
;     for (int q = 0; q < 4; ++q) {
;       const int r = glds_row(q), ch = glds_chunk(r);
;       const int tb = tb0 + r;
;       const bool ok = (tb >= 0) && (tb < S_);
;       aoff[q] = ok ? (unsigned)((tb * 1024 + ch * 8) * 2) : zoff;
;       const int wr = (r < 64) ? (nt * 64 + r) : (DFF + nt * 64 + r - 64);
;       boff[q] = (unsigned)((wr * 1024 + ch * 8) * 2);
;     }
;     f32x16 acc[2][2];
;     gemm_core(smem, 16, Abase, (const char*)wup, aoff, boff, acc);
.LBB0_25:
	s_ashr_i32 s18, s2, 3
	s_and_b32 s19, s18, 0xffffffc0
	s_lshl_b32 s20, s18, 1
	s_bfe_u32 s21, s18, 0x10005
	s_and_b32 s20, s20, 62
	s_or_b32 s19, s21, s19
	s_or_b32 s19, s19, s20
	s_or_b32 s20, s18, 63
	s_cmpk_lt_i32 s20, 0x5a1
	s_cselect_b32 s18, s19, s18
	s_bitcmp1_b32 s2, 0
	s_mul_hi_i32 s20, s18, 0x2e8ba2e9
	s_cselect_b32 s19, 0x83, 0
	s_lshr_b32 s21, s20, 31
	s_ashr_i32 s20, s20, 1
	s_add_i32 s21, s20, s21
	s_add_i32 s20, s21, s19
	s_bfe_u32 s19, s2, 0x20001
	s_mul_i32 s21, s21, 11
	s_mul_i32 s19, s19, 11
	s_sub_i32 s18, s18, s21
	s_add_i32 s21, s18, s19
	s_mul_hi_i32 s18, s20, 0x3e88cb3d
	s_lshr_b32 s19, s18, 31
	s_ashr_i32 s18, s18, 5
	v_mov_b32_e32 v0, v161
	s_add_i32 s68, s18, s19
	s_mul_i32 s18, s68, 0x83
	v_ashrrev_i32_e32 v1, 1, v0
	v_lshrrev_b32_e32 v2, 3, v0
	v_bfe_u32 v0, v0, 3, 3
	s_movk_i32 s3, 0xffe0
	s_sub_i32 s28, s20, s18
	v_and_or_b32 v0, v1, s3, v0
	v_mov_b32_e32 v1, v161
	s_mulk_i32 s28, 0x7e
	s_ashr_i32 s69, s68, 31
	v_bfe_u32 v2, v2, 1, 2
	s_add_i32 s29, s28, -2
	s_lshl_b64 s[22:23], s[68:69], 25
	v_xor_b32_e32 v1, v2, v1
	s_add_u32 s18, s84, s22
	v_lshlrev_b32_e32 v1, 4, v1
	s_addc_u32 s19, s85, s23
	s_sub_i32 s22, 0x1b508000, s22
	s_lshl_b32 s21, s21, 6
	v_add_u32_e32 v2, s29, v0
	v_and_b32_e32 v1, 0x70, v1
	s_movk_i32 s3, 0x4000
	s_add_i32 s23, s21, 0xac0
	v_lshl_or_b32 v3, v2, 11, v1
	v_mov_b32_e32 v4, s22
	v_cmp_gt_u32_e32 vcc, s3, v2
	v_mov_b32_e32 v5, s21
	v_mov_b32_e32 v12, v161
	v_cndmask_b32_e32 v136, v4, v3, vcc
	v_mov_b32_e32 v3, s23
	v_cmp_gt_i32_e32 vcc, 64, v0
	v_lshl_add_u64 v[64:65], s[18:19], 0, v[136:137]
	s_mov_b64 s[4:5], 0x100
	v_cndmask_b32_e32 v2, v3, v5, vcc
	v_add_u32_e32 v0, v2, v0
	v_lshl_or_b32 v76, v0, 11, v1
	v_mov_b32_e32 v0, v161
	s_mov_b64 s[6:7], 0x780
	v_ashrrev_i32_e32 v1, 1, v0
	v_and_b32_e32 v1, 0xffffffe0, v1
	v_bfe_u32 v0, v0, 3, 3
	v_or3_b32 v1, v1, v0, 8
	v_mov_b32_e32 v0, v161
	v_lshrrev_b32_e32 v2, 1, v1
	v_xor_b32_e32 v0, v2, v0
	v_lshlrev_b32_e32 v0, 4, v0
	v_add_u32_e32 v2, s29, v1
	v_and_b32_e32 v6, 0x70, v0
	v_lshl_or_b32 v0, v2, 11, v6
	v_cmp_gt_u32_e32 vcc, s3, v2
	s_nop 1
	v_cndmask_b32_e32 v0, v4, v0, vcc
	v_cmp_gt_i32_e32 vcc, 64, v1
	s_nop 1
	v_cndmask_b32_e32 v2, v3, v5, vcc
	v_add_u32_e32 v1, v2, v1
	v_lshl_or_b32 v77, v1, 11, v6
	v_mov_b32_e32 v1, v161
	s_nop 0
	v_ashrrev_i32_e32 v2, 1, v1
	v_and_b32_e32 v2, 0xffffffe0, v2
	v_lshrrev_b32_e32 v6, 3, v1
	v_bfe_u32 v1, v1, 3, 3
	v_or3_b32 v1, v2, v1, 16
	v_mov_b32_e32 v2, v161
	v_bfe_u32 v6, v6, 1, 2
	v_xor_b32_e32 v2, v6, v2
	v_lshlrev_b32_e32 v2, 4, v2
	v_add_u32_e32 v6, s29, v1
	v_and_b32_e32 v7, 0x70, v2
	v_lshl_or_b32 v2, v6, 11, v7
	v_cmp_gt_u32_e32 vcc, s3, v6
	s_nop 1
	v_cndmask_b32_e32 v2, v4, v2, vcc
	v_cmp_gt_i32_e32 vcc, 64, v1
	s_nop 1
	v_cndmask_b32_e32 v6, v3, v5, vcc
	v_add_u32_e32 v1, v6, v1
	v_lshl_or_b32 v78, v1, 11, v7
	v_mov_b32_e32 v1, v161
	s_nop 0
	v_ashrrev_i32_e32 v6, 1, v1
	v_and_b32_e32 v6, 0xffffffe0, v6
	v_bfe_u32 v1, v1, 3, 3
	v_or3_b32 v1, v6, v1, 24
	v_mov_b32_e32 v6, v161
	v_lshrrev_b32_e32 v7, 1, v1
	v_xor_b32_e32 v6, v7, v6
	v_lshlrev_b32_e32 v6, 4, v6
	v_add_u32_e32 v7, s29, v1
	v_and_b32_e32 v6, 0x70, v6
	v_lshl_or_b32 v8, v7, 11, v6
	v_cmp_gt_u32_e32 vcc, s3, v7
	s_mov_b32 s3, 0x1ffffc0
	v_bfe_u32 v86, v12, 1, 3
	v_cndmask_b32_e32 v4, v4, v8, vcc
	v_cmp_gt_i32_e32 vcc, 64, v1
	v_bfe_u32 v117, v12, 5, 1
	s_nop 0
	v_cndmask_b32_e32 v3, v3, v5, vcc
	v_add_u32_e32 v1, v3, v1
	v_lshl_or_b32 v84, v1, 11, v6
	v_and_b32_e32 v1, 31, v12
	v_lshrrev_b32_e32 v5, 1, v12
	v_and_or_b32 v1, v5, s3, v1
	v_lshlrev_b32_e32 v87, 7, v1
	v_lshlrev_b32_e32 v1, 6, v12
	v_and_b32_e32 v97, 0xfffff000, v1
	v_add_u32_e32 v96, 0x4000, v97
	v_readfirstlane_b32 s84, v97
	s_mov_b32 m0, s84
	v_readfirstlane_b32 s85, v96
	v_or_b32_e32 v98, 0x400, v97
	global_load_lds_dwordx4 v136, s[18:19]
	s_mov_b32 m0, s85
	v_readfirstlane_b32 s86, v98
	v_add_u32_e32 v99, 0x4400, v97
	global_load_lds_dwordx4 v76, s[0:1]
	s_mov_b32 m0, s86
	v_readfirstlane_b32 s87, v99
	v_or_b32_e32 v100, 0x800, v97
	global_load_lds_dwordx4 v0, s[18:19]
	s_mov_b32 m0, s87
	v_readfirstlane_b32 s88, v100
	v_add_u32_e32 v101, 0x4800, v97
	v_lshrrev_b32_e32 v3, 5, v12
	global_load_lds_dwordx4 v77, s[0:1]
	s_mov_b32 m0, s88
	v_readfirstlane_b32 s89, v101
	v_or_b32_e32 v102, 0xc00, v97
	v_bitop3_b32 v3, v3, v86, 1 bitop3:0x6c
	global_load_lds_dwordx4 v2, s[18:19]
	s_mov_b32 m0, s89
	v_readfirstlane_b32 s90, v102
	v_add_u32_e32 v103, 0x4c00, v97
	v_lshlrev_b32_e32 v6, 4, v3
	v_mov_b32_e32 v1, v137
	v_mov_b32_e32 v3, v137
	global_load_lds_dwordx4 v78, s[0:1]
	v_mov_b32_e32 v5, v137
	s_mov_b32 m0, s90
	v_readfirstlane_b32 s91, v103
	v_add_u32_e32 v89, 0x8000, v97
	v_lshl_add_u64 v[66:67], s[18:19], 0, v[0:1]
	v_lshl_add_u64 v[68:69], s[18:19], 0, v[2:3]
	v_lshl_add_u64 v[70:71], s[18:19], 0, v[4:5]
	global_load_lds_dwordx4 v4, s[18:19]
	s_mov_b32 m0, s91
	v_add_u32_e32 v88, 0xc000, v97
	v_readfirstlane_b32 s18, v89
	global_load_lds_dwordx4 v84, s[0:1]
	v_lshl_add_u64 v[0:1], v[64:65], 0, s[94:95]
	s_mov_b32 m0, s18
	v_readfirstlane_b32 s19, v88
	v_add_u32_e32 v90, 0x8400, v97
	global_load_lds_dwordx4 v[0:1], off
	s_mov_b32 m0, s19
	v_readfirstlane_b32 s22, v90
	v_add_u32_e32 v91, 0xc400, v97
	global_load_lds_dwordx4 v76, s[14:15]
	v_lshl_add_u64 v[0:1], v[66:67], 0, s[94:95]
	s_mov_b32 m0, s22
	v_readfirstlane_b32 s23, v91
	v_add_u32_e32 v92, 0x8800, v97
	global_load_lds_dwordx4 v[0:1], off
	s_mov_b32 m0, s23
	v_readfirstlane_b32 s29, v92
	v_add_u32_e32 v93, 0xc800, v97
	global_load_lds_dwordx4 v77, s[14:15]
	v_lshl_add_u64 v[0:1], v[68:69], 0, s[94:95]
	s_mov_b32 m0, s29
	v_readfirstlane_b32 s69, v93
	v_add_u32_e32 v94, 0x8c00, v97
	global_load_lds_dwordx4 v[0:1], off
	s_mov_b32 m0, s69
	v_readfirstlane_b32 s70, v94
	v_add_u32_e32 v95, 0xcc00, v97
	global_load_lds_dwordx4 v78, s[14:15]
	v_lshl_add_u64 v[0:1], v[70:71], 0, s[94:95]
	s_mov_b32 m0, s70
	v_readfirstlane_b32 s71, v95
	global_load_lds_dwordx4 v[0:1], off
	s_mov_b32 m0, s71
	v_or_b32_e32 v79, v87, v6
	global_load_lds_dwordx4 v84, s[14:15]
	s_waitcnt vmcnt(8)
	s_waitcnt vmcnt(8) lgkmcnt(0)
	s_barrier
; #define WAIT_V0() asm volatile("s_waitcnt vmcnt(0)" ::: "memory")
; DI void gemm_core(char* smem, int nk, const char* Ab, const char* Bb, const unsigned (&aoff)[4], const unsigned (&boff)[4],
;                   f32x16 (&acc)[2][2]) {
;     ...
;   for (int kt = 0; kt < nk; ++kt) {
;     const int cur = kt & 1;
;     if (kt + 1 < nk) stage(cur ^ 1, kt + 1);
;     const char* sb = smem + cur * STAGE_B;
; #pragma unroll
;     for (int ks = 0; ks < 4; ++ks) {
;       bf16x8 af[2], bfr[2];
; #pragma unroll
;       for (int mb = 0; mb < 2; ++mb) af[mb] = *(const bf16x8*)(sb + a_base + mb * 4096 + xo[ks]);
; #pragma unroll
;       for (int nb = 0; nb < 2; ++nb) bfr[nb] = *(const bf16x8*)(sb + b_base + nb * 4096 + xo[ks]);
; #pragma unroll
;       for (int mb = 0; mb < 2; ++mb)
; #pragma unroll
;         for (int nb = 0; nb < 2; ++nb)
;           acc[mb][nb] = __builtin_amdgcn_mfma_f32_32x32x16_bf16(af[mb], bfr[nb], acc[mb][nb], 0, 0, 0);
;     }
;     WAIT_V0();
;     __syncthreads();
;   }
	ds_read_b128 v[0:3], v79
	v_lshlrev_b32_e32 v4, 7, v12
	v_and_b32_e32 v116, 0x2f80, v4
	v_or_b32_e32 v81, v116, v6
	ds_read_b128 v[4:7], v81 offset:16384
	ds_read_b128 v[8:11], v81 offset:20480
	s_waitcnt lgkmcnt(0)
	v_mfma_f32_32x32x16_bf16 v[48:63], v[0:3], v[4:7], 0
	s_mov_b32 m0, s84
	s_mov_b32 s3, 0xfffffc0
	v_mfma_f32_32x32x16_bf16 v[32:47], v[0:3], v[8:11], 0
	ds_read_b128 v[0:3], v79 offset:4096
	s_waitcnt lgkmcnt(0)
	v_mfma_f32_32x32x16_bf16 v[16:31], v[0:3], v[4:7], 0
	v_bitop3_b32 v4, v117, v86, 2 bitop3:0x36
	v_lshlrev_b32_e32 v82, 4, v4
	v_or_b32_e32 v80, v87, v82
	ds_read_b128 v[104:107], v80
	v_or_b32_e32 v83, v116, v82
	ds_read_b128 v[108:111], v83 offset:16384
	ds_read_b128 v[112:115], v83 offset:20480
	s_waitcnt lgkmcnt(0)
	v_mfma_f32_32x32x16_bf16 v[48:63], v[104:107], v[108:111], v[48:63]
	v_bitop3_b32 v82, v117, v86, 4 bitop3:0x36
	v_lshlrev_b32_e32 v85, 4, v82
	v_or_b32_e32 v82, v87, v85
	v_or_b32_e32 v85, v116, v85
	v_bitop3_b32 v86, v117, v86, 6 bitop3:0x36
	v_mfma_f32_32x32x16_bf16 v[32:47], v[104:107], v[112:115], v[32:47]
	ds_read_b128 v[104:107], v80 offset:4096
	v_mfma_f32_32x32x16_bf16 v[0:15], v[0:3], v[8:11], 0
	s_waitcnt lgkmcnt(0)
	v_mfma_f32_32x32x16_bf16 v[16:31], v[104:107], v[108:111], v[16:31]
	ds_read_b128 v[108:111], v85 offset:16384
	v_mfma_f32_32x32x16_bf16 v[0:15], v[104:107], v[112:115], v[0:15]
	ds_read_b128 v[104:107], v82
	ds_read_b128 v[112:115], v85 offset:20480
	s_waitcnt lgkmcnt(0)
	v_mfma_f32_32x32x16_bf16 v[48:63], v[104:107], v[108:111], v[48:63]
	v_mfma_f32_32x32x16_bf16 v[32:47], v[104:107], v[112:115], v[32:47]
	ds_read_b128 v[104:107], v82 offset:4096
	s_waitcnt lgkmcnt(0)
	v_mfma_f32_32x32x16_bf16 v[16:31], v[104:107], v[108:111], v[16:31]
	v_lshlrev_b32_e32 v108, 4, v86
	v_or_b32_e32 v86, v87, v108
	v_or_b32_e32 v87, v116, v108
	ds_read_b128 v[108:111], v87 offset:16384
	v_mfma_f32_32x32x16_bf16 v[0:15], v[104:107], v[112:115], v[0:15]
	ds_read_b128 v[104:107], v86
	ds_read_b128 v[112:115], v87 offset:20480
	s_waitcnt lgkmcnt(0)
	v_mfma_f32_32x32x16_bf16 v[48:63], v[104:107], v[108:111], v[48:63]
	v_mfma_f32_32x32x16_bf16 v[32:47], v[104:107], v[112:115], v[32:47]
	ds_read_b128 v[104:107], v86 offset:4096
	s_waitcnt lgkmcnt(0)
	v_mfma_f32_32x32x16_bf16 v[16:31], v[104:107], v[108:111], v[16:31]
	v_mfma_f32_32x32x16_bf16 v[0:15], v[104:107], v[112:115], v[0:15]
	s_waitcnt vmcnt(0)
	s_barrier
	ds_read_b128 v[104:107], v79 offset:32768
	ds_read_b128 v[108:111], v81 offset:49152
	ds_read_b128 v[112:115], v81 offset:53248
	v_lshl_add_u64 v[140:141], v[64:65], 0, s[4:5]
	global_load_lds_dwordx4 v[140:141], off
	s_mov_b32 m0, s85
	v_lshl_add_u64 v[142:143], v[66:67], 0, s[4:5]
	global_load_lds_dwordx4 v76, s[16:17]
	s_mov_b32 m0, s86
	s_nop 0
	global_load_lds_dwordx4 v[142:143], off
	s_mov_b32 m0, s87
	v_lshl_add_u64 v[140:141], v[68:69], 0, s[4:5]
	global_load_lds_dwordx4 v77, s[16:17]
	s_mov_b32 m0, s88
	s_nop 0
	global_load_lds_dwordx4 v[140:141], off
	s_mov_b32 m0, s89
	v_lshl_add_u64 v[142:143], v[70:71], 0, s[4:5]
	global_load_lds_dwordx4 v78, s[16:17]
	s_mov_b32 m0, s90
	s_mov_b64 s[4:5], 0x180
	global_load_lds_dwordx4 v[142:143], off
	s_mov_b32 m0, s91
	s_nop 0
	global_load_lds_dwordx4 v84, s[16:17]
	s_waitcnt lgkmcnt(0)
	v_mfma_f32_32x32x16_bf16 v[48:63], v[104:107], v[108:111], v[48:63]
	s_mov_b32 m0, s18
	v_mfma_f32_32x32x16_bf16 v[32:47], v[104:107], v[112:115], v[32:47]
	ds_read_b128 v[104:107], v79 offset:36864
	s_waitcnt lgkmcnt(0)
	v_mfma_f32_32x32x16_bf16 v[16:31], v[104:107], v[108:111], v[16:31]
	v_mfma_f32_32x32x16_bf16 v[0:15], v[104:107], v[112:115], v[0:15]
	ds_read_b128 v[104:107], v80 offset:32768
	ds_read_b128 v[108:111], v83 offset:49152
	ds_read_b128 v[112:115], v83 offset:53248
	s_waitcnt lgkmcnt(0)
	v_mfma_f32_32x32x16_bf16 v[48:63], v[104:107], v[108:111], v[48:63]
	v_mfma_f32_32x32x16_bf16 v[32:47], v[104:107], v[112:115], v[32:47]
	ds_read_b128 v[104:107], v80 offset:36864
	s_waitcnt lgkmcnt(0)
	v_mfma_f32_32x32x16_bf16 v[16:31], v[104:107], v[108:111], v[16:31]
	v_mfma_f32_32x32x16_bf16 v[0:15], v[104:107], v[112:115], v[0:15]
	ds_read_b128 v[104:107], v82 offset:32768
	ds_read_b128 v[108:111], v85 offset:49152
	ds_read_b128 v[112:115], v85 offset:53248
	s_waitcnt lgkmcnt(0)
	v_mfma_f32_32x32x16_bf16 v[48:63], v[104:107], v[108:111], v[48:63]
	v_mfma_f32_32x32x16_bf16 v[32:47], v[104:107], v[112:115], v[32:47]
	ds_read_b128 v[104:107], v82 offset:36864
	s_waitcnt lgkmcnt(0)
	v_mfma_f32_32x32x16_bf16 v[16:31], v[104:107], v[108:111], v[16:31]
	v_mfma_f32_32x32x16_bf16 v[0:15], v[104:107], v[112:115], v[0:15]
	ds_read_b128 v[104:107], v86 offset:32768
	ds_read_b128 v[108:111], v87 offset:49152
	ds_read_b128 v[112:115], v87 offset:53248
	s_waitcnt lgkmcnt(0)
	v_mfma_f32_32x32x16_bf16 v[48:63], v[104:107], v[108:111], v[48:63]
	v_mfma_f32_32x32x16_bf16 v[32:47], v[104:107], v[112:115], v[32:47]
	ds_read_b128 v[104:107], v86 offset:36864
	s_waitcnt lgkmcnt(0)
	v_mfma_f32_32x32x16_bf16 v[16:31], v[104:107], v[108:111], v[16:31]
	v_mfma_f32_32x32x16_bf16 v[0:15], v[104:107], v[112:115], v[0:15]
	s_waitcnt vmcnt(0)
	s_barrier
; #define WAIT_V0() asm volatile("s_waitcnt vmcnt(0)" ::: "memory")
; DI void gemm_core(char* smem, int nk, const char* Ab, const char* Bb, const unsigned (&aoff)[4], const unsigned (&boff)[4],
;                   f32x16 (&acc)[2][2]) {
;     ...
;   for (int kt = 0; kt < nk; ++kt) {
;     const int cur = kt & 1;
;     if (kt + 1 < nk) stage(cur ^ 1, kt + 1);
;     const char* sb = smem + cur * STAGE_B;
; #pragma unroll
;     for (int ks = 0; ks < 4; ++ks) {
;       bf16x8 af[2], bfr[2];
; #pragma unroll
;       for (int mb = 0; mb < 2; ++mb) af[mb] = *(const bf16x8*)(sb + a_base + mb * 4096 + xo[ks]);
; #pragma unroll
;       for (int nb = 0; nb < 2; ++nb) bfr[nb] = *(const bf16x8*)(sb + b_base + nb * 4096 + xo[ks]);
; #pragma unroll
;       for (int mb = 0; mb < 2; ++mb)
; #pragma unroll
;         for (int nb = 0; nb < 2; ++nb)
;           acc[mb][nb] = __builtin_amdgcn_mfma_f32_32x32x16_bf16(af[mb], bfr[nb], acc[mb][nb], 0, 0, 0);
;     }
;     WAIT_V0();
;     __syncthreads();
;   }
	ds_read_b128 v[104:107], v79
	ds_read_b128 v[108:111], v81 offset:16384
	ds_read_b128 v[112:115], v81 offset:20480
	v_lshl_add_u64 v[140:141], v[64:65], 0, s[4:5]
	global_load_lds_dwordx4 v[140:141], off
	s_mov_b32 m0, s19
	v_lshl_add_u64 v[142:143], v[66:67], 0, s[4:5]
	global_load_lds_dwordx4 v76, s[42:43]
	s_mov_b32 m0, s22
	s_nop 0
	global_load_lds_dwordx4 v[142:143], off
	s_mov_b32 m0, s23
	v_lshl_add_u64 v[140:141], v[68:69], 0, s[4:5]
	global_load_lds_dwordx4 v77, s[42:43]
	s_mov_b32 m0, s29
	s_nop 0
	global_load_lds_dwordx4 v[140:141], off
	s_mov_b32 m0, s69
	v_lshl_add_u64 v[142:143], v[70:71], 0, s[4:5]
	global_load_lds_dwordx4 v78, s[42:43]
	s_mov_b32 m0, s70
	s_mov_b64 s[4:5], 0x280
	global_load_lds_dwordx4 v[142:143], off
	s_mov_b32 m0, s71
	s_nop 0
	global_load_lds_dwordx4 v84, s[42:43]
	s_waitcnt lgkmcnt(0)
	v_mfma_f32_32x32x16_bf16 v[48:63], v[104:107], v[108:111], v[48:63]
	s_mov_b32 m0, s84
	v_mfma_f32_32x32x16_bf16 v[32:47], v[104:107], v[112:115], v[32:47]
	ds_read_b128 v[104:107], v79 offset:4096
	s_waitcnt lgkmcnt(0)
	v_mfma_f32_32x32x16_bf16 v[16:31], v[104:107], v[108:111], v[16:31]
	v_mfma_f32_32x32x16_bf16 v[0:15], v[104:107], v[112:115], v[0:15]
	ds_read_b128 v[104:107], v80
	ds_read_b128 v[108:111], v83 offset:16384
	ds_read_b128 v[112:115], v83 offset:20480
	s_waitcnt lgkmcnt(0)
	v_mfma_f32_32x32x16_bf16 v[48:63], v[104:107], v[108:111], v[48:63]
	v_mfma_f32_32x32x16_bf16 v[32:47], v[104:107], v[112:115], v[32:47]
	ds_read_b128 v[104:107], v80 offset:4096
	s_waitcnt lgkmcnt(0)
	v_mfma_f32_32x32x16_bf16 v[16:31], v[104:107], v[108:111], v[16:31]
	v_mfma_f32_32x32x16_bf16 v[0:15], v[104:107], v[112:115], v[0:15]
	ds_read_b128 v[104:107], v82
	ds_read_b128 v[108:111], v85 offset:16384
	ds_read_b128 v[112:115], v85 offset:20480
	s_waitcnt lgkmcnt(0)
	v_mfma_f32_32x32x16_bf16 v[48:63], v[104:107], v[108:111], v[48:63]
	v_mfma_f32_32x32x16_bf16 v[32:47], v[104:107], v[112:115], v[32:47]
	ds_read_b128 v[104:107], v82 offset:4096
	s_waitcnt lgkmcnt(0)
	v_mfma_f32_32x32x16_bf16 v[16:31], v[104:107], v[108:111], v[16:31]
	v_mfma_f32_32x32x16_bf16 v[0:15], v[104:107], v[112:115], v[0:15]
	ds_read_b128 v[104:107], v86
	ds_read_b128 v[108:111], v87 offset:16384
	ds_read_b128 v[112:115], v87 offset:20480
	s_waitcnt lgkmcnt(0)
	v_mfma_f32_32x32x16_bf16 v[48:63], v[104:107], v[108:111], v[48:63]
	v_mfma_f32_32x32x16_bf16 v[32:47], v[104:107], v[112:115], v[32:47]
	ds_read_b128 v[104:107], v86 offset:4096
	s_waitcnt lgkmcnt(0)
	v_mfma_f32_32x32x16_bf16 v[16:31], v[104:107], v[108:111], v[16:31]
	v_mfma_f32_32x32x16_bf16 v[0:15], v[104:107], v[112:115], v[0:15]
	s_waitcnt vmcnt(0)
	s_barrier
	ds_read_b128 v[104:107], v79 offset:32768
	ds_read_b128 v[108:111], v81 offset:49152
	ds_read_b128 v[112:115], v81 offset:53248
	v_lshl_add_u64 v[140:141], v[64:65], 0, s[30:31]
	global_load_lds_dwordx4 v[140:141], off
	s_mov_b32 m0, s85
	v_lshl_add_u64 v[142:143], v[66:67], 0, s[30:31]
	global_load_lds_dwordx4 v76, s[44:45]
	s_mov_b32 m0, s86
	s_nop 0
	global_load_lds_dwordx4 v[142:143], off
	s_mov_b32 m0, s87
	v_lshl_add_u64 v[140:141], v[68:69], 0, s[30:31]
	global_load_lds_dwordx4 v77, s[44:45]
	s_mov_b32 m0, s88
	s_nop 0
	global_load_lds_dwordx4 v[140:141], off
	s_mov_b32 m0, s89
	v_lshl_add_u64 v[142:143], v[70:71], 0, s[30:31]
	global_load_lds_dwordx4 v78, s[44:45]
	s_mov_b32 m0, s90
	s_nop 0
	global_load_lds_dwordx4 v[142:143], off
	s_mov_b32 m0, s91
	s_nop 0
	global_load_lds_dwordx4 v84, s[44:45]
	s_waitcnt lgkmcnt(0)
	v_mfma_f32_32x32x16_bf16 v[48:63], v[104:107], v[108:111], v[48:63]
	s_mov_b32 m0, s18
	v_mfma_f32_32x32x16_bf16 v[32:47], v[104:107], v[112:115], v[32:47]
	ds_read_b128 v[104:107], v79 offset:36864
	s_waitcnt lgkmcnt(0)
	v_mfma_f32_32x32x16_bf16 v[16:31], v[104:107], v[108:111], v[16:31]
	v_mfma_f32_32x32x16_bf16 v[0:15], v[104:107], v[112:115], v[0:15]
	ds_read_b128 v[104:107], v80 offset:32768
	ds_read_b128 v[108:111], v83 offset:49152
	ds_read_b128 v[112:115], v83 offset:53248
	s_waitcnt lgkmcnt(0)
	v_mfma_f32_32x32x16_bf16 v[48:63], v[104:107], v[108:111], v[48:63]
	v_mfma_f32_32x32x16_bf16 v[32:47], v[104:107], v[112:115], v[32:47]
	ds_read_b128 v[104:107], v80 offset:36864
	s_waitcnt lgkmcnt(0)
	v_mfma_f32_32x32x16_bf16 v[16:31], v[104:107], v[108:111], v[16:31]
	v_mfma_f32_32x32x16_bf16 v[0:15], v[104:107], v[112:115], v[0:15]
	ds_read_b128 v[104:107], v82 offset:32768
	ds_read_b128 v[108:111], v85 offset:49152
	ds_read_b128 v[112:115], v85 offset:53248
	s_waitcnt lgkmcnt(0)
	v_mfma_f32_32x32x16_bf16 v[48:63], v[104:107], v[108:111], v[48:63]
	v_mfma_f32_32x32x16_bf16 v[32:47], v[104:107], v[112:115], v[32:47]
	ds_read_b128 v[104:107], v82 offset:36864
	s_waitcnt lgkmcnt(0)
	v_mfma_f32_32x32x16_bf16 v[16:31], v[104:107], v[108:111], v[16:31]
	v_mfma_f32_32x32x16_bf16 v[0:15], v[104:107], v[112:115], v[0:15]
	ds_read_b128 v[104:107], v86 offset:32768
	ds_read_b128 v[108:111], v87 offset:49152
	ds_read_b128 v[112:115], v87 offset:53248
	s_waitcnt lgkmcnt(0)
	v_mfma_f32_32x32x16_bf16 v[48:63], v[104:107], v[108:111], v[48:63]
	v_mfma_f32_32x32x16_bf16 v[32:47], v[104:107], v[112:115], v[32:47]
	ds_read_b128 v[104:107], v86 offset:36864
	s_waitcnt lgkmcnt(0)
	v_mfma_f32_32x32x16_bf16 v[16:31], v[104:107], v[108:111], v[16:31]
	v_mfma_f32_32x32x16_bf16 v[0:15], v[104:107], v[112:115], v[0:15]
	s_waitcnt vmcnt(0)
	s_barrier
; #define WAIT_V0() asm volatile("s_waitcnt vmcnt(0)" ::: "memory")
; DI void gemm_core(char* smem, int nk, const char* Ab, const char* Bb, const unsigned (&aoff)[4], const unsigned (&boff)[4],
;                   f32x16 (&acc)[2][2]) {
;     ...
;   for (int kt = 0; kt < nk; ++kt) {
;     const int cur = kt & 1;
;     if (kt + 1 < nk) stage(cur ^ 1, kt + 1);
;     const char* sb = smem + cur * STAGE_B;
; #pragma unroll
;     for (int ks = 0; ks < 4; ++ks) {
;       bf16x8 af[2], bfr[2];
; #pragma unroll
;       for (int mb = 0; mb < 2; ++mb) af[mb] = *(const bf16x8*)(sb + a_base + mb * 4096 + xo[ks]);
; #pragma unroll
;       for (int nb = 0; nb < 2; ++nb) bfr[nb] = *(const bf16x8*)(sb + b_base + nb * 4096 + xo[ks]);
; #pragma unroll
;       for (int mb = 0; mb < 2; ++mb)
; #pragma unroll
;         for (int nb = 0; nb < 2; ++nb)
;           acc[mb][nb] = __builtin_amdgcn_mfma_f32_32x32x16_bf16(af[mb], bfr[nb], acc[mb][nb], 0, 0, 0);
;     }
;     WAIT_V0();
;     __syncthreads();
;   }
	ds_read_b128 v[104:107], v79
	ds_read_b128 v[108:111], v81 offset:16384
	ds_read_b128 v[112:115], v81 offset:20480
	v_lshl_add_u64 v[140:141], v[64:65], 0, s[4:5]
	global_load_lds_dwordx4 v[140:141], off
	s_mov_b32 m0, s19
	v_lshl_add_u64 v[142:143], v[66:67], 0, s[4:5]
	global_load_lds_dwordx4 v76, s[46:47]
	s_mov_b32 m0, s22
	s_nop 0
	global_load_lds_dwordx4 v[142:143], off
	s_mov_b32 m0, s23
	v_lshl_add_u64 v[140:141], v[68:69], 0, s[4:5]
	global_load_lds_dwordx4 v77, s[46:47]
	s_mov_b32 m0, s29
	s_nop 0
	global_load_lds_dwordx4 v[140:141], off
	s_mov_b32 m0, s69
	v_lshl_add_u64 v[142:143], v[70:71], 0, s[4:5]
	global_load_lds_dwordx4 v78, s[46:47]
	s_mov_b32 m0, s70
	s_mov_b64 s[4:5], 0x300
	global_load_lds_dwordx4 v[142:143], off
	s_mov_b32 m0, s71
	s_nop 0
	global_load_lds_dwordx4 v84, s[46:47]
	s_waitcnt lgkmcnt(0)
	v_mfma_f32_32x32x16_bf16 v[48:63], v[104:107], v[108:111], v[48:63]
	s_mov_b32 m0, s84
	v_mfma_f32_32x32x16_bf16 v[32:47], v[104:107], v[112:115], v[32:47]
	ds_read_b128 v[104:107], v79 offset:4096
	s_waitcnt lgkmcnt(0)
	v_mfma_f32_32x32x16_bf16 v[16:31], v[104:107], v[108:111], v[16:31]
	v_mfma_f32_32x32x16_bf16 v[0:15], v[104:107], v[112:115], v[0:15]
	ds_read_b128 v[104:107], v80
	ds_read_b128 v[108:111], v83 offset:16384
	ds_read_b128 v[112:115], v83 offset:20480
	s_waitcnt lgkmcnt(0)
	v_mfma_f32_32x32x16_bf16 v[48:63], v[104:107], v[108:111], v[48:63]
	v_mfma_f32_32x32x16_bf16 v[32:47], v[104:107], v[112:115], v[32:47]
	ds_read_b128 v[104:107], v80 offset:4096
	s_waitcnt lgkmcnt(0)
	v_mfma_f32_32x32x16_bf16 v[16:31], v[104:107], v[108:111], v[16:31]
	v_mfma_f32_32x32x16_bf16 v[0:15], v[104:107], v[112:115], v[0:15]
	ds_read_b128 v[104:107], v82
	ds_read_b128 v[108:111], v85 offset:16384
	ds_read_b128 v[112:115], v85 offset:20480
	s_waitcnt lgkmcnt(0)
	v_mfma_f32_32x32x16_bf16 v[48:63], v[104:107], v[108:111], v[48:63]
	v_mfma_f32_32x32x16_bf16 v[32:47], v[104:107], v[112:115], v[32:47]
	ds_read_b128 v[104:107], v82 offset:4096
	s_waitcnt lgkmcnt(0)
	v_mfma_f32_32x32x16_bf16 v[16:31], v[104:107], v[108:111], v[16:31]
	v_mfma_f32_32x32x16_bf16 v[0:15], v[104:107], v[112:115], v[0:15]
	ds_read_b128 v[104:107], v86
	ds_read_b128 v[108:111], v87 offset:16384
	ds_read_b128 v[112:115], v87 offset:20480
	s_waitcnt lgkmcnt(0)
	v_mfma_f32_32x32x16_bf16 v[48:63], v[104:107], v[108:111], v[48:63]
	v_mfma_f32_32x32x16_bf16 v[32:47], v[104:107], v[112:115], v[32:47]
	ds_read_b128 v[104:107], v86 offset:4096
	s_waitcnt lgkmcnt(0)
	v_mfma_f32_32x32x16_bf16 v[16:31], v[104:107], v[108:111], v[16:31]
	v_mfma_f32_32x32x16_bf16 v[0:15], v[104:107], v[112:115], v[0:15]
	s_waitcnt vmcnt(0)
	s_barrier
	ds_read_b128 v[104:107], v79 offset:32768
	ds_read_b128 v[108:111], v81 offset:49152
	ds_read_b128 v[112:115], v81 offset:53248
	v_lshl_add_u64 v[140:141], v[64:65], 0, s[4:5]
	global_load_lds_dwordx4 v[140:141], off
	s_mov_b32 m0, s85
	v_lshl_add_u64 v[142:143], v[66:67], 0, s[4:5]
	global_load_lds_dwordx4 v76, s[48:49]
	s_mov_b32 m0, s86
	s_nop 0
	global_load_lds_dwordx4 v[142:143], off
	s_mov_b32 m0, s87
	v_lshl_add_u64 v[140:141], v[68:69], 0, s[4:5]
	global_load_lds_dwordx4 v77, s[48:49]
	s_mov_b32 m0, s88
	s_nop 0
	global_load_lds_dwordx4 v[140:141], off
	s_mov_b32 m0, s89
	v_lshl_add_u64 v[142:143], v[70:71], 0, s[4:5]
	global_load_lds_dwordx4 v78, s[48:49]
	s_mov_b32 m0, s90
	s_mov_b64 s[4:5], 0x380
	global_load_lds_dwordx4 v[142:143], off
	s_mov_b32 m0, s91
	s_nop 0
	global_load_lds_dwordx4 v84, s[48:49]
	s_waitcnt lgkmcnt(0)
	v_mfma_f32_32x32x16_bf16 v[48:63], v[104:107], v[108:111], v[48:63]
	s_mov_b32 m0, s18
	v_mfma_f32_32x32x16_bf16 v[32:47], v[104:107], v[112:115], v[32:47]
	ds_read_b128 v[104:107], v79 offset:36864
	s_waitcnt lgkmcnt(0)
	v_mfma_f32_32x32x16_bf16 v[16:31], v[104:107], v[108:111], v[16:31]
	v_mfma_f32_32x32x16_bf16 v[0:15], v[104:107], v[112:115], v[0:15]
	ds_read_b128 v[104:107], v80 offset:32768
	ds_read_b128 v[108:111], v83 offset:49152
	ds_read_b128 v[112:115], v83 offset:53248
	s_waitcnt lgkmcnt(0)
	v_mfma_f32_32x32x16_bf16 v[48:63], v[104:107], v[108:111], v[48:63]
	v_mfma_f32_32x32x16_bf16 v[32:47], v[104:107], v[112:115], v[32:47]
	ds_read_b128 v[104:107], v80 offset:36864
	s_waitcnt lgkmcnt(0)
	v_mfma_f32_32x32x16_bf16 v[16:31], v[104:107], v[108:111], v[16:31]
	v_mfma_f32_32x32x16_bf16 v[0:15], v[104:107], v[112:115], v[0:15]
	ds_read_b128 v[104:107], v82 offset:32768
	ds_read_b128 v[108:111], v85 offset:49152
	ds_read_b128 v[112:115], v85 offset:53248
	s_waitcnt lgkmcnt(0)
	v_mfma_f32_32x32x16_bf16 v[48:63], v[104:107], v[108:111], v[48:63]
	v_mfma_f32_32x32x16_bf16 v[32:47], v[104:107], v[112:115], v[32:47]
	ds_read_b128 v[104:107], v82 offset:36864
	s_waitcnt lgkmcnt(0)
	v_mfma_f32_32x32x16_bf16 v[16:31], v[104:107], v[108:111], v[16:31]
	v_mfma_f32_32x32x16_bf16 v[0:15], v[104:107], v[112:115], v[0:15]
	ds_read_b128 v[104:107], v86 offset:32768
	ds_read_b128 v[108:111], v87 offset:49152
	ds_read_b128 v[112:115], v87 offset:53248
	s_waitcnt lgkmcnt(0)
	v_mfma_f32_32x32x16_bf16 v[48:63], v[104:107], v[108:111], v[48:63]
	v_mfma_f32_32x32x16_bf16 v[32:47], v[104:107], v[112:115], v[32:47]
	ds_read_b128 v[104:107], v86 offset:36864
	s_waitcnt lgkmcnt(0)
	v_mfma_f32_32x32x16_bf16 v[16:31], v[104:107], v[108:111], v[16:31]
	v_mfma_f32_32x32x16_bf16 v[0:15], v[104:107], v[112:115], v[0:15]
	s_waitcnt vmcnt(0)
	s_barrier
; #define WAIT_V0() asm volatile("s_waitcnt vmcnt(0)" ::: "memory")
; DI void gemm_core(char* smem, int nk, const char* Ab, const char* Bb, const unsigned (&aoff)[4], const unsigned (&boff)[4],
;                   f32x16 (&acc)[2][2]) {
;     ...
;   for (int kt = 0; kt < nk; ++kt) {
;     const int cur = kt & 1;
;     if (kt + 1 < nk) stage(cur ^ 1, kt + 1);
;     const char* sb = smem + cur * STAGE_B;
; #pragma unroll
;     for (int ks = 0; ks < 4; ++ks) {
;       bf16x8 af[2], bfr[2];
; #pragma unroll
;       for (int mb = 0; mb < 2; ++mb) af[mb] = *(const bf16x8*)(sb + a_base + mb * 4096 + xo[ks]);
; #pragma unroll
;       for (int nb = 0; nb < 2; ++nb) bfr[nb] = *(const bf16x8*)(sb + b_base + nb * 4096 + xo[ks]);
; #pragma unroll
;       for (int mb = 0; mb < 2; ++mb)
; #pragma unroll
;         for (int nb = 0; nb < 2; ++nb)
;           acc[mb][nb] = __builtin_amdgcn_mfma_f32_32x32x16_bf16(af[mb], bfr[nb], acc[mb][nb], 0, 0, 0);
;     }
;     WAIT_V0();
;     __syncthreads();
;   }
	ds_read_b128 v[104:107], v79
	ds_read_b128 v[108:111], v81 offset:16384
	ds_read_b128 v[112:115], v81 offset:20480
	v_lshl_add_u64 v[140:141], v[64:65], 0, s[4:5]
	global_load_lds_dwordx4 v[140:141], off
	s_mov_b32 m0, s19
	v_lshl_add_u64 v[142:143], v[66:67], 0, s[4:5]
	global_load_lds_dwordx4 v76, s[50:51]
	s_mov_b32 m0, s22
	s_nop 0
	global_load_lds_dwordx4 v[142:143], off
	s_mov_b32 m0, s23
	v_lshl_add_u64 v[140:141], v[68:69], 0, s[4:5]
	global_load_lds_dwordx4 v77, s[50:51]
	s_mov_b32 m0, s29
	s_nop 0
	global_load_lds_dwordx4 v[140:141], off
	s_mov_b32 m0, s69
	v_lshl_add_u64 v[142:143], v[70:71], 0, s[4:5]
	global_load_lds_dwordx4 v78, s[50:51]
	s_mov_b32 m0, s70
	s_mov_b64 s[4:5], 0x400
	global_load_lds_dwordx4 v[142:143], off
	s_mov_b32 m0, s71
	s_nop 0
	global_load_lds_dwordx4 v84, s[50:51]
	s_waitcnt lgkmcnt(0)
	v_mfma_f32_32x32x16_bf16 v[48:63], v[104:107], v[108:111], v[48:63]
	s_mov_b32 m0, s84
	v_readfirstlane_b32 s84, v89
	v_mfma_f32_32x32x16_bf16 v[32:47], v[104:107], v[112:115], v[32:47]
	ds_read_b128 v[104:107], v79 offset:4096
	s_waitcnt lgkmcnt(0)
	v_mfma_f32_32x32x16_bf16 v[16:31], v[104:107], v[108:111], v[16:31]
	v_mfma_f32_32x32x16_bf16 v[0:15], v[104:107], v[112:115], v[0:15]
	ds_read_b128 v[104:107], v80
	ds_read_b128 v[108:111], v83 offset:16384
	ds_read_b128 v[112:115], v83 offset:20480
	s_waitcnt lgkmcnt(0)
	v_mfma_f32_32x32x16_bf16 v[48:63], v[104:107], v[108:111], v[48:63]
	v_mfma_f32_32x32x16_bf16 v[32:47], v[104:107], v[112:115], v[32:47]
	ds_read_b128 v[104:107], v80 offset:4096
	s_waitcnt lgkmcnt(0)
	v_mfma_f32_32x32x16_bf16 v[16:31], v[104:107], v[108:111], v[16:31]
	v_mfma_f32_32x32x16_bf16 v[0:15], v[104:107], v[112:115], v[0:15]
	ds_read_b128 v[104:107], v82
	ds_read_b128 v[108:111], v85 offset:16384
	ds_read_b128 v[112:115], v85 offset:20480
	s_waitcnt lgkmcnt(0)
	v_mfma_f32_32x32x16_bf16 v[48:63], v[104:107], v[108:111], v[48:63]
	v_mfma_f32_32x32x16_bf16 v[32:47], v[104:107], v[112:115], v[32:47]
	ds_read_b128 v[104:107], v82 offset:4096
	s_waitcnt lgkmcnt(0)
	v_mfma_f32_32x32x16_bf16 v[16:31], v[104:107], v[108:111], v[16:31]
	v_mfma_f32_32x32x16_bf16 v[0:15], v[104:107], v[112:115], v[0:15]
	ds_read_b128 v[104:107], v86
	ds_read_b128 v[108:111], v87 offset:16384
	ds_read_b128 v[112:115], v87 offset:20480
	s_waitcnt lgkmcnt(0)
	v_mfma_f32_32x32x16_bf16 v[48:63], v[104:107], v[108:111], v[48:63]
	v_mfma_f32_32x32x16_bf16 v[32:47], v[104:107], v[112:115], v[32:47]
	ds_read_b128 v[104:107], v86 offset:4096
	s_waitcnt lgkmcnt(0)
	v_mfma_f32_32x32x16_bf16 v[16:31], v[104:107], v[108:111], v[16:31]
	v_mfma_f32_32x32x16_bf16 v[0:15], v[104:107], v[112:115], v[0:15]
	s_waitcnt vmcnt(0)
	s_barrier
	ds_read_b128 v[104:107], v79 offset:32768
	ds_read_b128 v[108:111], v81 offset:49152
	ds_read_b128 v[112:115], v81 offset:53248
	v_lshl_add_u64 v[140:141], v[64:65], 0, s[4:5]
	global_load_lds_dwordx4 v[140:141], off
	s_mov_b32 m0, s85
	v_lshl_add_u64 v[142:143], v[66:67], 0, s[4:5]
	global_load_lds_dwordx4 v76, s[52:53]
	s_mov_b32 m0, s86
	v_readfirstlane_b32 s85, v88
	global_load_lds_dwordx4 v[142:143], off
	s_mov_b32 m0, s87
	v_lshl_add_u64 v[140:141], v[68:69], 0, s[4:5]
	global_load_lds_dwordx4 v77, s[52:53]
	s_mov_b32 m0, s88
	v_readfirstlane_b32 s86, v90
	global_load_lds_dwordx4 v[140:141], off
	s_mov_b32 m0, s89
	v_lshl_add_u64 v[142:143], v[70:71], 0, s[4:5]
	global_load_lds_dwordx4 v78, s[52:53]
	s_mov_b32 m0, s90
	s_mov_b64 s[4:5], 0x480
	global_load_lds_dwordx4 v[142:143], off
	s_mov_b32 m0, s91
	v_readfirstlane_b32 s87, v91
	global_load_lds_dwordx4 v84, s[52:53]
	s_waitcnt lgkmcnt(0)
	v_mfma_f32_32x32x16_bf16 v[48:63], v[104:107], v[108:111], v[48:63]
	s_mov_b32 m0, s18
	v_readfirstlane_b32 s18, v97
	v_readfirstlane_b32 s88, v92
	v_readfirstlane_b32 s89, v93
	v_readfirstlane_b32 s90, v94
	v_readfirstlane_b32 s91, v95
	v_mfma_f32_32x32x16_bf16 v[32:47], v[104:107], v[112:115], v[32:47]
	ds_read_b128 v[104:107], v79 offset:36864
	s_waitcnt lgkmcnt(0)
	v_mfma_f32_32x32x16_bf16 v[16:31], v[104:107], v[108:111], v[16:31]
	v_mfma_f32_32x32x16_bf16 v[0:15], v[104:107], v[112:115], v[0:15]
	ds_read_b128 v[104:107], v80 offset:32768
	ds_read_b128 v[108:111], v83 offset:49152
	ds_read_b128 v[112:115], v83 offset:53248
	s_waitcnt lgkmcnt(0)
	v_mfma_f32_32x32x16_bf16 v[48:63], v[104:107], v[108:111], v[48:63]
	v_mfma_f32_32x32x16_bf16 v[32:47], v[104:107], v[112:115], v[32:47]
	ds_read_b128 v[104:107], v80 offset:36864
	s_waitcnt lgkmcnt(0)
	v_mfma_f32_32x32x16_bf16 v[16:31], v[104:107], v[108:111], v[16:31]
	v_mfma_f32_32x32x16_bf16 v[0:15], v[104:107], v[112:115], v[0:15]
	ds_read_b128 v[104:107], v82 offset:32768
	ds_read_b128 v[108:111], v85 offset:49152
	ds_read_b128 v[112:115], v85 offset:53248
	s_waitcnt lgkmcnt(0)
	v_mfma_f32_32x32x16_bf16 v[48:63], v[104:107], v[108:111], v[48:63]
	v_mfma_f32_32x32x16_bf16 v[32:47], v[104:107], v[112:115], v[32:47]
	ds_read_b128 v[104:107], v82 offset:36864
	s_waitcnt lgkmcnt(0)
	v_mfma_f32_32x32x16_bf16 v[16:31], v[104:107], v[108:111], v[16:31]
	v_mfma_f32_32x32x16_bf16 v[0:15], v[104:107], v[112:115], v[0:15]
	ds_read_b128 v[104:107], v86 offset:32768
	ds_read_b128 v[108:111], v87 offset:49152
	ds_read_b128 v[112:115], v87 offset:53248
	s_waitcnt lgkmcnt(0)
	v_mfma_f32_32x32x16_bf16 v[48:63], v[104:107], v[108:111], v[48:63]
	v_mfma_f32_32x32x16_bf16 v[32:47], v[104:107], v[112:115], v[32:47]
	ds_read_b128 v[104:107], v86 offset:36864
	s_waitcnt lgkmcnt(0)
	v_mfma_f32_32x32x16_bf16 v[16:31], v[104:107], v[108:111], v[16:31]
	v_mfma_f32_32x32x16_bf16 v[0:15], v[104:107], v[112:115], v[0:15]
	s_waitcnt vmcnt(0)
	s_barrier
; #define WAIT_V0() asm volatile("s_waitcnt vmcnt(0)" ::: "memory")
; DI void gemm_core(char* smem, int nk, const char* Ab, const char* Bb, const unsigned (&aoff)[4], const unsigned (&boff)[4],
;                   f32x16 (&acc)[2][2]) {
;     ...
;   for (int kt = 0; kt < nk; ++kt) {
;     const int cur = kt & 1;
;     if (kt + 1 < nk) stage(cur ^ 1, kt + 1);
;     const char* sb = smem + cur * STAGE_B;
; #pragma unroll
;     for (int ks = 0; ks < 4; ++ks) {
;       bf16x8 af[2], bfr[2];
; #pragma unroll
;       for (int mb = 0; mb < 2; ++mb) af[mb] = *(const bf16x8*)(sb + a_base + mb * 4096 + xo[ks]);
; #pragma unroll
;       for (int nb = 0; nb < 2; ++nb) bfr[nb] = *(const bf16x8*)(sb + b_base + nb * 4096 + xo[ks]);
; #pragma unroll
;       for (int mb = 0; mb < 2; ++mb)
; #pragma unroll
;         for (int nb = 0; nb < 2; ++nb)
;           acc[mb][nb] = __builtin_amdgcn_mfma_f32_32x32x16_bf16(af[mb], bfr[nb], acc[mb][nb], 0, 0, 0);
;     }
;     WAIT_V0();
;     __syncthreads();
;   }
	v_lshl_add_u64 v[104:105], v[64:65], 0, s[4:5]
	global_load_lds_dwordx4 v[104:105], off
	s_mov_b32 m0, s19
	v_lshl_add_u64 v[104:105], v[66:67], 0, s[4:5]
	global_load_lds_dwordx4 v76, s[54:55]
	s_mov_b32 m0, s22
	v_readfirstlane_b32 s19, v96
	global_load_lds_dwordx4 v[104:105], off
	s_mov_b32 m0, s23
	v_lshl_add_u64 v[104:105], v[68:69], 0, s[4:5]
	global_load_lds_dwordx4 v77, s[54:55]
	s_mov_b32 m0, s29
	v_readfirstlane_b32 s22, v98
	global_load_lds_dwordx4 v[104:105], off
	s_mov_b32 m0, s69
	v_lshl_add_u64 v[104:105], v[70:71], 0, s[4:5]
	global_load_lds_dwordx4 v78, s[54:55]
	s_mov_b32 m0, s70
	s_mov_b64 s[4:5], 0x500
	global_load_lds_dwordx4 v[104:105], off
	s_mov_b32 m0, s71
	v_lshl_add_u64 v[96:97], v[66:67], 0, s[4:5]
	global_load_lds_dwordx4 v84, s[54:55]
	ds_read_b128 v[104:107], v79
	ds_read_b128 v[108:111], v81 offset:16384
	ds_read_b128 v[112:115], v81 offset:20480
	s_waitcnt lgkmcnt(0)
	v_mfma_f32_32x32x16_bf16 v[48:63], v[104:107], v[108:111], v[48:63]
	s_mov_b32 m0, s18
	v_readfirstlane_b32 s23, v99
	v_readfirstlane_b32 s29, v100
	v_readfirstlane_b32 s69, v101
	v_readfirstlane_b32 s70, v102
	v_readfirstlane_b32 s71, v103
	v_mfma_f32_32x32x16_bf16 v[32:47], v[104:107], v[112:115], v[32:47]
	ds_read_b128 v[104:107], v79 offset:4096
	s_waitcnt lgkmcnt(0)
	v_mfma_f32_32x32x16_bf16 v[16:31], v[104:107], v[108:111], v[16:31]
	v_mfma_f32_32x32x16_bf16 v[0:15], v[104:107], v[112:115], v[0:15]
	ds_read_b128 v[104:107], v80
	ds_read_b128 v[108:111], v83 offset:16384
	ds_read_b128 v[112:115], v83 offset:20480
	s_waitcnt lgkmcnt(0)
	v_mfma_f32_32x32x16_bf16 v[48:63], v[104:107], v[108:111], v[48:63]
	v_mfma_f32_32x32x16_bf16 v[32:47], v[104:107], v[112:115], v[32:47]
	ds_read_b128 v[104:107], v80 offset:4096
	s_waitcnt lgkmcnt(0)
	v_mfma_f32_32x32x16_bf16 v[16:31], v[104:107], v[108:111], v[16:31]
	v_mfma_f32_32x32x16_bf16 v[0:15], v[104:107], v[112:115], v[0:15]
	ds_read_b128 v[104:107], v82
	ds_read_b128 v[108:111], v85 offset:16384
	ds_read_b128 v[112:115], v85 offset:20480
	s_waitcnt lgkmcnt(0)
	v_mfma_f32_32x32x16_bf16 v[48:63], v[104:107], v[108:111], v[48:63]
	v_mfma_f32_32x32x16_bf16 v[32:47], v[104:107], v[112:115], v[32:47]
	ds_read_b128 v[104:107], v82 offset:4096
	s_waitcnt lgkmcnt(0)
	v_mfma_f32_32x32x16_bf16 v[16:31], v[104:107], v[108:111], v[16:31]
	v_mfma_f32_32x32x16_bf16 v[0:15], v[104:107], v[112:115], v[0:15]
	ds_read_b128 v[104:107], v86
	ds_read_b128 v[108:111], v87 offset:16384
	ds_read_b128 v[112:115], v87 offset:20480
	s_waitcnt lgkmcnt(0)
	v_mfma_f32_32x32x16_bf16 v[48:63], v[104:107], v[108:111], v[48:63]
	v_mfma_f32_32x32x16_bf16 v[32:47], v[104:107], v[112:115], v[32:47]
	ds_read_b128 v[104:107], v86 offset:4096
	s_waitcnt lgkmcnt(0)
	v_mfma_f32_32x32x16_bf16 v[16:31], v[104:107], v[108:111], v[16:31]
	v_mfma_f32_32x32x16_bf16 v[0:15], v[104:107], v[112:115], v[0:15]
	s_waitcnt vmcnt(0)
	s_barrier
	v_lshl_add_u64 v[104:105], v[64:65], 0, s[4:5]
	global_load_lds_dwordx4 v[104:105], off
	s_mov_b32 m0, s19
	s_nop 0
	global_load_lds_dwordx4 v76, s[56:57]
	s_mov_b32 m0, s22
	s_nop 0
	global_load_lds_dwordx4 v[96:97], off
	s_mov_b32 m0, s23
	v_lshl_add_u64 v[96:97], v[68:69], 0, s[4:5]
	global_load_lds_dwordx4 v77, s[56:57]
	s_mov_b32 m0, s29
	s_nop 0
	global_load_lds_dwordx4 v[96:97], off
	s_mov_b32 m0, s69
	v_lshl_add_u64 v[96:97], v[70:71], 0, s[4:5]
	global_load_lds_dwordx4 v78, s[56:57]
	s_mov_b32 m0, s70
	s_mov_b64 s[4:5], 0x580
	global_load_lds_dwordx4 v[96:97], off
	s_mov_b32 m0, s71
	v_lshl_add_u64 v[88:89], v[66:67], 0, s[4:5]
	global_load_lds_dwordx4 v84, s[56:57]
	ds_read_b128 v[96:99], v79 offset:32768
	ds_read_b128 v[100:103], v81 offset:49152
	ds_read_b128 v[104:107], v81 offset:53248
	s_waitcnt lgkmcnt(0)
	v_mfma_f32_32x32x16_bf16 v[48:63], v[96:99], v[100:103], v[48:63]
	s_mov_b32 m0, s84
	v_mfma_f32_32x32x16_bf16 v[32:47], v[96:99], v[104:107], v[32:47]
	ds_read_b128 v[96:99], v79 offset:36864
	s_waitcnt lgkmcnt(0)
	v_mfma_f32_32x32x16_bf16 v[16:31], v[96:99], v[100:103], v[16:31]
	v_mfma_f32_32x32x16_bf16 v[0:15], v[96:99], v[104:107], v[0:15]
	ds_read_b128 v[96:99], v80 offset:32768
	ds_read_b128 v[100:103], v83 offset:49152
	ds_read_b128 v[104:107], v83 offset:53248
	s_waitcnt lgkmcnt(0)
	v_mfma_f32_32x32x16_bf16 v[48:63], v[96:99], v[100:103], v[48:63]
	v_mfma_f32_32x32x16_bf16 v[32:47], v[96:99], v[104:107], v[32:47]
	ds_read_b128 v[96:99], v80 offset:36864
	s_waitcnt lgkmcnt(0)
	v_mfma_f32_32x32x16_bf16 v[16:31], v[96:99], v[100:103], v[16:31]
	v_mfma_f32_32x32x16_bf16 v[0:15], v[96:99], v[104:107], v[0:15]
	ds_read_b128 v[96:99], v82 offset:32768
	ds_read_b128 v[100:103], v85 offset:49152
	ds_read_b128 v[104:107], v85 offset:53248
	s_waitcnt lgkmcnt(0)
	v_mfma_f32_32x32x16_bf16 v[48:63], v[96:99], v[100:103], v[48:63]
	v_mfma_f32_32x32x16_bf16 v[32:47], v[96:99], v[104:107], v[32:47]
	ds_read_b128 v[96:99], v82 offset:36864
	s_waitcnt lgkmcnt(0)
	v_mfma_f32_32x32x16_bf16 v[16:31], v[96:99], v[100:103], v[16:31]
	v_mfma_f32_32x32x16_bf16 v[0:15], v[96:99], v[104:107], v[0:15]
	ds_read_b128 v[96:99], v86 offset:32768
	ds_read_b128 v[100:103], v87 offset:49152
	ds_read_b128 v[104:107], v87 offset:53248
	s_waitcnt lgkmcnt(0)
	v_mfma_f32_32x32x16_bf16 v[48:63], v[96:99], v[100:103], v[48:63]
	v_mfma_f32_32x32x16_bf16 v[32:47], v[96:99], v[104:107], v[32:47]
	ds_read_b128 v[96:99], v86 offset:36864
	s_waitcnt lgkmcnt(0)
	v_mfma_f32_32x32x16_bf16 v[16:31], v[96:99], v[100:103], v[16:31]
	v_mfma_f32_32x32x16_bf16 v[0:15], v[96:99], v[104:107], v[0:15]
	s_waitcnt vmcnt(0)
	s_barrier
; #define WAIT_V0() asm volatile("s_waitcnt vmcnt(0)" ::: "memory")
; DI void gemm_core(char* smem, int nk, const char* Ab, const char* Bb, const unsigned (&aoff)[4], const unsigned (&boff)[4],
;                   f32x16 (&acc)[2][2]) {
;     ...
;   for (int kt = 0; kt < nk; ++kt) {
;     const int cur = kt & 1;
;     if (kt + 1 < nk) stage(cur ^ 1, kt + 1);
;     const char* sb = smem + cur * STAGE_B;
; #pragma unroll
;     for (int ks = 0; ks < 4; ++ks) {
;       bf16x8 af[2], bfr[2];
; #pragma unroll
;       for (int mb = 0; mb < 2; ++mb) af[mb] = *(const bf16x8*)(sb + a_base + mb * 4096 + xo[ks]);
; #pragma unroll
;       for (int nb = 0; nb < 2; ++nb) bfr[nb] = *(const bf16x8*)(sb + b_base + nb * 4096 + xo[ks]);
; #pragma unroll
;       for (int mb = 0; mb < 2; ++mb)
; #pragma unroll
;         for (int nb = 0; nb < 2; ++nb)
;           acc[mb][nb] = __builtin_amdgcn_mfma_f32_32x32x16_bf16(af[mb], bfr[nb], acc[mb][nb], 0, 0, 0);
;     }
;     WAIT_V0();
;     __syncthreads();
;   }
	v_lshl_add_u64 v[96:97], v[64:65], 0, s[4:5]
	global_load_lds_dwordx4 v[96:97], off
	s_mov_b32 m0, s85
	s_nop 0
	global_load_lds_dwordx4 v76, s[58:59]
	s_mov_b32 m0, s86
	s_nop 0
	global_load_lds_dwordx4 v[88:89], off
	s_mov_b32 m0, s87
	v_lshl_add_u64 v[88:89], v[68:69], 0, s[4:5]
	global_load_lds_dwordx4 v77, s[58:59]
	s_mov_b32 m0, s88
	s_nop 0
	global_load_lds_dwordx4 v[88:89], off
	s_mov_b32 m0, s89
	v_lshl_add_u64 v[88:89], v[70:71], 0, s[4:5]
	global_load_lds_dwordx4 v78, s[58:59]
	s_mov_b32 m0, s90
	s_mov_b64 s[4:5], 0x600
	global_load_lds_dwordx4 v[88:89], off
	s_mov_b32 m0, s91
	s_nop 0
	global_load_lds_dwordx4 v84, s[58:59]
	ds_read_b128 v[88:91], v79
	ds_read_b128 v[92:95], v81 offset:16384
	ds_read_b128 v[96:99], v81 offset:20480
	s_waitcnt lgkmcnt(0)
	v_mfma_f32_32x32x16_bf16 v[48:63], v[88:91], v[92:95], v[48:63]
	s_mov_b32 m0, s18
	v_mfma_f32_32x32x16_bf16 v[32:47], v[88:91], v[96:99], v[32:47]
	ds_read_b128 v[88:91], v79 offset:4096
	s_waitcnt lgkmcnt(0)
	v_mfma_f32_32x32x16_bf16 v[16:31], v[88:91], v[92:95], v[16:31]
	v_mfma_f32_32x32x16_bf16 v[0:15], v[88:91], v[96:99], v[0:15]
	ds_read_b128 v[88:91], v80
	ds_read_b128 v[92:95], v83 offset:16384
	ds_read_b128 v[96:99], v83 offset:20480
	s_waitcnt lgkmcnt(0)
	v_mfma_f32_32x32x16_bf16 v[48:63], v[88:91], v[92:95], v[48:63]
	v_mfma_f32_32x32x16_bf16 v[32:47], v[88:91], v[96:99], v[32:47]
	ds_read_b128 v[88:91], v80 offset:4096
	s_waitcnt lgkmcnt(0)
	v_mfma_f32_32x32x16_bf16 v[16:31], v[88:91], v[92:95], v[16:31]
	v_mfma_f32_32x32x16_bf16 v[0:15], v[88:91], v[96:99], v[0:15]
	ds_read_b128 v[88:91], v82
	ds_read_b128 v[92:95], v85 offset:16384
	ds_read_b128 v[96:99], v85 offset:20480
	s_waitcnt lgkmcnt(0)
	v_mfma_f32_32x32x16_bf16 v[48:63], v[88:91], v[92:95], v[48:63]
	v_mfma_f32_32x32x16_bf16 v[32:47], v[88:91], v[96:99], v[32:47]
	ds_read_b128 v[88:91], v82 offset:4096
	s_waitcnt lgkmcnt(0)
	v_mfma_f32_32x32x16_bf16 v[16:31], v[88:91], v[92:95], v[16:31]
	v_mfma_f32_32x32x16_bf16 v[0:15], v[88:91], v[96:99], v[0:15]
	ds_read_b128 v[88:91], v86
	ds_read_b128 v[92:95], v87 offset:16384
	ds_read_b128 v[96:99], v87 offset:20480
	s_waitcnt lgkmcnt(0)
	v_mfma_f32_32x32x16_bf16 v[48:63], v[88:91], v[92:95], v[48:63]
	v_mfma_f32_32x32x16_bf16 v[32:47], v[88:91], v[96:99], v[32:47]
	ds_read_b128 v[88:91], v86 offset:4096
	s_waitcnt lgkmcnt(0)
	v_mfma_f32_32x32x16_bf16 v[16:31], v[88:91], v[92:95], v[16:31]
	v_mfma_f32_32x32x16_bf16 v[0:15], v[88:91], v[96:99], v[0:15]
	s_waitcnt vmcnt(0)
	s_barrier
	ds_read_b128 v[88:91], v79 offset:32768
	ds_read_b128 v[92:95], v81 offset:49152
	ds_read_b128 v[96:99], v81 offset:53248
	v_lshl_add_u64 v[140:141], v[64:65], 0, s[4:5]
	global_load_lds_dwordx4 v[140:141], off
	s_mov_b32 m0, s19
	v_lshl_add_u64 v[142:143], v[66:67], 0, s[4:5]
	global_load_lds_dwordx4 v76, s[60:61]
	s_mov_b32 m0, s22
	s_nop 0
	global_load_lds_dwordx4 v[142:143], off
	s_mov_b32 m0, s23
	v_lshl_add_u64 v[140:141], v[68:69], 0, s[4:5]
	global_load_lds_dwordx4 v77, s[60:61]
	s_mov_b32 m0, s29
	s_nop 0
	global_load_lds_dwordx4 v[140:141], off
	s_mov_b32 m0, s69
	v_lshl_add_u64 v[142:143], v[70:71], 0, s[4:5]
	global_load_lds_dwordx4 v78, s[60:61]
	s_mov_b32 m0, s70
	s_mov_b64 s[4:5], 0x680
	global_load_lds_dwordx4 v[142:143], off
	s_mov_b32 m0, s71
	s_nop 0
	global_load_lds_dwordx4 v84, s[60:61]
	s_waitcnt lgkmcnt(0)
	v_mfma_f32_32x32x16_bf16 v[48:63], v[88:91], v[92:95], v[48:63]
	s_mov_b32 m0, s84
	v_mfma_f32_32x32x16_bf16 v[32:47], v[88:91], v[96:99], v[32:47]
	ds_read_b128 v[88:91], v79 offset:36864
	s_waitcnt lgkmcnt(0)
	v_mfma_f32_32x32x16_bf16 v[16:31], v[88:91], v[92:95], v[16:31]
	v_mfma_f32_32x32x16_bf16 v[0:15], v[88:91], v[96:99], v[0:15]
	ds_read_b128 v[88:91], v80 offset:32768
	ds_read_b128 v[92:95], v83 offset:49152
	ds_read_b128 v[96:99], v83 offset:53248
	s_waitcnt lgkmcnt(0)
	v_mfma_f32_32x32x16_bf16 v[48:63], v[88:91], v[92:95], v[48:63]
	v_mfma_f32_32x32x16_bf16 v[32:47], v[88:91], v[96:99], v[32:47]
	ds_read_b128 v[88:91], v80 offset:36864
	s_waitcnt lgkmcnt(0)
	v_mfma_f32_32x32x16_bf16 v[16:31], v[88:91], v[92:95], v[16:31]
	v_mfma_f32_32x32x16_bf16 v[0:15], v[88:91], v[96:99], v[0:15]
	ds_read_b128 v[88:91], v82 offset:32768
	ds_read_b128 v[92:95], v85 offset:49152
	ds_read_b128 v[96:99], v85 offset:53248
	s_waitcnt lgkmcnt(0)
	v_mfma_f32_32x32x16_bf16 v[48:63], v[88:91], v[92:95], v[48:63]
	v_mfma_f32_32x32x16_bf16 v[32:47], v[88:91], v[96:99], v[32:47]
	ds_read_b128 v[88:91], v82 offset:36864
	s_waitcnt lgkmcnt(0)
	v_mfma_f32_32x32x16_bf16 v[16:31], v[88:91], v[92:95], v[16:31]
	v_mfma_f32_32x32x16_bf16 v[0:15], v[88:91], v[96:99], v[0:15]
	ds_read_b128 v[88:91], v86 offset:32768
	ds_read_b128 v[92:95], v87 offset:49152
	ds_read_b128 v[96:99], v87 offset:53248
	s_waitcnt lgkmcnt(0)
	v_mfma_f32_32x32x16_bf16 v[48:63], v[88:91], v[92:95], v[48:63]
	v_mfma_f32_32x32x16_bf16 v[32:47], v[88:91], v[96:99], v[32:47]
	ds_read_b128 v[88:91], v86 offset:36864
	s_waitcnt lgkmcnt(0)
	v_mfma_f32_32x32x16_bf16 v[16:31], v[88:91], v[92:95], v[16:31]
	v_mfma_f32_32x32x16_bf16 v[0:15], v[88:91], v[96:99], v[0:15]
	s_waitcnt vmcnt(0)
	s_barrier
; #define WAIT_V0() asm volatile("s_waitcnt vmcnt(0)" ::: "memory")
; DI void gemm_core(char* smem, int nk, const char* Ab, const char* Bb, const unsigned (&aoff)[4], const unsigned (&boff)[4],
;                   f32x16 (&acc)[2][2]) {
;     ...
;   for (int kt = 0; kt < nk; ++kt) {
;     const int cur = kt & 1;
;     if (kt + 1 < nk) stage(cur ^ 1, kt + 1);
;     const char* sb = smem + cur * STAGE_B;
; #pragma unroll
;     for (int ks = 0; ks < 4; ++ks) {
;       bf16x8 af[2], bfr[2];
; #pragma unroll
;       for (int mb = 0; mb < 2; ++mb) af[mb] = *(const bf16x8*)(sb + a_base + mb * 4096 + xo[ks]);
; #pragma unroll
;       for (int nb = 0; nb < 2; ++nb) bfr[nb] = *(const bf16x8*)(sb + b_base + nb * 4096 + xo[ks]);
; #pragma unroll
;       for (int mb = 0; mb < 2; ++mb)
; #pragma unroll
;         for (int nb = 0; nb < 2; ++nb)
;           acc[mb][nb] = __builtin_amdgcn_mfma_f32_32x32x16_bf16(af[mb], bfr[nb], acc[mb][nb], 0, 0, 0);
;     }
;     WAIT_V0();
;     __syncthreads();
;   }
	ds_read_b128 v[88:91], v79
	ds_read_b128 v[92:95], v81 offset:16384
	ds_read_b128 v[96:99], v81 offset:20480
	v_lshl_add_u64 v[140:141], v[64:65], 0, s[4:5]
	global_load_lds_dwordx4 v[140:141], off
	s_mov_b32 m0, s85
	v_lshl_add_u64 v[142:143], v[66:67], 0, s[4:5]
	global_load_lds_dwordx4 v76, s[62:63]
	s_mov_b32 m0, s86
	s_nop 0
	global_load_lds_dwordx4 v[142:143], off
	s_mov_b32 m0, s87
	v_lshl_add_u64 v[140:141], v[68:69], 0, s[4:5]
	global_load_lds_dwordx4 v77, s[62:63]
	s_mov_b32 m0, s88
	s_nop 0
	global_load_lds_dwordx4 v[140:141], off
	s_mov_b32 m0, s89
	v_lshl_add_u64 v[142:143], v[70:71], 0, s[4:5]
	global_load_lds_dwordx4 v78, s[62:63]
	s_mov_b32 m0, s90
	s_mov_b64 s[4:5], 0x700
	global_load_lds_dwordx4 v[142:143], off
	s_mov_b32 m0, s91
	s_nop 0
	global_load_lds_dwordx4 v84, s[62:63]
	s_waitcnt lgkmcnt(0)
	v_mfma_f32_32x32x16_bf16 v[48:63], v[88:91], v[92:95], v[48:63]
	s_mov_b32 m0, s18
	v_mfma_f32_32x32x16_bf16 v[32:47], v[88:91], v[96:99], v[32:47]
	ds_read_b128 v[88:91], v79 offset:4096
	s_waitcnt lgkmcnt(0)
	v_mfma_f32_32x32x16_bf16 v[16:31], v[88:91], v[92:95], v[16:31]
	v_mfma_f32_32x32x16_bf16 v[0:15], v[88:91], v[96:99], v[0:15]
	ds_read_b128 v[88:91], v80
	ds_read_b128 v[92:95], v83 offset:16384
	ds_read_b128 v[96:99], v83 offset:20480
	s_waitcnt lgkmcnt(0)
	v_mfma_f32_32x32x16_bf16 v[48:63], v[88:91], v[92:95], v[48:63]
	v_mfma_f32_32x32x16_bf16 v[32:47], v[88:91], v[96:99], v[32:47]
	ds_read_b128 v[88:91], v80 offset:4096
	s_waitcnt lgkmcnt(0)
	v_mfma_f32_32x32x16_bf16 v[16:31], v[88:91], v[92:95], v[16:31]
	v_mfma_f32_32x32x16_bf16 v[0:15], v[88:91], v[96:99], v[0:15]
	ds_read_b128 v[88:91], v82
	ds_read_b128 v[92:95], v85 offset:16384
	ds_read_b128 v[96:99], v85 offset:20480
	s_waitcnt lgkmcnt(0)
	v_mfma_f32_32x32x16_bf16 v[48:63], v[88:91], v[92:95], v[48:63]
	v_mfma_f32_32x32x16_bf16 v[32:47], v[88:91], v[96:99], v[32:47]
	ds_read_b128 v[88:91], v82 offset:4096
	s_waitcnt lgkmcnt(0)
	v_mfma_f32_32x32x16_bf16 v[16:31], v[88:91], v[92:95], v[16:31]
	v_mfma_f32_32x32x16_bf16 v[0:15], v[88:91], v[96:99], v[0:15]
	ds_read_b128 v[88:91], v86
	ds_read_b128 v[92:95], v87 offset:16384
	ds_read_b128 v[96:99], v87 offset:20480
	s_waitcnt lgkmcnt(0)
	v_mfma_f32_32x32x16_bf16 v[48:63], v[88:91], v[92:95], v[48:63]
	v_mfma_f32_32x32x16_bf16 v[32:47], v[88:91], v[96:99], v[32:47]
	ds_read_b128 v[88:91], v86 offset:4096
	s_waitcnt lgkmcnt(0)
	v_mfma_f32_32x32x16_bf16 v[16:31], v[88:91], v[92:95], v[16:31]
	v_mfma_f32_32x32x16_bf16 v[0:15], v[88:91], v[96:99], v[0:15]
	s_waitcnt vmcnt(0)
	s_barrier
	v_lshl_add_u64 v[88:89], v[64:65], 0, s[4:5]
	global_load_lds_dwordx4 v[88:89], off
	s_mov_b32 m0, s19
	v_lshl_add_u64 v[88:89], v[66:67], 0, s[4:5]
	global_load_lds_dwordx4 v76, s[64:65]
	s_mov_b32 m0, s22
	s_nop 0
	global_load_lds_dwordx4 v[88:89], off
	s_mov_b32 m0, s23
	v_lshl_add_u64 v[88:89], v[68:69], 0, s[4:5]
	global_load_lds_dwordx4 v77, s[64:65]
	s_mov_b32 m0, s29
	s_nop 0
	global_load_lds_dwordx4 v[88:89], off
	s_mov_b32 m0, s69
	v_lshl_add_u64 v[88:89], v[70:71], 0, s[4:5]
	global_load_lds_dwordx4 v78, s[64:65]
	s_mov_b32 m0, s70
	s_mov_b64 s[4:5], 0x780
	global_load_lds_dwordx4 v[88:89], off
	s_mov_b32 m0, s71
	v_lshl_add_u64 v[64:65], v[64:65], 0, s[4:5]
	global_load_lds_dwordx4 v84, s[64:65]
	ds_read_b128 v[88:91], v79 offset:32768
	ds_read_b128 v[92:95], v81 offset:49152
	ds_read_b128 v[96:99], v81 offset:53248
	s_waitcnt lgkmcnt(0)
	v_mfma_f32_32x32x16_bf16 v[48:63], v[88:91], v[92:95], v[48:63]
	s_mov_b32 m0, s84
	s_movk_i32 s4, 0x4000
	v_mfma_f32_32x32x16_bf16 v[32:47], v[88:91], v[96:99], v[32:47]
	ds_read_b128 v[88:91], v79 offset:36864
	s_waitcnt lgkmcnt(0)
	v_mfma_f32_32x32x16_bf16 v[16:31], v[88:91], v[92:95], v[16:31]
	v_mfma_f32_32x32x16_bf16 v[0:15], v[88:91], v[96:99], v[0:15]
	ds_read_b128 v[88:91], v80 offset:32768
	ds_read_b128 v[92:95], v83 offset:49152
	ds_read_b128 v[96:99], v83 offset:53248
	s_waitcnt lgkmcnt(0)
	v_mfma_f32_32x32x16_bf16 v[48:63], v[88:91], v[92:95], v[48:63]
	v_mfma_f32_32x32x16_bf16 v[32:47], v[88:91], v[96:99], v[32:47]
	ds_read_b128 v[88:91], v80 offset:36864
	s_waitcnt lgkmcnt(0)
	v_mfma_f32_32x32x16_bf16 v[16:31], v[88:91], v[92:95], v[16:31]
	v_mfma_f32_32x32x16_bf16 v[0:15], v[88:91], v[96:99], v[0:15]
	ds_read_b128 v[88:91], v82 offset:32768
	ds_read_b128 v[92:95], v85 offset:49152
	ds_read_b128 v[96:99], v85 offset:53248
	s_waitcnt lgkmcnt(0)
	v_mfma_f32_32x32x16_bf16 v[48:63], v[88:91], v[92:95], v[48:63]
	v_mfma_f32_32x32x16_bf16 v[32:47], v[88:91], v[96:99], v[32:47]
	ds_read_b128 v[88:91], v82 offset:36864
	s_waitcnt lgkmcnt(0)
	v_mfma_f32_32x32x16_bf16 v[16:31], v[88:91], v[92:95], v[16:31]
	v_mfma_f32_32x32x16_bf16 v[0:15], v[88:91], v[96:99], v[0:15]
	ds_read_b128 v[88:91], v86 offset:32768
	ds_read_b128 v[92:95], v87 offset:49152
	ds_read_b128 v[96:99], v87 offset:53248
	s_waitcnt lgkmcnt(0)
	v_mfma_f32_32x32x16_bf16 v[48:63], v[88:91], v[92:95], v[48:63]
	v_mfma_f32_32x32x16_bf16 v[32:47], v[88:91], v[96:99], v[32:47]
	ds_read_b128 v[88:91], v86 offset:36864
	s_waitcnt vmcnt(0)
	s_waitcnt vmcnt(0) lgkmcnt(0)
	s_barrier
; #define WAIT_V0() asm volatile("s_waitcnt vmcnt(0)" ::: "memory")
; DI void gemm_core(char* smem, int nk, const char* Ab, const char* Bb, const unsigned (&aoff)[4], const unsigned (&boff)[4],
;                   f32x16 (&acc)[2][2]) {
;     ...
;   for (int kt = 0; kt < nk; ++kt) {
;     const int cur = kt & 1;
;     if (kt + 1 < nk) stage(cur ^ 1, kt + 1);
;     const char* sb = smem + cur * STAGE_B;
; #pragma unroll
;     for (int ks = 0; ks < 4; ++ks) {
;       bf16x8 af[2], bfr[2];
; #pragma unroll
;       for (int mb = 0; mb < 2; ++mb) af[mb] = *(const bf16x8*)(sb + a_base + mb * 4096 + xo[ks]);
; #pragma unroll
;       for (int nb = 0; nb < 2; ++nb) bfr[nb] = *(const bf16x8*)(sb + b_base + nb * 4096 + xo[ks]);
; #pragma unroll
;       for (int mb = 0; mb < 2; ++mb)
; #pragma unroll
;         for (int nb = 0; nb < 2; ++nb)
;           acc[mb][nb] = __builtin_amdgcn_mfma_f32_32x32x16_bf16(af[mb], bfr[nb], acc[mb][nb], 0, 0, 0);
;     }
;     WAIT_V0();
;     __syncthreads();
;   }
	global_load_lds_dwordx4 v[64:65], off
	s_mov_b32 m0, s85
	v_lshl_add_u64 v[64:65], v[66:67], 0, s[6:7]
	global_load_lds_dwordx4 v76, s[66:67]
	s_mov_b32 m0, s86
	v_mfma_f32_32x32x16_bf16 v[16:31], v[88:91], v[92:95], v[16:31]
	global_load_lds_dwordx4 v[64:65], off
	s_mov_b32 m0, s87
	v_lshl_add_u64 v[64:65], v[68:69], 0, s[6:7]
	global_load_lds_dwordx4 v77, s[66:67]
	s_mov_b32 m0, s88
	v_mfma_f32_32x32x16_bf16 v[0:15], v[88:91], v[96:99], v[0:15]
	global_load_lds_dwordx4 v[64:65], off
	s_mov_b32 m0, s89
	v_lshl_add_u64 v[64:65], v[70:71], 0, s[6:7]
	global_load_lds_dwordx4 v78, s[66:67]
	s_mov_b32 m0, s90
	v_readlane_b32 s86, v254, 58
	global_load_lds_dwordx4 v[64:65], off
	s_mov_b32 m0, s91
	v_readlane_b32 s87, v254, 59
	global_load_lds_dwordx4 v84, s[66:67]
	ds_read_b128 v[64:67], v79
	ds_read_b128 v[68:71], v81 offset:16384
	ds_read_b128 v[88:91], v81 offset:20480
	s_waitcnt lgkmcnt(0)
	v_mfma_f32_32x32x16_bf16 v[48:63], v[64:67], v[68:71], v[48:63]
	v_mfma_f32_32x32x16_bf16 v[32:47], v[64:67], v[88:91], v[32:47]
	ds_read_b128 v[64:67], v79 offset:4096
	s_waitcnt lgkmcnt(0)
	v_mfma_f32_32x32x16_bf16 v[16:31], v[64:67], v[68:71], v[16:31]
	v_mfma_f32_32x32x16_bf16 v[0:15], v[64:67], v[88:91], v[0:15]
	ds_read_b128 v[64:67], v80
	ds_read_b128 v[68:71], v83 offset:16384
	ds_read_b128 v[88:91], v83 offset:20480
	s_waitcnt lgkmcnt(0)
	v_mfma_f32_32x32x16_bf16 v[48:63], v[64:67], v[68:71], v[48:63]
	v_mfma_f32_32x32x16_bf16 v[32:47], v[64:67], v[88:91], v[32:47]
	ds_read_b128 v[64:67], v80 offset:4096
	s_waitcnt lgkmcnt(0)
	v_mfma_f32_32x32x16_bf16 v[16:31], v[64:67], v[68:71], v[16:31]
	v_mfma_f32_32x32x16_bf16 v[0:15], v[64:67], v[88:91], v[0:15]
	ds_read_b128 v[64:67], v82
	ds_read_b128 v[68:71], v85 offset:16384
	ds_read_b128 v[88:91], v85 offset:20480
	s_waitcnt lgkmcnt(0)
	v_mfma_f32_32x32x16_bf16 v[48:63], v[64:67], v[68:71], v[48:63]
	v_mfma_f32_32x32x16_bf16 v[32:47], v[64:67], v[88:91], v[32:47]
	ds_read_b128 v[64:67], v82 offset:4096
	s_waitcnt lgkmcnt(0)
	v_mfma_f32_32x32x16_bf16 v[16:31], v[64:67], v[68:71], v[16:31]
	v_mfma_f32_32x32x16_bf16 v[0:15], v[64:67], v[88:91], v[0:15]
	ds_read_b128 v[64:67], v86
	ds_read_b128 v[68:71], v87 offset:16384
	ds_read_b128 v[88:91], v87 offset:20480
	s_waitcnt lgkmcnt(0)
	v_mfma_f32_32x32x16_bf16 v[48:63], v[64:67], v[68:71], v[48:63]
	v_mfma_f32_32x32x16_bf16 v[32:47], v[64:67], v[88:91], v[32:47]
	ds_read_b128 v[64:67], v86 offset:4096
	s_waitcnt lgkmcnt(0)
	v_mfma_f32_32x32x16_bf16 v[16:31], v[64:67], v[68:71], v[16:31]
	v_mfma_f32_32x32x16_bf16 v[0:15], v[64:67], v[88:91], v[0:15]
	s_waitcnt vmcnt(0)
	s_barrier
	ds_read_b128 v[64:67], v79 offset:32768
	ds_read_b128 v[68:71], v81 offset:49152
	ds_read_b128 v[88:91], v81 offset:53248
	s_waitcnt lgkmcnt(1)
	v_mfma_f32_32x32x16_bf16 v[48:63], v[64:67], v[68:71], v[48:63]
	s_waitcnt lgkmcnt(0)
	v_mfma_f32_32x32x16_bf16 v[32:47], v[64:67], v[88:91], v[32:47]
	ds_read_b128 v[64:67], v79 offset:36864
	s_waitcnt lgkmcnt(0)
	v_mfma_f32_32x32x16_bf16 v[16:31], v[64:67], v[68:71], v[16:31]
	v_mfma_f32_32x32x16_bf16 v[0:15], v[64:67], v[88:91], v[0:15]
	ds_read_b128 v[64:67], v80 offset:32768
	ds_read_b128 v[68:71], v83 offset:49152
	ds_read_b128 v[76:79], v83 offset:53248
	s_waitcnt lgkmcnt(1)
	v_mfma_f32_32x32x16_bf16 v[48:63], v[64:67], v[68:71], v[48:63]
	s_waitcnt lgkmcnt(0)
	v_mfma_f32_32x32x16_bf16 v[32:47], v[64:67], v[76:79], v[32:47]
	ds_read_b128 v[64:67], v80 offset:36864
	s_waitcnt lgkmcnt(0)
	v_mfma_f32_32x32x16_bf16 v[16:31], v[64:67], v[68:71], v[16:31]
	v_mfma_f32_32x32x16_bf16 v[0:15], v[64:67], v[76:79], v[0:15]
	ds_read_b128 v[64:67], v82 offset:32768
	ds_read_b128 v[68:71], v85 offset:49152
	ds_read_b128 v[76:79], v85 offset:53248
	s_waitcnt lgkmcnt(1)
	v_mfma_f32_32x32x16_bf16 v[48:63], v[64:67], v[68:71], v[48:63]
	s_waitcnt lgkmcnt(0)
	v_mfma_f32_32x32x16_bf16 v[32:47], v[64:67], v[76:79], v[32:47]
	ds_read_b128 v[64:67], v82 offset:36864
	s_waitcnt lgkmcnt(0)
	v_mfma_f32_32x32x16_bf16 v[16:31], v[64:67], v[68:71], v[16:31]
	ds_read_b128 v[68:71], v87 offset:53248
	ds_read_b128 v[80:83], v87 offset:49152
	ds_read_b128 v[88:91], v86 offset:36864
	ds_read_b128 v[84:87], v86 offset:32768
	s_waitcnt vmcnt(0)
	s_waitcnt lgkmcnt(0)
	s_barrier
; DI int ltid() { int t = threadIdx.x; asm volatile("" : "+v"(t)); return t; }
; template <class F>
; DI void epi_foreach(const f32x16 (&acc)[2][2], F f) {
;   const int lane = ltid() & 63, w = ltid() >> 6;
;   const int wm = w >> 1, wn = w & 1;
; #pragma unroll
;   for (int mb = 0; mb < 2; ++mb)
; #pragma unroll
;     for (int nb = 0; nb < 2; ++nb)
; #pragma unroll
;       for (int r = 0; r < 16; ++r) {
;         const int row = wm * 64 + mb * 32 + (r & 3) + 8 * (r >> 2) + 4 * (lane >> 5);
;         const int col = wn * 64 + nb * 32 + (lane & 31);
;         f(row, col, acc[mb][nb][r]);
;         if ((r & 7) == 7) __builtin_amdgcn_sched_barrier(0);
;       }
; DI void phase_up(const Params& P, int layer, char* smem) {
;     ...
;     epi_foreach(acc, [&](int row, int col, float v) __attribute__((always_inline)) { Cs[row * 136 + col] = f2bf(v); });
;     __syncthreads();
;     {
;       const int col = tid & 63, rb = tid >> 6;
;       const int cv = nt * 64 + col, cg_ = DFF + nt * 64 + col;
;       const float w0v = cw[cv], w1v = cw[5632 + cv], w2v = cw[2 * 5632 + cv], bv = cb[cv];
;       const float w0g = cw[cg_], w1g = cw[5632 + cg_], w2g = cw[2 * 5632 + cg_], bgt = cb[cg_];
	v_mfma_f32_32x32x16_bf16 v[48:63], v[84:87], v[80:83], v[48:63]
	v_mfma_f32_32x32x16_bf16 v[0:15], v[64:67], v[76:79], v[0:15]
	v_mov_b32_e32 v64, v161
	v_mov_b32_e32 v65, v161
	v_lshrrev_b32_e32 v67, 3, v64
	v_and_b32_e32 v67, 4, v67
	v_lshrrev_b32_e32 v66, 1, v65
	v_and_b32_e32 v64, 31, v64
	v_and_or_b32 v64, v65, 64, v64
	v_and_or_b32 v65, v66, s3, v67
	v_mul_lo_u32 v65, v65, s97
	s_nop 1
	v_cvt_pk_bf16_f32 v48, v48, s0
	v_lshl_add_u32 v64, v64, 1, v65
	ds_write_b16 v64, v48
	v_cvt_pk_bf16_f32 v48, v49, s0
	ds_write_b16 v64, v48 offset:272
	v_cvt_pk_bf16_f32 v48, v50, s0
	ds_write_b16 v64, v48 offset:544
	v_cvt_pk_bf16_f32 v48, v51, s0
	ds_write_b16 v64, v48 offset:816
	v_cvt_pk_bf16_f32 v48, v52, s0
	ds_write_b16 v64, v48 offset:2176
	v_cvt_pk_bf16_f32 v48, v53, s0
	ds_write_b16 v64, v48 offset:2448
	v_cvt_pk_bf16_f32 v48, v54, s0
	ds_write_b16 v64, v48 offset:2720
	v_cvt_pk_bf16_f32 v48, v55, s0
	v_mfma_f32_32x32x16_bf16 v[32:47], v[84:87], v[68:71], v[32:47]
	ds_write_b16 v64, v48 offset:2992
	v_mfma_f32_32x32x16_bf16 v[16:31], v[88:91], v[80:83], v[16:31]
	v_mfma_f32_32x32x16_bf16 v[0:15], v[88:91], v[68:71], v[0:15]
	v_cvt_pk_bf16_f32 v48, v56, s0
	ds_write_b16 v64, v48 offset:4352
	v_cvt_pk_bf16_f32 v48, v57, s0
	ds_write_b16 v64, v48 offset:4624
	v_cvt_pk_bf16_f32 v48, v58, s0
	ds_write_b16 v64, v48 offset:4896
	v_cvt_pk_bf16_f32 v48, v59, s0
	ds_write_b16 v64, v48 offset:5168
	v_cvt_pk_bf16_f32 v48, v60, s0
	ds_write_b16 v64, v48 offset:6528
	v_cvt_pk_bf16_f32 v48, v61, s0
	ds_write_b16 v64, v48 offset:6800
	v_cvt_pk_bf16_f32 v48, v62, s0
	ds_write_b16 v64, v48 offset:7072
	v_cvt_pk_bf16_f32 v48, v63, s0
	ds_write_b16 v64, v48 offset:7344
	v_cvt_pk_bf16_f32 v32, v32, s0
	ds_write_b16 v64, v32 offset:64
	v_cvt_pk_bf16_f32 v32, v33, s0
	ds_write_b16 v64, v32 offset:336
	v_cvt_pk_bf16_f32 v32, v34, s0
	ds_write_b16 v64, v32 offset:608
	v_cvt_pk_bf16_f32 v32, v35, s0
	ds_write_b16 v64, v32 offset:880
	v_cvt_pk_bf16_f32 v32, v36, s0
	ds_write_b16 v64, v32 offset:2240
	v_cvt_pk_bf16_f32 v32, v37, s0
	ds_write_b16 v64, v32 offset:2512
	v_cvt_pk_bf16_f32 v32, v38, s0
	ds_write_b16 v64, v32 offset:2784
	v_cvt_pk_bf16_f32 v32, v39, s0
	ds_write_b16 v64, v32 offset:3056
	v_cvt_pk_bf16_f32 v32, v40, s0
	ds_write_b16 v64, v32 offset:4416
	v_cvt_pk_bf16_f32 v32, v41, s0
	ds_write_b16 v64, v32 offset:4688
	v_cvt_pk_bf16_f32 v32, v42, s0
	ds_write_b16 v64, v32 offset:4960
	v_cvt_pk_bf16_f32 v32, v43, s0
	ds_write_b16 v64, v32 offset:5232
	v_cvt_pk_bf16_f32 v32, v44, s0
	ds_write_b16 v64, v32 offset:6592
	v_cvt_pk_bf16_f32 v32, v45, s0
	ds_write_b16 v64, v32 offset:6864
	v_cvt_pk_bf16_f32 v32, v46, s0
	ds_write_b16 v64, v32 offset:7136
	v_cvt_pk_bf16_f32 v32, v47, s0
	ds_write_b16 v64, v32 offset:7408
	v_cvt_pk_bf16_f32 v16, v16, s0
	ds_write_b16 v64, v16 offset:8704
	v_cvt_pk_bf16_f32 v16, v17, s0
	ds_write_b16 v64, v16 offset:8976
	v_cvt_pk_bf16_f32 v16, v18, s0
	ds_write_b16 v64, v16 offset:9248
	v_cvt_pk_bf16_f32 v16, v19, s0
	ds_write_b16 v64, v16 offset:9520
	v_cvt_pk_bf16_f32 v16, v20, s0
	ds_write_b16 v64, v16 offset:10880
	v_cvt_pk_bf16_f32 v16, v21, s0
	ds_write_b16 v64, v16 offset:11152
	v_cvt_pk_bf16_f32 v16, v22, s0
	ds_write_b16 v64, v16 offset:11424
	v_cvt_pk_bf16_f32 v16, v23, s0
	ds_write_b16 v64, v16 offset:11696
	v_cvt_pk_bf16_f32 v16, v24, s0
	ds_write_b16 v64, v16 offset:13056
	v_cvt_pk_bf16_f32 v16, v25, s0
	ds_write_b16 v64, v16 offset:13328
	v_cvt_pk_bf16_f32 v16, v26, s0
	ds_write_b16 v64, v16 offset:13600
	v_cvt_pk_bf16_f32 v16, v27, s0
	ds_write_b16 v64, v16 offset:13872
	v_cvt_pk_bf16_f32 v16, v28, s0
	ds_write_b16 v64, v16 offset:15232
	v_cvt_pk_bf16_f32 v16, v29, s0
	ds_write_b16 v64, v16 offset:15504
	v_cvt_pk_bf16_f32 v16, v30, s0
	ds_write_b16 v64, v16 offset:15776
	v_cvt_pk_bf16_f32 v16, v31, s0
	ds_write_b16 v64, v16 offset:16048
	v_cvt_pk_bf16_f32 v0, v0, s0
	ds_write_b16 v64, v0 offset:8768
	v_cvt_pk_bf16_f32 v0, v1, s0
	ds_write_b16 v64, v0 offset:9040
	v_cvt_pk_bf16_f32 v0, v2, s0
	ds_write_b16 v64, v0 offset:9312
	v_cvt_pk_bf16_f32 v0, v3, s0
	ds_write_b16 v64, v0 offset:9584
	v_cvt_pk_bf16_f32 v0, v4, s0
	ds_write_b16 v64, v0 offset:10944
	v_cvt_pk_bf16_f32 v0, v5, s0
	ds_write_b16 v64, v0 offset:11216
	v_cvt_pk_bf16_f32 v0, v6, s0
	ds_write_b16 v64, v0 offset:11488
	v_cvt_pk_bf16_f32 v0, v7, s0
	ds_write_b16 v64, v0 offset:11760
	v_cvt_pk_bf16_f32 v0, v8, s0
	ds_write_b16 v64, v0 offset:13120
	v_cvt_pk_bf16_f32 v0, v9, s0
	ds_write_b16 v64, v0 offset:13392
	v_cvt_pk_bf16_f32 v0, v10, s0
	ds_write_b16 v64, v0 offset:13664
	v_cvt_pk_bf16_f32 v0, v11, s0
	ds_write_b16 v64, v0 offset:13936
	v_cvt_pk_bf16_f32 v0, v12, s0
	ds_write_b16 v64, v0 offset:15296
	v_cvt_pk_bf16_f32 v0, v13, s0
	ds_write_b16 v64, v0 offset:15568
	v_cvt_pk_bf16_f32 v0, v14, s0
	ds_write_b16 v64, v0 offset:15840
	v_cvt_pk_bf16_f32 v0, v15, s0
	ds_write_b16 v64, v0 offset:16112
	s_waitcnt lgkmcnt(0)
	s_barrier
	s_and_saveexec_b64 s[18:19], s[40:41]
	s_mov_b32 s3, 0xb000
	s_cbranch_execz .LBB0_24
	v_add_u32_e32 v136, s21, v74
	v_lshlrev_b64 v[4:5], 2, v[136:137]
	v_lshl_add_u64 v[8:9], s[10:11], 0, v[4:5]
	v_or_b32_e32 v10, s21, v72
	v_lshlrev_b32_e32 v126, 1, v10
	v_lshl_add_u64 v[2:3], s[12:13], 0, v[4:5]
	v_add_co_u32_e32 v4, vcc, 0xb000, v8
	v_ashrrev_i32_e32 v11, 31, v10
	s_nop 0
	v_addc_co_u32_e32 v5, vcc, 0, v9, vcc
	v_lshl_add_u64 v[0:1], v[10:11], 1, s[86:87]
	v_add_co_u32_e32 v6, vcc, 0x5000, v8
	v_lshlrev_b64 v[10:11], 2, v[10:11]
	s_nop 0
	v_addc_co_u32_e32 v7, vcc, 0, v9, vcc
	v_lshl_add_u64 v[12:13], s[12:13], 0, v[10:11]
	v_lshl_add_u64 v[10:11], s[10:11], 0, v[10:11]
	global_load_dword v3, v[2:3], off
	s_mulk_i32 s20, 0x7e
	global_load_dword v5, v[4:5], off
	s_nop 0
	global_load_dword v7, v[6:7], off offset:2048
	s_nop 0
	global_load_dword v9, v[8:9], off
	s_mul_i32 s21, s68, 0x7a
	global_load_dword v2, v[12:13], off
	v_add_co_u32_e32 v12, vcc, s3, v10
	s_sub_i32 s29, s20, s21
	s_nop 0
	v_addc_co_u32_e32 v13, vcc, 0, v11, vcc
	global_load_dword v4, v[12:13], off
	v_add_co_u32_e32 v12, vcc, 0x5000, v10
	s_mov_b64 s[20:21], 0
	s_nop 0
	v_addc_co_u32_e32 v13, vcc, 0, v11, vcc
	global_load_dword v6, v[12:13], off offset:2048
	global_load_dword v8, v[10:11], off
	v_mov_b32_e32 v11, v73
	v_mul_u32_u24_e32 v10, 0x110, v73
	v_mov_b32_e32 v128, 0
	v_mov_b32_e32 v129, 0
	v_mov_b32_e32 v130, 0
	v_mov_b32_e32 v131, 0
	v_mov_b32_e32 v132, 0
	v_mov_b32_e32 v133, 0
	v_mov_b32_e32 v134, 0
	v_mov_b32_e32 v135, 0
	s_waitcnt vmcnt(0)
	v_readfirstlane_b32 s22, v73
	v_add_u32_e32 v10, v75, v10
	v_add_u32_e32 v127, 0x1600, v126
	s_lshl_b32 s22, s22, 1
	s_add_i32 s23, s29, s22
	s_mul_hi_i32 s21, s23, 0x1600
	s_mul_i32 s20, s23, 0x1600
	s_add_u32 s20, s20, s86
	s_addc_u32 s21, s21, s87
	s_branch .LBB0_28

; template <class T> DI T* uoff(T* base, unsigned byteoff) { return (T*)((char*)base + byteoff); }
; template <class T> DI const T* uoff(const T* base, unsigned byteoff) { return (const T*)((const char*)base + byteoff); }
; DI void phase_out(const Params& P, int layer, const float* xin, char* smem) {
;     ...
;   for (int t0 = blockIdx.x; t0 < 256 * 8; t0 += gridDim.x) {
;     const int t = xcd_tile(t0, 256 * 8);
;     const int m0 = (t >> 3) * 128, n0 = (t & 7) * 128;
;     f32x16 acc[2][2];
;     float xr[2][2][16];
;     const unsigned obase_b = 4u * (unsigned)((m0 + wm * 64 + 4 * (lane >> 5)) * 1024 + n0 + wn * 64 + (lane & 31));
; #pragma unroll
;     for (int mb = 0; mb < 2; ++mb)
; #pragma unroll
;       for (int nb = 0; nb < 2; ++nb)
; #pragma unroll
;         for (int r = 0; r < 16; ++r) xr[mb][nb][r] = (*uoff(xin + ((mb * 32 + (r & 3) + 8 * (r >> 2)) * 1024 + nb * 32), obase_b));
.LBB0_43:
	s_ashr_i32 s0, s14, 3
	s_and_b32 s1, s0, 0xffffffc0
	s_lshl_b32 s10, s0, 1
	s_bfe_u32 s11, s0, 0x10005
	s_and_b32 s10, s10, 62
	s_or_b32 s1, s11, s1
	s_or_b32 s1, s1, s10
	s_and_b32 s10, s13, 0x700
	s_or_b32 s11, s0, 63
	s_cmpk_lt_i32 s11, 0x100
	s_cselect_b32 s1, s1, s0
	s_add_i32 s0, s1, s10
	s_lshl_b32 s0, s0, 4
	s_and_b32 s0, s0, 0xffffff80
	s_lshl_b32 s1, s1, 7
	s_and_b32 s15, s1, 0x380
	v_add_lshl_u32 v0, v80, s0, 10
	v_or3_b32 v0, v0, v81, s15
	v_lshlrev_b32_e32 v136, 2, v0
	v_lshl_add_u64 v[0:1], s[18:19], 0, v[136:137]
	v_add_co_u32_e32 v2, vcc, s17, v0
	s_mov_b32 s2, 0x13000
	s_nop 0
	v_addc_co_u32_e32 v3, vcc, 0, v1, vcc
	v_add_co_u32_e32 v4, vcc, s16, v0
	s_mov_b32 s68, 0x18000
	s_nop 0
	v_addc_co_u32_e32 v5, vcc, 0, v1, vcc
	v_add_co_u32_e32 v6, vcc, s20, v0
	s_mov_b32 s3, 0x1b000
	s_nop 0
	v_addc_co_u32_e32 v7, vcc, 0, v1, vcc
	v_add_co_u32_e32 v8, vcc, s9, v0
	global_load_dword v147, v136, s[18:19]
	s_nop 0
	v_addc_co_u32_e32 v9, vcc, 0, v1, vcc
	v_add_co_u32_e32 v10, vcc, s21, v0
	global_load_dword v148, v[4:5], off offset:-4096
	global_load_dword v145, v[4:5], off
	v_addc_co_u32_e32 v11, vcc, 0, v1, vcc
	v_add_co_u32_e32 v12, vcc, s22, v0
	global_load_dword v146, v[6:7], off
	s_nop 0
	v_addc_co_u32_e32 v13, vcc, 0, v1, vcc
	v_add_co_u32_e32 v14, vcc, s23, v0
	global_load_dword v144, v[10:11], off offset:-4096
	global_load_dword v142, v[10:11], off
	v_addc_co_u32_e32 v15, vcc, 0, v1, vcc
	v_add_co_u32_e32 v16, vcc, s28, v0
	global_load_dword v143, v[14:15], off offset:-4096
	global_load_dword v140, v[14:15], off
	v_addc_co_u32_e32 v17, vcc, 0, v1, vcc
	v_add_co_u32_e32 v18, vcc, s29, v0
	s_mov_b32 s6, 0x21000
	s_nop 0
	v_addc_co_u32_e32 v19, vcc, 0, v1, vcc
	v_add_co_u32_e32 v20, vcc, s42, v0
	global_load_dword v141, v[18:19], off offset:-4096
	global_load_dword v135, v[18:19], off
	v_addc_co_u32_e32 v21, vcc, 0, v1, vcc
	v_add_co_u32_e32 v22, vcc, s2, v0
	s_mov_b32 s2, 0x19000
	s_nop 0
	v_addc_co_u32_e32 v23, vcc, 0, v1, vcc
	v_add_co_u32_e32 v24, vcc, s68, v0
	s_mov_b32 s68, 0x1a000
	s_nop 0
	v_addc_co_u32_e32 v25, vcc, 0, v1, vcc
	v_add_co_u32_e32 v26, vcc, s2, v0
	global_load_dword v139, v[22:23], off offset:-4096
	global_load_dword v133, v[22:23], off
	v_addc_co_u32_e32 v27, vcc, 0, v1, vcc
	v_add_co_u32_e32 v28, vcc, s68, v0
	global_load_dword v134, v[26:27], off offset:-4096
	global_load_dword v131, v[26:27], off
	v_addc_co_u32_e32 v29, vcc, 0, v1, vcc
	v_add_co_u32_e32 v30, vcc, s3, v0
	s_mov_b32 s3, 0x20000
	s_nop 0
	v_addc_co_u32_e32 v31, vcc, 0, v1, vcc
	global_load_dword v132, v[30:31], off offset:-4096
	global_load_dword v130, v[30:31], off
	global_load_dword v129, v136, s[18:19] offset:128
	global_load_dword v128, v[2:3], off offset:128
	global_load_dword v127, v[4:5], off offset:128
	global_load_dword v126, v[6:7], off offset:128
	global_load_dword v125, v[8:9], off offset:128
	global_load_dword v124, v[10:11], off offset:128
	global_load_dword v123, v[12:13], off offset:128
	global_load_dword v122, v[14:15], off offset:128
	global_load_dword v121, v[16:17], off offset:128
	global_load_dword v120, v[18:19], off offset:128
	global_load_dword v119, v[20:21], off offset:128
	global_load_dword v117, v[22:23], off offset:128
	global_load_dword v116, v[24:25], off offset:128
	global_load_dword v115, v[26:27], off offset:128
	global_load_dword v114, v[28:29], off offset:128
	global_load_dword v113, v[30:31], off offset:128
	v_add_co_u32_e32 v2, vcc, s3, v0
	s_mov_b32 s12, 0x23000
	s_nop 0
	v_addc_co_u32_e32 v3, vcc, 0, v1, vcc
	v_add_co_u32_e32 v4, vcc, s6, v0
	s_mov_b32 s6, 0x22000
	s_nop 0
	v_addc_co_u32_e32 v5, vcc, 0, v1, vcc
	v_add_co_u32_e32 v6, vcc, s6, v0
	s_mov_b32 s8, 0x28000
	s_nop 0
	v_addc_co_u32_e32 v7, vcc, 0, v1, vcc
	v_add_co_u32_e32 v8, vcc, s12, v0
	s_mov_b32 s64, 0x2a000
	s_nop 0
	v_addc_co_u32_e32 v9, vcc, 0, v1, vcc
	v_add_co_u32_e32 v10, vcc, s8, v0
	s_mov_b32 s8, 0x29000
	s_nop 0
	v_addc_co_u32_e32 v11, vcc, 0, v1, vcc
	v_add_co_u32_e32 v12, vcc, s8, v0
	s_mov_b32 s65, 0x30000
	s_nop 0
	v_addc_co_u32_e32 v13, vcc, 0, v1, vcc
	v_add_co_u32_e32 v14, vcc, s64, v0
	s_mov_b32 s64, 0x2b000
	s_nop 0
	v_addc_co_u32_e32 v15, vcc, 0, v1, vcc
	v_add_co_u32_e32 v16, vcc, s64, v0
	s_mov_b32 s66, 0x32000
	s_nop 0
	v_addc_co_u32_e32 v17, vcc, 0, v1, vcc
	v_add_co_u32_e32 v18, vcc, s65, v0
	s_mov_b32 s65, 0x31000
	s_nop 0
	v_addc_co_u32_e32 v19, vcc, 0, v1, vcc
	v_add_co_u32_e32 v20, vcc, s65, v0
	s_mov_b32 s67, 0x38000
	s_nop 0
	v_addc_co_u32_e32 v21, vcc, 0, v1, vcc
	v_add_co_u32_e32 v22, vcc, s66, v0
	s_mov_b32 s66, 0x33000
	s_nop 0
	v_addc_co_u32_e32 v23, vcc, 0, v1, vcc
	v_add_co_u32_e32 v24, vcc, s66, v0
	global_load_dword v118, v[4:5], off offset:-4096
	global_load_dword v111, v[4:5], off
	v_addc_co_u32_e32 v25, vcc, 0, v1, vcc
	v_add_co_u32_e32 v26, vcc, s67, v0
	s_mov_b32 s67, 0x39000
	s_nop 0
	v_addc_co_u32_e32 v27, vcc, 0, v1, vcc
	v_add_co_u32_e32 v28, vcc, s67, v0
	global_load_dword v112, v[8:9], off offset:-4096
	global_load_dword v109, v[8:9], off
	v_addc_co_u32_e32 v29, vcc, 0, v1, vcc
	v_add_co_u32_e32 v30, vcc, s69, v0
	global_load_dword v110, v[12:13], off offset:-4096
	global_load_dword v107, v[12:13], off
	v_addc_co_u32_e32 v31, vcc, 0, v1, vcc
	v_add_co_u32_e32 v0, vcc, s71, v0
	global_load_dword v108, v[16:17], off offset:-4096
	global_load_dword v105, v[16:17], off
	v_addc_co_u32_e32 v1, vcc, 0, v1, vcc
	global_load_dword v106, v[20:21], off offset:-4096
	global_load_dword v103, v[20:21], off
	global_load_dword v104, v[24:25], off offset:-4096
	global_load_dword v101, v[24:25], off
	global_load_dword v102, v[28:29], off offset:-4096
	global_load_dword v99, v[28:29], off
; #define WAIT_V0() asm volatile("s_waitcnt vmcnt(0)" ::: "memory")
; DI int glds_row(int i) { const int tid = ltid(); return ((tid >> 6) * 4 + i) * 8 + ((tid & 63) >> 3); }
; DI int glds_chunk(int row) { return (ltid() & 7) ^ ((row >> 1) & 7); }
; DI void gemm_core(char* smem, int nk, const char* Ab, const char* Bb, const unsigned (&aoff)[4], const unsigned (&boff)[4],
;                   f32x16 (&acc)[2][2]) {
;     ...
;   auto stage = [&](int buf, int kt) __attribute__((always_inline)) {
;     const char* ak = Ab + kt * 128;
;     const char* bk = Bb + kt * 128;
;     char* sa = smem + buf * STAGE_B + w * 4096;
; #pragma unroll
;     for (int i = 0; i < 4; ++i) {
;       __builtin_amdgcn_global_load_lds((const unsigned*)(ak + aoff[i]), (unsigned*)(sa + i * 1024), 16, 0, 0);
;       __builtin_amdgcn_global_load_lds((const unsigned*)(bk + boff[i]), (unsigned*)(sa + 16384 + i * 1024), 16, 0, 0);
;     }
;   };
;   stage(0, 0);
;   WAIT_V0();
;   __syncthreads();
; DI void gemm_tile(char* smem, int nk, const bf16* A, int lda, int m0, const bf16* Bt, int ldb, int n0, f32x16 (&acc)[2][2]) {
;   unsigned aoff[4], boff[4];
; #pragma unroll
;   for (int i = 0; i < 4; ++i) {
;     const int row = glds_row(i), ch = glds_chunk(row);
;     aoff[i] = (unsigned)((row * lda + ch * 8) * 2);
;     boff[i] = (unsigned)((row * ldb + ch * 8) * 2);
;   }
;   gemm_core(smem, nk, (const char*)(A + (size_t)m0 * lda), (const char*)(Bt + (size_t)n0 * ldb), aoff, boff, acc);
; }
	global_load_dword v100, v[0:1], off offset:-4096
	global_load_dword v98, v[0:1], off
	global_load_dword v97, v[2:3], off offset:128
	global_load_dword v96, v[4:5], off offset:128
	global_load_dword v95, v[6:7], off offset:128
	global_load_dword v94, v[8:9], off offset:128
	global_load_dword v93, v[10:11], off offset:128
	global_load_dword v92, v[12:13], off offset:128
	global_load_dword v91, v[14:15], off offset:128
	global_load_dword v90, v[16:17], off offset:128
	global_load_dword v89, v[18:19], off offset:128
	global_load_dword v88, v[20:21], off offset:128
	global_load_dword v87, v[22:23], off offset:128
	global_load_dword v86, v[24:25], off offset:128
	global_load_dword v85, v[26:27], off offset:128
	global_load_dword v84, v[28:29], off offset:128
	global_load_dword v83, v[30:31], off offset:128
	global_load_dword v82, v[0:1], off offset:128
	v_mov_b32_e32 v0, v161
	s_ashr_i32 s1, s0, 31
	v_lshrrev_b32_e32 v1, 1, v0
	v_lshrrev_b32_e32 v2, 3, v0
	v_bfe_u32 v0, v0, 3, 3
	v_and_or_b32 v0, v1, s43, v0
	v_mov_b32_e32 v1, v161
	v_bfe_u32 v2, v2, 1, 2
	v_xor_b32_e32 v1, v2, v1
	v_lshlrev_b32_e32 v0, 11, v0
	v_lshlrev_b32_e32 v1, 4, v1
	v_and_or_b32 v2, v1, s92, v0
	v_mov_b32_e32 v0, v161
	s_lshl_b64 s[0:1], s[0:1], 11
	v_ashrrev_i32_e32 v1, 1, v0
	v_and_b32_e32 v1, 0xffffffe0, v1
	v_bfe_u32 v0, v0, 3, 3
	v_or3_b32 v0, v0, v1, 8
	v_mov_b32_e32 v1, v161
	v_lshrrev_b32_e32 v3, 1, v0
	v_xor_b32_e32 v1, v3, v1
	v_lshlrev_b32_e32 v0, 11, v0
	v_lshlrev_b32_e32 v1, 4, v1
	v_and_or_b32 v4, v1, s92, v0
	v_mov_b32_e32 v0, v161
	s_add_u32 s10, s4, s0
	v_lshrrev_b32_e32 v1, 1, v0
	v_lshrrev_b32_e32 v3, 3, v0
	v_bfe_u32 v0, v0, 3, 3
	v_and_or_b32 v0, v1, s43, v0
	v_mov_b32_e32 v1, v161
	v_bfe_u32 v3, v3, 1, 2
	v_xor_b32_e32 v1, v3, v1
	v_lshlrev_b32_e32 v1, 4, v1
	v_lshlrev_b32_e32 v0, 11, v0
	v_and_b32_e32 v1, 0x70, v1
	v_or3_b32 v6, v0, v1, s9
	v_mov_b32_e32 v0, v161
	s_addc_u32 s11, s5, s1
	v_ashrrev_i32_e32 v1, 1, v0
	v_and_b32_e32 v1, 0xffffffe0, v1
	v_bfe_u32 v0, v0, 3, 3
	v_or3_b32 v0, v0, v1, 24
	v_mov_b32_e32 v1, v161
	v_lshrrev_b32_e32 v3, 1, v0
	v_xor_b32_e32 v1, v3, v1
	v_lshlrev_b32_e32 v0, 11, v0
	v_lshlrev_b32_e32 v1, 4, v1
	v_and_or_b32 v0, v1, s92, v0
	v_mov_b32_e32 v1, v161
	s_lshl_b32 s0, s15, 11
	v_and_b32_e32 v3, 31, v1
	v_lshrrev_b32_e32 v5, 5, v1
	v_bfe_u32 v7, v1, 5, 1
	v_lshrrev_b32_e32 v8, 1, v1
	v_bfe_u32 v9, v1, 1, 3
	v_lshlrev_b32_e32 v10, 7, v1
	v_lshlrev_b32_e32 v1, 6, v1
	v_and_b32_e32 v154, 0xfffff000, v1
	v_readlane_b32 s1, v255, 6
	v_add_u32_e32 v151, 0x4000, v154
	v_readfirstlane_b32 s17, v154
	s_add_u32 s0, s1, s0
	v_readlane_b32 s1, v255, 5
	s_mov_b32 m0, s17
	v_readfirstlane_b32 s16, v151
	v_or_b32_e32 v160, 0x400, v154
	s_addc_u32 s1, s1, 0
	global_load_lds_dwordx4 v2, s[10:11]
	s_mov_b32 m0, s16
	v_readfirstlane_b32 s18, v160
	v_add_u32_e32 v159, 0x4400, v154
	global_load_lds_dwordx4 v2, s[0:1]
	s_mov_b32 m0, s18
	v_readfirstlane_b32 s19, v159
	v_or_b32_e32 v164, 0x800, v154
	global_load_lds_dwordx4 v4, s[10:11]
	s_mov_b32 m0, s19
	v_readfirstlane_b32 s21, v164
	v_add_u32_e32 v162, 0x4800, v154
	s_mov_b32 s12, 0x1ffffc0
	v_bitop3_b32 v5, v5, v9, 1 bitop3:0x6c
	global_load_lds_dwordx4 v4, s[0:1]
	s_mov_b32 m0, s21
	v_readfirstlane_b32 s20, v162
	v_or_b32_e32 v166, 0xc00, v154
	v_and_or_b32 v3, v8, s12, v3
	v_lshlrev_b32_e32 v8, 4, v5
	v_bitop3_b32 v5, v7, v9, 2 bitop3:0x36
	global_load_lds_dwordx4 v6, s[10:11]
	s_mov_b32 m0, s20
	v_readfirstlane_b32 s23, v166
	v_add_u32_e32 v168, 0x4c00, v154
	v_lshlrev_b32_e32 v153, 4, v5
	v_bitop3_b32 v5, v7, v9, 4 bitop3:0x36
	v_lshlrev_b32_e32 v157, 7, v3
	v_mov_b32_e32 v3, v137
	global_load_lds_dwordx4 v6, s[0:1]
	s_mov_b32 m0, s23
	v_readfirstlane_b32 s22, v168
	v_add_u32_e32 v172, 0x8000, v154
	v_lshlrev_b32_e32 v156, 4, v5
	v_bitop3_b32 v5, v7, v9, 6 bitop3:0x36
	v_lshl_add_u64 v[66:67], s[10:11], 0, v[2:3]
	v_mov_b32_e32 v1, v137
	global_load_lds_dwordx4 v0, s[10:11]
	s_mov_b32 m0, s22
	v_add_u32_e32 v170, 0xc000, v154
	v_readfirstlane_b32 s29, v172
	v_lshlrev_b32_e32 v158, 4, v5
	v_lshl_add_u64 v[64:65], s[0:1], 0, v[2:3]
	v_mov_b32_e32 v5, v137
	v_lshl_add_u64 v[76:77], s[10:11], 0, v[0:1]
	v_lshl_add_u64 v[78:79], s[0:1], 0, v[0:1]
	global_load_lds_dwordx4 v0, s[0:1]
	v_lshl_add_u64 v[0:1], v[66:67], 0, s[94:95]
	s_mov_b32 m0, s29
	v_readfirstlane_b32 s28, v170
	v_add_u32_e32 v174, 0x8400, v154
	v_lshl_add_u64 v[68:69], s[10:11], 0, v[4:5]
	v_mov_b32_e32 v7, v137
	global_load_lds_dwordx4 v[0:1], off
	v_lshl_add_u64 v[0:1], v[64:65], 0, s[94:95]
	s_mov_b32 m0, s28
	v_readfirstlane_b32 s42, v174
	v_add_u32_e32 v2, 0xc400, v154
	v_lshl_add_u64 v[70:71], s[0:1], 0, v[4:5]
	v_lshl_add_u64 v[72:73], s[0:1], 0, v[6:7]
	global_load_lds_dwordx4 v[0:1], off
	v_lshl_add_u64 v[0:1], v[68:69], 0, s[94:95]
	s_mov_b32 m0, s42
	v_readfirstlane_b32 s0, v2
	v_add_u32_e32 v2, 0x8800, v154
	v_lshl_add_u64 v[74:75], s[10:11], 0, v[6:7]
	global_load_lds_dwordx4 v[0:1], off
	v_lshl_add_u64 v[0:1], v[70:71], 0, s[94:95]
	s_mov_b32 m0, s0
	v_readfirstlane_b32 s1, v2
	v_add_u32_e32 v2, 0xc800, v154
	global_load_lds_dwordx4 v[0:1], off
	v_lshl_add_u64 v[0:1], v[74:75], 0, s[94:95]
	s_mov_b32 m0, s1
	v_readfirstlane_b32 s10, v2
	v_add_u32_e32 v2, 0x8c00, v154
	global_load_lds_dwordx4 v[0:1], off
	v_lshl_add_u64 v[0:1], v[72:73], 0, s[94:95]
	s_mov_b32 m0, s10
	v_readfirstlane_b32 s11, v2
	v_add_u32_e32 v2, 0xcc00, v154
	global_load_lds_dwordx4 v[0:1], off
	v_lshl_add_u64 v[0:1], v[76:77], 0, s[94:95]
	s_mov_b32 m0, s11
	v_readfirstlane_b32 s15, v2
	v_and_b32_e32 v176, 0x2f80, v10
	global_load_lds_dwordx4 v[0:1], off
	v_lshl_add_u64 v[0:1], v[78:79], 0, s[94:95]
	s_mov_b32 m0, s15
	v_or_b32_e32 v149, v157, v8
	global_load_lds_dwordx4 v[0:1], off
	s_waitcnt vmcnt(8)
	s_waitcnt vmcnt(8) lgkmcnt(0)
	s_barrier
; #define WAIT_V0() asm volatile("s_waitcnt vmcnt(0)" ::: "memory")
; DI void gemm_core(char* smem, int nk, const char* Ab, const char* Bb, const unsigned (&aoff)[4], const unsigned (&boff)[4],
;                   f32x16 (&acc)[2][2]) {
;     ...
;   for (int kt = 0; kt < nk; ++kt) {
;     const int cur = kt & 1;
;     if (kt + 1 < nk) stage(cur ^ 1, kt + 1);
;     const char* sb = smem + cur * STAGE_B;
; #pragma unroll
;     for (int ks = 0; ks < 4; ++ks) {
;       bf16x8 af[2], bfr[2];
; #pragma unroll
;       for (int mb = 0; mb < 2; ++mb) af[mb] = *(const bf16x8*)(sb + a_base + mb * 4096 + xo[ks]);
; #pragma unroll
;       for (int nb = 0; nb < 2; ++nb) bfr[nb] = *(const bf16x8*)(sb + b_base + nb * 4096 + xo[ks]);
; #pragma unroll
;       for (int mb = 0; mb < 2; ++mb)
; #pragma unroll
;         for (int nb = 0; nb < 2; ++nb)
;           acc[mb][nb] = __builtin_amdgcn_mfma_f32_32x32x16_bf16(af[mb], bfr[nb], acc[mb][nb], 0, 0, 0);
;     }
;     WAIT_V0();
;     __syncthreads();
;   }
	v_or_b32_e32 v150, v176, v8
	ds_read_b128 v[0:3], v149
	ds_read_b128 v[4:7], v149 offset:4096
	ds_read_b128 v[8:11], v150 offset:16384
	ds_read_b128 v[12:15], v150 offset:20480
	s_waitcnt lgkmcnt(0)
	v_mfma_f32_32x32x16_bf16 v[48:63], v[0:3], v[8:11], 0
	v_or_b32_e32 v152, v157, v153
	v_or_b32_e32 v153, v176, v153
	ds_read_b128 v[208:211], v152
	ds_read_b128 v[212:215], v152 offset:4096
	ds_read_b128 v[216:219], v153 offset:16384
	ds_read_b128 v[220:223], v153 offset:20480
	v_or_b32_e32 v155, v157, v156
	v_or_b32_e32 v156, v176, v156
	v_or_b32_e32 v157, v157, v158
	v_mfma_f32_32x32x16_bf16 v[32:47], v[0:3], v[12:15], 0
	v_or_b32_e32 v158, v176, v158
	s_mov_b32 m0, s17
	s_add_i32 s14, s14, s70
	s_add_i32 s13, s13, s7
	s_cmpk_gt_i32 s14, 0x7ff
	v_mfma_f32_32x32x16_bf16 v[16:31], v[4:7], v[8:11], 0
	v_mfma_f32_32x32x16_bf16 v[0:15], v[4:7], v[12:15], 0
	s_waitcnt lgkmcnt(0)
	v_mfma_f32_32x32x16_bf16 v[48:63], v[208:211], v[216:219], v[48:63]
	v_mfma_f32_32x32x16_bf16 v[32:47], v[208:211], v[220:223], v[32:47]
	v_mfma_f32_32x32x16_bf16 v[16:31], v[212:215], v[216:219], v[16:31]
	v_mfma_f32_32x32x16_bf16 v[0:15], v[212:215], v[220:223], v[0:15]
	ds_read_b128 v[208:211], v155
	ds_read_b128 v[212:215], v155 offset:4096
	ds_read_b128 v[216:219], v156 offset:16384
	ds_read_b128 v[220:223], v156 offset:20480
	s_waitcnt lgkmcnt(0)
	v_mfma_f32_32x32x16_bf16 v[48:63], v[208:211], v[216:219], v[48:63]
	v_mfma_f32_32x32x16_bf16 v[32:47], v[208:211], v[220:223], v[32:47]
	v_mfma_f32_32x32x16_bf16 v[16:31], v[212:215], v[216:219], v[16:31]
	v_mfma_f32_32x32x16_bf16 v[0:15], v[212:215], v[220:223], v[0:15]
	ds_read_b128 v[208:211], v157
	ds_read_b128 v[212:215], v157 offset:4096
	ds_read_b128 v[216:219], v158 offset:16384
	ds_read_b128 v[220:223], v158 offset:20480
	s_waitcnt lgkmcnt(0)
	v_mfma_f32_32x32x16_bf16 v[48:63], v[208:211], v[216:219], v[48:63]
	v_mfma_f32_32x32x16_bf16 v[32:47], v[208:211], v[220:223], v[32:47]
	v_mfma_f32_32x32x16_bf16 v[16:31], v[212:215], v[216:219], v[16:31]
	v_mfma_f32_32x32x16_bf16 v[0:15], v[212:215], v[220:223], v[0:15]
	s_waitcnt vmcnt(0)
	s_barrier
	ds_read_b128 v[208:211], v149 offset:32768
	ds_read_b128 v[212:215], v149 offset:36864
	ds_read_b128 v[216:219], v150 offset:49152
	ds_read_b128 v[220:223], v150 offset:53248
	v_lshl_add_u64 v[224:225], v[66:67], 0, s[90:91]
	global_load_lds_dwordx4 v[224:225], off
	v_lshl_add_u64 v[226:227], v[64:65], 0, s[90:91]
	s_mov_b32 m0, s16
	s_nop 0
	global_load_lds_dwordx4 v[226:227], off
	v_lshl_add_u64 v[224:225], v[68:69], 0, s[90:91]
	s_mov_b32 m0, s18
	s_nop 0
	global_load_lds_dwordx4 v[224:225], off
	v_lshl_add_u64 v[226:227], v[70:71], 0, s[90:91]
	s_mov_b32 m0, s19
	s_nop 0
	global_load_lds_dwordx4 v[226:227], off
	v_lshl_add_u64 v[224:225], v[74:75], 0, s[90:91]
	s_mov_b32 m0, s21
	s_nop 0
	global_load_lds_dwordx4 v[224:225], off
	v_lshl_add_u64 v[226:227], v[72:73], 0, s[90:91]
	s_mov_b32 m0, s20
	s_nop 0
	global_load_lds_dwordx4 v[226:227], off
	v_lshl_add_u64 v[224:225], v[76:77], 0, s[90:91]
	s_mov_b32 m0, s23
	s_nop 0
	global_load_lds_dwordx4 v[224:225], off
	v_lshl_add_u64 v[226:227], v[78:79], 0, s[90:91]
	s_mov_b32 m0, s22
	s_nop 0
	global_load_lds_dwordx4 v[226:227], off
	s_waitcnt lgkmcnt(0)
	v_mfma_f32_32x32x16_bf16 v[48:63], v[208:211], v[216:219], v[48:63]
	s_mov_b32 m0, s29
	v_mfma_f32_32x32x16_bf16 v[32:47], v[208:211], v[220:223], v[32:47]
	v_mfma_f32_32x32x16_bf16 v[16:31], v[212:215], v[216:219], v[16:31]
	v_mfma_f32_32x32x16_bf16 v[0:15], v[212:215], v[220:223], v[0:15]
	ds_read_b128 v[208:211], v152 offset:32768
	ds_read_b128 v[212:215], v152 offset:36864
	ds_read_b128 v[216:219], v153 offset:49152
	ds_read_b128 v[220:223], v153 offset:53248
	s_waitcnt lgkmcnt(0)
	v_mfma_f32_32x32x16_bf16 v[48:63], v[208:211], v[216:219], v[48:63]
	v_mfma_f32_32x32x16_bf16 v[32:47], v[208:211], v[220:223], v[32:47]
	v_mfma_f32_32x32x16_bf16 v[16:31], v[212:215], v[216:219], v[16:31]
	v_mfma_f32_32x32x16_bf16 v[0:15], v[212:215], v[220:223], v[0:15]
	ds_read_b128 v[208:211], v155 offset:32768
	ds_read_b128 v[212:215], v155 offset:36864
	ds_read_b128 v[216:219], v156 offset:49152
	ds_read_b128 v[220:223], v156 offset:53248
	s_waitcnt lgkmcnt(0)
	v_mfma_f32_32x32x16_bf16 v[48:63], v[208:211], v[216:219], v[48:63]
	v_mfma_f32_32x32x16_bf16 v[32:47], v[208:211], v[220:223], v[32:47]
	v_mfma_f32_32x32x16_bf16 v[16:31], v[212:215], v[216:219], v[16:31]
	v_mfma_f32_32x32x16_bf16 v[0:15], v[212:215], v[220:223], v[0:15]
	ds_read_b128 v[208:211], v157 offset:32768
	ds_read_b128 v[212:215], v157 offset:36864
	ds_read_b128 v[216:219], v158 offset:49152
	ds_read_b128 v[220:223], v158 offset:53248
	s_waitcnt lgkmcnt(0)
	v_mfma_f32_32x32x16_bf16 v[48:63], v[208:211], v[216:219], v[48:63]
	v_mfma_f32_32x32x16_bf16 v[32:47], v[208:211], v[220:223], v[32:47]
	v_mfma_f32_32x32x16_bf16 v[16:31], v[212:215], v[216:219], v[16:31]
	v_mfma_f32_32x32x16_bf16 v[0:15], v[212:215], v[220:223], v[0:15]
	s_waitcnt vmcnt(0)
	s_barrier
; #define WAIT_V0() asm volatile("s_waitcnt vmcnt(0)" ::: "memory")
; DI void gemm_core(char* smem, int nk, const char* Ab, const char* Bb, const unsigned (&aoff)[4], const unsigned (&boff)[4],
;                   f32x16 (&acc)[2][2]) {
;     ...
;   for (int kt = 0; kt < nk; ++kt) {
;     const int cur = kt & 1;
;     if (kt + 1 < nk) stage(cur ^ 1, kt + 1);
;     const char* sb = smem + cur * STAGE_B;
; #pragma unroll
;     for (int ks = 0; ks < 4; ++ks) {
;       bf16x8 af[2], bfr[2];
; #pragma unroll
;       for (int mb = 0; mb < 2; ++mb) af[mb] = *(const bf16x8*)(sb + a_base + mb * 4096 + xo[ks]);
; #pragma unroll
;       for (int nb = 0; nb < 2; ++nb) bfr[nb] = *(const bf16x8*)(sb + b_base + nb * 4096 + xo[ks]);
; #pragma unroll
;       for (int mb = 0; mb < 2; ++mb)
; #pragma unroll
;         for (int nb = 0; nb < 2; ++nb)
;           acc[mb][nb] = __builtin_amdgcn_mfma_f32_32x32x16_bf16(af[mb], bfr[nb], acc[mb][nb], 0, 0, 0);
;     }
;     WAIT_V0();
;     __syncthreads();
;   }
	ds_read_b128 v[208:211], v149
	ds_read_b128 v[212:215], v149 offset:4096
	ds_read_b128 v[216:219], v150 offset:16384
	ds_read_b128 v[220:223], v150 offset:20480
	v_lshl_add_u64 v[224:225], v[66:67], 0, s[40:41]
	global_load_lds_dwordx4 v[224:225], off
	v_lshl_add_u64 v[226:227], v[64:65], 0, s[40:41]
	s_mov_b32 m0, s28
	s_nop 0
	global_load_lds_dwordx4 v[226:227], off
	v_lshl_add_u64 v[224:225], v[68:69], 0, s[40:41]
	s_mov_b32 m0, s42
	s_nop 0
	global_load_lds_dwordx4 v[224:225], off
	v_lshl_add_u64 v[226:227], v[70:71], 0, s[40:41]
	s_mov_b32 m0, s0
	s_nop 0
	global_load_lds_dwordx4 v[226:227], off
	v_lshl_add_u64 v[224:225], v[74:75], 0, s[40:41]
	s_mov_b32 m0, s1
	s_nop 0
	global_load_lds_dwordx4 v[224:225], off
	v_lshl_add_u64 v[226:227], v[72:73], 0, s[40:41]
	s_mov_b32 m0, s10
	s_nop 0
	global_load_lds_dwordx4 v[226:227], off
	v_lshl_add_u64 v[224:225], v[76:77], 0, s[40:41]
	s_mov_b32 m0, s11
	s_nop 0
	global_load_lds_dwordx4 v[224:225], off
	v_lshl_add_u64 v[226:227], v[78:79], 0, s[40:41]
	s_mov_b32 m0, s15
	s_nop 0
	global_load_lds_dwordx4 v[226:227], off
	s_waitcnt lgkmcnt(0)
	v_mfma_f32_32x32x16_bf16 v[48:63], v[208:211], v[216:219], v[48:63]
	s_mov_b32 m0, s17
	v_mfma_f32_32x32x16_bf16 v[32:47], v[208:211], v[220:223], v[32:47]
	v_mfma_f32_32x32x16_bf16 v[16:31], v[212:215], v[216:219], v[16:31]
	v_mfma_f32_32x32x16_bf16 v[0:15], v[212:215], v[220:223], v[0:15]
	ds_read_b128 v[208:211], v152
	ds_read_b128 v[212:215], v152 offset:4096
	ds_read_b128 v[216:219], v153 offset:16384
	ds_read_b128 v[220:223], v153 offset:20480
	s_waitcnt lgkmcnt(0)
	v_mfma_f32_32x32x16_bf16 v[48:63], v[208:211], v[216:219], v[48:63]
	v_mfma_f32_32x32x16_bf16 v[32:47], v[208:211], v[220:223], v[32:47]
	v_mfma_f32_32x32x16_bf16 v[16:31], v[212:215], v[216:219], v[16:31]
	v_mfma_f32_32x32x16_bf16 v[0:15], v[212:215], v[220:223], v[0:15]
	ds_read_b128 v[208:211], v155
	ds_read_b128 v[212:215], v155 offset:4096
	ds_read_b128 v[216:219], v156 offset:16384
	ds_read_b128 v[220:223], v156 offset:20480
	s_waitcnt lgkmcnt(0)
	v_mfma_f32_32x32x16_bf16 v[48:63], v[208:211], v[216:219], v[48:63]
	v_mfma_f32_32x32x16_bf16 v[32:47], v[208:211], v[220:223], v[32:47]
	v_mfma_f32_32x32x16_bf16 v[16:31], v[212:215], v[216:219], v[16:31]
	v_mfma_f32_32x32x16_bf16 v[0:15], v[212:215], v[220:223], v[0:15]
	ds_read_b128 v[208:211], v157
	ds_read_b128 v[212:215], v157 offset:4096
	ds_read_b128 v[216:219], v158 offset:16384
	ds_read_b128 v[220:223], v158 offset:20480
	s_waitcnt lgkmcnt(0)
	v_mfma_f32_32x32x16_bf16 v[48:63], v[208:211], v[216:219], v[48:63]
	v_mfma_f32_32x32x16_bf16 v[32:47], v[208:211], v[220:223], v[32:47]
	v_mfma_f32_32x32x16_bf16 v[16:31], v[212:215], v[216:219], v[16:31]
	v_mfma_f32_32x32x16_bf16 v[0:15], v[212:215], v[220:223], v[0:15]
	s_waitcnt vmcnt(0)
	s_barrier
	ds_read_b128 v[208:211], v149 offset:32768
	ds_read_b128 v[212:215], v149 offset:36864
	ds_read_b128 v[216:219], v150 offset:49152
	ds_read_b128 v[220:223], v150 offset:53248
	v_lshl_add_u64 v[224:225], v[66:67], 0, s[30:31]
	global_load_lds_dwordx4 v[224:225], off
	v_lshl_add_u64 v[226:227], v[64:65], 0, s[30:31]
	s_mov_b32 m0, s16
	s_nop 0
	global_load_lds_dwordx4 v[226:227], off
	v_lshl_add_u64 v[224:225], v[68:69], 0, s[30:31]
	s_mov_b32 m0, s18
	s_nop 0
	global_load_lds_dwordx4 v[224:225], off
	v_lshl_add_u64 v[226:227], v[70:71], 0, s[30:31]
	s_mov_b32 m0, s19
	s_nop 0
	global_load_lds_dwordx4 v[226:227], off
	v_lshl_add_u64 v[224:225], v[74:75], 0, s[30:31]
	s_mov_b32 m0, s21
	s_nop 0
	global_load_lds_dwordx4 v[224:225], off
	v_lshl_add_u64 v[226:227], v[72:73], 0, s[30:31]
	s_mov_b32 m0, s20
	s_nop 0
	global_load_lds_dwordx4 v[226:227], off
	v_lshl_add_u64 v[224:225], v[76:77], 0, s[30:31]
	s_mov_b32 m0, s23
	s_nop 0
	global_load_lds_dwordx4 v[224:225], off
	v_lshl_add_u64 v[226:227], v[78:79], 0, s[30:31]
	s_mov_b32 m0, s22
	s_nop 0
	global_load_lds_dwordx4 v[226:227], off
	s_waitcnt lgkmcnt(0)
	v_mfma_f32_32x32x16_bf16 v[48:63], v[208:211], v[216:219], v[48:63]
	s_mov_b32 m0, s29
	v_mfma_f32_32x32x16_bf16 v[32:47], v[208:211], v[220:223], v[32:47]
	v_mfma_f32_32x32x16_bf16 v[16:31], v[212:215], v[216:219], v[16:31]
	v_mfma_f32_32x32x16_bf16 v[0:15], v[212:215], v[220:223], v[0:15]
	ds_read_b128 v[208:211], v152 offset:32768
	ds_read_b128 v[212:215], v152 offset:36864
	ds_read_b128 v[216:219], v153 offset:49152
	ds_read_b128 v[220:223], v153 offset:53248
	s_waitcnt lgkmcnt(0)
	v_mfma_f32_32x32x16_bf16 v[48:63], v[208:211], v[216:219], v[48:63]
	v_mfma_f32_32x32x16_bf16 v[32:47], v[208:211], v[220:223], v[32:47]
	v_mfma_f32_32x32x16_bf16 v[16:31], v[212:215], v[216:219], v[16:31]
	v_mfma_f32_32x32x16_bf16 v[0:15], v[212:215], v[220:223], v[0:15]
	ds_read_b128 v[208:211], v155 offset:32768
	ds_read_b128 v[212:215], v155 offset:36864
	ds_read_b128 v[216:219], v156 offset:49152
	ds_read_b128 v[220:223], v156 offset:53248
	s_waitcnt lgkmcnt(0)
	v_mfma_f32_32x32x16_bf16 v[48:63], v[208:211], v[216:219], v[48:63]
	v_mfma_f32_32x32x16_bf16 v[32:47], v[208:211], v[220:223], v[32:47]
	v_mfma_f32_32x32x16_bf16 v[16:31], v[212:215], v[216:219], v[16:31]
	v_mfma_f32_32x32x16_bf16 v[0:15], v[212:215], v[220:223], v[0:15]
	ds_read_b128 v[208:211], v157 offset:32768
	ds_read_b128 v[212:215], v157 offset:36864
	ds_read_b128 v[216:219], v158 offset:49152
	ds_read_b128 v[220:223], v158 offset:53248
	s_waitcnt lgkmcnt(0)
	v_mfma_f32_32x32x16_bf16 v[48:63], v[208:211], v[216:219], v[48:63]
	v_mfma_f32_32x32x16_bf16 v[32:47], v[208:211], v[220:223], v[32:47]
	v_mfma_f32_32x32x16_bf16 v[16:31], v[212:215], v[216:219], v[16:31]
	v_mfma_f32_32x32x16_bf16 v[0:15], v[212:215], v[220:223], v[0:15]
	s_waitcnt vmcnt(0)
	s_barrier
; #define WAIT_V0() asm volatile("s_waitcnt vmcnt(0)" ::: "memory")
; DI void gemm_core(char* smem, int nk, const char* Ab, const char* Bb, const unsigned (&aoff)[4], const unsigned (&boff)[4],
;                   f32x16 (&acc)[2][2]) {
;     ...
;   for (int kt = 0; kt < nk; ++kt) {
;     const int cur = kt & 1;
;     if (kt + 1 < nk) stage(cur ^ 1, kt + 1);
;     const char* sb = smem + cur * STAGE_B;
; #pragma unroll
;     for (int ks = 0; ks < 4; ++ks) {
;       bf16x8 af[2], bfr[2];
; #pragma unroll
;       for (int mb = 0; mb < 2; ++mb) af[mb] = *(const bf16x8*)(sb + a_base + mb * 4096 + xo[ks]);
; #pragma unroll
;       for (int nb = 0; nb < 2; ++nb) bfr[nb] = *(const bf16x8*)(sb + b_base + nb * 4096 + xo[ks]);
; #pragma unroll
;       for (int mb = 0; mb < 2; ++mb)
; #pragma unroll
;         for (int nb = 0; nb < 2; ++nb)
;           acc[mb][nb] = __builtin_amdgcn_mfma_f32_32x32x16_bf16(af[mb], bfr[nb], acc[mb][nb], 0, 0, 0);
;     }
;     WAIT_V0();
;     __syncthreads();
;   }
	ds_read_b128 v[208:211], v149
	ds_read_b128 v[212:215], v149 offset:4096
	ds_read_b128 v[216:219], v150 offset:16384
	ds_read_b128 v[220:223], v150 offset:20480
	v_lshl_add_u64 v[224:225], v[66:67], 0, s[88:89]
	global_load_lds_dwordx4 v[224:225], off
	v_lshl_add_u64 v[226:227], v[64:65], 0, s[88:89]
	s_mov_b32 m0, s28
	s_nop 0
	global_load_lds_dwordx4 v[226:227], off
	v_lshl_add_u64 v[224:225], v[68:69], 0, s[88:89]
	s_mov_b32 m0, s42
	s_nop 0
	global_load_lds_dwordx4 v[224:225], off
	v_lshl_add_u64 v[226:227], v[70:71], 0, s[88:89]
	s_mov_b32 m0, s0
	s_nop 0
	global_load_lds_dwordx4 v[226:227], off
	v_lshl_add_u64 v[224:225], v[74:75], 0, s[88:89]
	s_mov_b32 m0, s1
	s_nop 0
	global_load_lds_dwordx4 v[224:225], off
	v_lshl_add_u64 v[226:227], v[72:73], 0, s[88:89]
	s_mov_b32 m0, s10
	s_nop 0
	global_load_lds_dwordx4 v[226:227], off
	v_lshl_add_u64 v[224:225], v[76:77], 0, s[88:89]
	s_mov_b32 m0, s11
	s_nop 0
	global_load_lds_dwordx4 v[224:225], off
	v_lshl_add_u64 v[226:227], v[78:79], 0, s[88:89]
	s_mov_b32 m0, s15
	s_nop 0
	global_load_lds_dwordx4 v[226:227], off
	s_waitcnt lgkmcnt(0)
	v_mfma_f32_32x32x16_bf16 v[48:63], v[208:211], v[216:219], v[48:63]
	s_mov_b32 m0, s17
	v_mfma_f32_32x32x16_bf16 v[32:47], v[208:211], v[220:223], v[32:47]
	v_mfma_f32_32x32x16_bf16 v[16:31], v[212:215], v[216:219], v[16:31]
	v_mfma_f32_32x32x16_bf16 v[0:15], v[212:215], v[220:223], v[0:15]
	ds_read_b128 v[208:211], v152
	ds_read_b128 v[212:215], v152 offset:4096
	ds_read_b128 v[216:219], v153 offset:16384
	ds_read_b128 v[220:223], v153 offset:20480
	s_waitcnt lgkmcnt(0)
	v_mfma_f32_32x32x16_bf16 v[48:63], v[208:211], v[216:219], v[48:63]
	v_mfma_f32_32x32x16_bf16 v[32:47], v[208:211], v[220:223], v[32:47]
	v_mfma_f32_32x32x16_bf16 v[16:31], v[212:215], v[216:219], v[16:31]
	v_mfma_f32_32x32x16_bf16 v[0:15], v[212:215], v[220:223], v[0:15]
	ds_read_b128 v[208:211], v155
	ds_read_b128 v[212:215], v155 offset:4096
	ds_read_b128 v[216:219], v156 offset:16384
	ds_read_b128 v[220:223], v156 offset:20480
	s_waitcnt lgkmcnt(0)
	v_mfma_f32_32x32x16_bf16 v[48:63], v[208:211], v[216:219], v[48:63]
	v_mfma_f32_32x32x16_bf16 v[32:47], v[208:211], v[220:223], v[32:47]
	v_mfma_f32_32x32x16_bf16 v[16:31], v[212:215], v[216:219], v[16:31]
	v_mfma_f32_32x32x16_bf16 v[0:15], v[212:215], v[220:223], v[0:15]
	ds_read_b128 v[208:211], v157
	ds_read_b128 v[212:215], v157 offset:4096
	ds_read_b128 v[216:219], v158 offset:16384
	ds_read_b128 v[220:223], v158 offset:20480
	s_waitcnt lgkmcnt(0)
	v_mfma_f32_32x32x16_bf16 v[48:63], v[208:211], v[216:219], v[48:63]
	v_mfma_f32_32x32x16_bf16 v[32:47], v[208:211], v[220:223], v[32:47]
	v_mfma_f32_32x32x16_bf16 v[16:31], v[212:215], v[216:219], v[16:31]
	v_mfma_f32_32x32x16_bf16 v[0:15], v[212:215], v[220:223], v[0:15]
	s_waitcnt vmcnt(0)
	s_barrier
	ds_read_b128 v[208:211], v149 offset:32768
	ds_read_b128 v[212:215], v149 offset:36864
	ds_read_b128 v[216:219], v150 offset:49152
	ds_read_b128 v[220:223], v150 offset:53248
	v_lshl_add_u64 v[224:225], v[66:67], 0, s[44:45]
	global_load_lds_dwordx4 v[224:225], off
	v_lshl_add_u64 v[226:227], v[64:65], 0, s[44:45]
	s_mov_b32 m0, s16
	s_nop 0
	global_load_lds_dwordx4 v[226:227], off
	v_lshl_add_u64 v[224:225], v[68:69], 0, s[44:45]
	s_mov_b32 m0, s18
	s_nop 0
	global_load_lds_dwordx4 v[224:225], off
	v_lshl_add_u64 v[226:227], v[70:71], 0, s[44:45]
	s_mov_b32 m0, s19
	s_nop 0
	global_load_lds_dwordx4 v[226:227], off
	v_lshl_add_u64 v[224:225], v[74:75], 0, s[44:45]
	s_mov_b32 m0, s21
	s_nop 0
	global_load_lds_dwordx4 v[224:225], off
	v_lshl_add_u64 v[226:227], v[72:73], 0, s[44:45]
	s_mov_b32 m0, s20
	s_nop 0
	global_load_lds_dwordx4 v[226:227], off
	v_lshl_add_u64 v[224:225], v[76:77], 0, s[44:45]
	s_mov_b32 m0, s23
	s_nop 0
	global_load_lds_dwordx4 v[224:225], off
	v_lshl_add_u64 v[226:227], v[78:79], 0, s[44:45]
	s_mov_b32 m0, s22
	s_nop 0
	global_load_lds_dwordx4 v[226:227], off
	s_waitcnt lgkmcnt(0)
	v_mfma_f32_32x32x16_bf16 v[48:63], v[208:211], v[216:219], v[48:63]
	s_mov_b32 m0, s29
	v_readfirstlane_b32 s29, v168
	v_mfma_f32_32x32x16_bf16 v[32:47], v[208:211], v[220:223], v[32:47]
	v_mfma_f32_32x32x16_bf16 v[16:31], v[212:215], v[216:219], v[16:31]
	v_mfma_f32_32x32x16_bf16 v[0:15], v[212:215], v[220:223], v[0:15]
	ds_read_b128 v[208:211], v152 offset:32768
	ds_read_b128 v[212:215], v152 offset:36864
	ds_read_b128 v[216:219], v153 offset:49152
	ds_read_b128 v[220:223], v153 offset:53248
	s_waitcnt lgkmcnt(0)
	v_mfma_f32_32x32x16_bf16 v[48:63], v[208:211], v[216:219], v[48:63]
	v_mfma_f32_32x32x16_bf16 v[32:47], v[208:211], v[220:223], v[32:47]
	v_mfma_f32_32x32x16_bf16 v[16:31], v[212:215], v[216:219], v[16:31]
	v_mfma_f32_32x32x16_bf16 v[0:15], v[212:215], v[220:223], v[0:15]
	ds_read_b128 v[208:211], v155 offset:32768
	ds_read_b128 v[212:215], v155 offset:36864
	ds_read_b128 v[216:219], v156 offset:49152
	ds_read_b128 v[220:223], v156 offset:53248
	s_waitcnt lgkmcnt(0)
	v_mfma_f32_32x32x16_bf16 v[48:63], v[208:211], v[216:219], v[48:63]
	v_mfma_f32_32x32x16_bf16 v[32:47], v[208:211], v[220:223], v[32:47]
	v_mfma_f32_32x32x16_bf16 v[16:31], v[212:215], v[216:219], v[16:31]
	v_mfma_f32_32x32x16_bf16 v[0:15], v[212:215], v[220:223], v[0:15]
	ds_read_b128 v[208:211], v157 offset:32768
	ds_read_b128 v[212:215], v157 offset:36864
	ds_read_b128 v[216:219], v158 offset:49152
	ds_read_b128 v[220:223], v158 offset:53248
	s_waitcnt lgkmcnt(0)
	v_mfma_f32_32x32x16_bf16 v[48:63], v[208:211], v[216:219], v[48:63]
	v_mfma_f32_32x32x16_bf16 v[32:47], v[208:211], v[220:223], v[32:47]
	v_mfma_f32_32x32x16_bf16 v[16:31], v[212:215], v[216:219], v[16:31]
	v_mfma_f32_32x32x16_bf16 v[0:15], v[212:215], v[220:223], v[0:15]
	s_waitcnt vmcnt(0)
	s_barrier
; #define WAIT_V0() asm volatile("s_waitcnt vmcnt(0)" ::: "memory")
; DI void gemm_core(char* smem, int nk, const char* Ab, const char* Bb, const unsigned (&aoff)[4], const unsigned (&boff)[4],
;                   f32x16 (&acc)[2][2]) {
;     ...
;   for (int kt = 0; kt < nk; ++kt) {
;     const int cur = kt & 1;
;     if (kt + 1 < nk) stage(cur ^ 1, kt + 1);
;     const char* sb = smem + cur * STAGE_B;
; #pragma unroll
;     for (int ks = 0; ks < 4; ++ks) {
;       bf16x8 af[2], bfr[2];
; #pragma unroll
;       for (int mb = 0; mb < 2; ++mb) af[mb] = *(const bf16x8*)(sb + a_base + mb * 4096 + xo[ks]);
; #pragma unroll
;       for (int nb = 0; nb < 2; ++nb) bfr[nb] = *(const bf16x8*)(sb + b_base + nb * 4096 + xo[ks]);
; #pragma unroll
;       for (int mb = 0; mb < 2; ++mb)
; #pragma unroll
;         for (int nb = 0; nb < 2; ++nb)
;           acc[mb][nb] = __builtin_amdgcn_mfma_f32_32x32x16_bf16(af[mb], bfr[nb], acc[mb][nb], 0, 0, 0);
;     }
;     WAIT_V0();
;     __syncthreads();
;   }
	ds_read_b128 v[208:211], v149
	ds_read_b128 v[212:215], v149 offset:4096
	ds_read_b128 v[216:219], v150 offset:16384
	ds_read_b128 v[220:223], v150 offset:20480
	v_lshl_add_u64 v[224:225], v[66:67], 0, s[46:47]
	global_load_lds_dwordx4 v[224:225], off
	v_lshl_add_u64 v[226:227], v[64:65], 0, s[46:47]
	s_mov_b32 m0, s28
	v_readfirstlane_b32 s28, v162
	global_load_lds_dwordx4 v[226:227], off
	v_lshl_add_u64 v[224:225], v[68:69], 0, s[46:47]
	s_mov_b32 m0, s42
	s_nop 0
	global_load_lds_dwordx4 v[224:225], off
	v_lshl_add_u64 v[226:227], v[70:71], 0, s[46:47]
	s_mov_b32 m0, s0
	v_readfirstlane_b32 s42, v166
	global_load_lds_dwordx4 v[226:227], off
	v_lshl_add_u64 v[224:225], v[74:75], 0, s[46:47]
	s_mov_b32 m0, s1
	s_nop 0
	global_load_lds_dwordx4 v[224:225], off
	v_lshl_add_u64 v[226:227], v[72:73], 0, s[46:47]
	s_mov_b32 m0, s10
	s_nop 0
	global_load_lds_dwordx4 v[226:227], off
	v_lshl_add_u64 v[224:225], v[76:77], 0, s[46:47]
	s_mov_b32 m0, s11
	s_nop 0
	global_load_lds_dwordx4 v[224:225], off
	v_lshl_add_u64 v[226:227], v[78:79], 0, s[46:47]
	s_mov_b32 m0, s15
	s_nop 0
	global_load_lds_dwordx4 v[226:227], off
	s_waitcnt lgkmcnt(0)
	v_mfma_f32_32x32x16_bf16 v[48:63], v[208:211], v[216:219], v[48:63]
	s_mov_b32 m0, s17
	v_readfirstlane_b32 s17, v170
	v_mfma_f32_32x32x16_bf16 v[32:47], v[208:211], v[220:223], v[32:47]
	v_mfma_f32_32x32x16_bf16 v[16:31], v[212:215], v[216:219], v[16:31]
	v_mfma_f32_32x32x16_bf16 v[0:15], v[212:215], v[220:223], v[0:15]
	ds_read_b128 v[208:211], v152
	ds_read_b128 v[212:215], v152 offset:4096
	ds_read_b128 v[216:219], v153 offset:16384
	ds_read_b128 v[220:223], v153 offset:20480
	s_waitcnt lgkmcnt(0)
	v_mfma_f32_32x32x16_bf16 v[48:63], v[208:211], v[216:219], v[48:63]
	v_mfma_f32_32x32x16_bf16 v[32:47], v[208:211], v[220:223], v[32:47]
	v_mfma_f32_32x32x16_bf16 v[16:31], v[212:215], v[216:219], v[16:31]
	v_mfma_f32_32x32x16_bf16 v[0:15], v[212:215], v[220:223], v[0:15]
	ds_read_b128 v[208:211], v155
	ds_read_b128 v[212:215], v155 offset:4096
	ds_read_b128 v[216:219], v156 offset:16384
	ds_read_b128 v[220:223], v156 offset:20480
	s_waitcnt lgkmcnt(0)
	v_mfma_f32_32x32x16_bf16 v[48:63], v[208:211], v[216:219], v[48:63]
	v_mfma_f32_32x32x16_bf16 v[32:47], v[208:211], v[220:223], v[32:47]
	v_mfma_f32_32x32x16_bf16 v[16:31], v[212:215], v[216:219], v[16:31]
	v_mfma_f32_32x32x16_bf16 v[0:15], v[212:215], v[220:223], v[0:15]
	ds_read_b128 v[208:211], v157
	ds_read_b128 v[212:215], v157 offset:4096
	ds_read_b128 v[216:219], v158 offset:16384
	ds_read_b128 v[220:223], v158 offset:20480
	s_waitcnt lgkmcnt(0)
	v_mfma_f32_32x32x16_bf16 v[48:63], v[208:211], v[216:219], v[48:63]
	v_mfma_f32_32x32x16_bf16 v[32:47], v[208:211], v[220:223], v[32:47]
	v_mfma_f32_32x32x16_bf16 v[16:31], v[212:215], v[216:219], v[16:31]
	v_mfma_f32_32x32x16_bf16 v[0:15], v[212:215], v[220:223], v[0:15]
	s_waitcnt vmcnt(0)
	s_barrier
	ds_read_b128 v[208:211], v149 offset:32768
	ds_read_b128 v[212:215], v149 offset:36864
	ds_read_b128 v[216:219], v150 offset:49152
	ds_read_b128 v[220:223], v150 offset:53248
	v_lshl_add_u64 v[224:225], v[66:67], 0, s[48:49]
	global_load_lds_dwordx4 v[224:225], off
	v_lshl_add_u64 v[226:227], v[64:65], 0, s[48:49]
	s_mov_b32 m0, s16
	v_readfirstlane_b32 s16, v172
	global_load_lds_dwordx4 v[226:227], off
	v_lshl_add_u64 v[224:225], v[68:69], 0, s[48:49]
	s_mov_b32 m0, s18
	s_nop 0
	global_load_lds_dwordx4 v[224:225], off
	v_lshl_add_u64 v[226:227], v[70:71], 0, s[48:49]
	s_mov_b32 m0, s19
	v_readfirstlane_b32 s18, v174
	global_load_lds_dwordx4 v[226:227], off
	v_lshl_add_u64 v[224:225], v[74:75], 0, s[48:49]
	s_mov_b32 m0, s21
	s_nop 0
	global_load_lds_dwordx4 v[224:225], off
	v_lshl_add_u64 v[226:227], v[72:73], 0, s[48:49]
	s_mov_b32 m0, s20
	v_readfirstlane_b32 s19, v154
	global_load_lds_dwordx4 v[226:227], off
	v_lshl_add_u64 v[224:225], v[76:77], 0, s[48:49]
	s_mov_b32 m0, s23
	v_readfirstlane_b32 s20, v151
	global_load_lds_dwordx4 v[224:225], off
	v_lshl_add_u64 v[226:227], v[78:79], 0, s[48:49]
	s_mov_b32 m0, s22
	v_readfirstlane_b32 s21, v160
	global_load_lds_dwordx4 v[226:227], off
	s_waitcnt lgkmcnt(0)
	v_mfma_f32_32x32x16_bf16 v[48:63], v[208:211], v[216:219], v[48:63]
	s_mov_b32 m0, s16
	v_readfirstlane_b32 s22, v159
	v_readfirstlane_b32 s23, v164
	v_mfma_f32_32x32x16_bf16 v[32:47], v[208:211], v[220:223], v[32:47]
	v_mfma_f32_32x32x16_bf16 v[16:31], v[212:215], v[216:219], v[16:31]
	v_mfma_f32_32x32x16_bf16 v[0:15], v[212:215], v[220:223], v[0:15]
	ds_read_b128 v[208:211], v152 offset:32768
	ds_read_b128 v[212:215], v152 offset:36864
	ds_read_b128 v[216:219], v153 offset:49152
	ds_read_b128 v[220:223], v153 offset:53248
	s_waitcnt lgkmcnt(0)
	v_mfma_f32_32x32x16_bf16 v[48:63], v[208:211], v[216:219], v[48:63]
	v_mfma_f32_32x32x16_bf16 v[32:47], v[208:211], v[220:223], v[32:47]
	v_mfma_f32_32x32x16_bf16 v[16:31], v[212:215], v[216:219], v[16:31]
	v_mfma_f32_32x32x16_bf16 v[0:15], v[212:215], v[220:223], v[0:15]
	ds_read_b128 v[208:211], v155 offset:32768
	ds_read_b128 v[212:215], v155 offset:36864
	ds_read_b128 v[216:219], v156 offset:49152
	ds_read_b128 v[220:223], v156 offset:53248
	s_waitcnt lgkmcnt(0)
	v_mfma_f32_32x32x16_bf16 v[48:63], v[208:211], v[216:219], v[48:63]
	v_mfma_f32_32x32x16_bf16 v[32:47], v[208:211], v[220:223], v[32:47]
	v_mfma_f32_32x32x16_bf16 v[16:31], v[212:215], v[216:219], v[16:31]
	v_mfma_f32_32x32x16_bf16 v[0:15], v[212:215], v[220:223], v[0:15]
	ds_read_b128 v[208:211], v157 offset:32768
	ds_read_b128 v[212:215], v157 offset:36864
	ds_read_b128 v[216:219], v158 offset:49152
	ds_read_b128 v[220:223], v158 offset:53248
	s_waitcnt lgkmcnt(0)
	v_mfma_f32_32x32x16_bf16 v[48:63], v[208:211], v[216:219], v[48:63]
	v_mfma_f32_32x32x16_bf16 v[32:47], v[208:211], v[220:223], v[32:47]
	v_mfma_f32_32x32x16_bf16 v[16:31], v[212:215], v[216:219], v[16:31]
	v_mfma_f32_32x32x16_bf16 v[0:15], v[212:215], v[220:223], v[0:15]
	s_waitcnt vmcnt(0)
	s_barrier
; #define WAIT_V0() asm volatile("s_waitcnt vmcnt(0)" ::: "memory")
; DI void gemm_core(char* smem, int nk, const char* Ab, const char* Bb, const unsigned (&aoff)[4], const unsigned (&boff)[4],
;                   f32x16 (&acc)[2][2]) {
;     ...
;   auto stage = [&](int buf, int kt) __attribute__((always_inline)) {
;     const char* ak = Ab + kt * 128;
;     const char* bk = Bb + kt * 128;
;     char* sa = smem + buf * STAGE_B + w * 4096;
; #pragma unroll
;     for (int i = 0; i < 4; ++i) {
;       __builtin_amdgcn_global_load_lds((const unsigned*)(ak + aoff[i]), (unsigned*)(sa + i * 1024), 16, 0, 0);
;       __builtin_amdgcn_global_load_lds((const unsigned*)(bk + boff[i]), (unsigned*)(sa + 16384 + i * 1024), 16, 0, 0);
;     }
;   };
;   stage(0, 0);
;   WAIT_V0();
;   __syncthreads();
;   for (int kt = 0; kt < nk; ++kt) {
;     const int cur = kt & 1;
;     if (kt + 1 < nk) stage(cur ^ 1, kt + 1);
;     const char* sb = smem + cur * STAGE_B;
; #pragma unroll
;     for (int ks = 0; ks < 4; ++ks) {
;       bf16x8 af[2], bfr[2];
; #pragma unroll
;       for (int mb = 0; mb < 2; ++mb) af[mb] = *(const bf16x8*)(sb + a_base + mb * 4096 + xo[ks]);
; #pragma unroll
;       for (int nb = 0; nb < 2; ++nb) bfr[nb] = *(const bf16x8*)(sb + b_base + nb * 4096 + xo[ks]);
; #pragma unroll
;       for (int mb = 0; mb < 2; ++mb)
; #pragma unroll
;         for (int nb = 0; nb < 2; ++nb)
;           acc[mb][nb] = __builtin_amdgcn_mfma_f32_32x32x16_bf16(af[mb], bfr[nb], acc[mb][nb], 0, 0, 0);
;     }
;     WAIT_V0();
;     __syncthreads();
;   }
	ds_read_b128 v[208:211], v149
	ds_read_b128 v[212:215], v149 offset:4096
	ds_read_b128 v[216:219], v150 offset:16384
	ds_read_b128 v[220:223], v150 offset:20480
	v_lshl_add_u64 v[224:225], v[66:67], 0, s[50:51]
	global_load_lds_dwordx4 v[224:225], off
	v_lshl_add_u64 v[226:227], v[64:65], 0, s[50:51]
	s_mov_b32 m0, s17
	s_nop 0
	global_load_lds_dwordx4 v[226:227], off
	v_lshl_add_u64 v[224:225], v[68:69], 0, s[50:51]
	s_mov_b32 m0, s18
	s_nop 0
	global_load_lds_dwordx4 v[224:225], off
	v_lshl_add_u64 v[226:227], v[70:71], 0, s[50:51]
	s_mov_b32 m0, s0
	s_nop 0
	global_load_lds_dwordx4 v[226:227], off
	v_lshl_add_u64 v[224:225], v[74:75], 0, s[50:51]
	s_mov_b32 m0, s1
	s_nop 0
	global_load_lds_dwordx4 v[224:225], off
	v_lshl_add_u64 v[226:227], v[72:73], 0, s[50:51]
	s_mov_b32 m0, s10
	s_nop 0
	global_load_lds_dwordx4 v[226:227], off
	v_lshl_add_u64 v[224:225], v[76:77], 0, s[50:51]
	s_mov_b32 m0, s11
	s_nop 0
	global_load_lds_dwordx4 v[224:225], off
	v_lshl_add_u64 v[226:227], v[78:79], 0, s[50:51]
	s_mov_b32 m0, s15
	s_nop 0
	global_load_lds_dwordx4 v[226:227], off
	s_waitcnt lgkmcnt(0)
	v_mfma_f32_32x32x16_bf16 v[48:63], v[208:211], v[216:219], v[48:63]
	s_mov_b32 m0, s19
	v_mfma_f32_32x32x16_bf16 v[32:47], v[208:211], v[220:223], v[32:47]
	v_mfma_f32_32x32x16_bf16 v[16:31], v[212:215], v[216:219], v[16:31]
	v_mfma_f32_32x32x16_bf16 v[0:15], v[212:215], v[220:223], v[0:15]
	ds_read_b128 v[208:211], v152
	ds_read_b128 v[212:215], v152 offset:4096
	ds_read_b128 v[216:219], v153 offset:16384
	ds_read_b128 v[220:223], v153 offset:20480
	s_waitcnt lgkmcnt(0)
	v_mfma_f32_32x32x16_bf16 v[48:63], v[208:211], v[216:219], v[48:63]
	v_mfma_f32_32x32x16_bf16 v[32:47], v[208:211], v[220:223], v[32:47]
	v_mfma_f32_32x32x16_bf16 v[16:31], v[212:215], v[216:219], v[16:31]
	v_mfma_f32_32x32x16_bf16 v[0:15], v[212:215], v[220:223], v[0:15]
	ds_read_b128 v[208:211], v155
	ds_read_b128 v[212:215], v155 offset:4096
	ds_read_b128 v[216:219], v156 offset:16384
	ds_read_b128 v[220:223], v156 offset:20480
	s_waitcnt lgkmcnt(0)
	v_mfma_f32_32x32x16_bf16 v[48:63], v[208:211], v[216:219], v[48:63]
	v_mfma_f32_32x32x16_bf16 v[32:47], v[208:211], v[220:223], v[32:47]
	v_mfma_f32_32x32x16_bf16 v[16:31], v[212:215], v[216:219], v[16:31]
	v_mfma_f32_32x32x16_bf16 v[0:15], v[212:215], v[220:223], v[0:15]
	ds_read_b128 v[208:211], v157
	ds_read_b128 v[212:215], v157 offset:4096
	ds_read_b128 v[216:219], v158 offset:16384
	ds_read_b128 v[220:223], v158 offset:20480
	s_waitcnt lgkmcnt(0)
	v_mfma_f32_32x32x16_bf16 v[48:63], v[208:211], v[216:219], v[48:63]
	v_mfma_f32_32x32x16_bf16 v[32:47], v[208:211], v[220:223], v[32:47]
	v_mfma_f32_32x32x16_bf16 v[16:31], v[212:215], v[216:219], v[16:31]
	v_mfma_f32_32x32x16_bf16 v[0:15], v[212:215], v[220:223], v[0:15]
	s_waitcnt vmcnt(0)
	s_barrier
	ds_read_b128 v[208:211], v149 offset:32768
	ds_read_b128 v[212:215], v149 offset:36864
	ds_read_b128 v[216:219], v150 offset:49152
	ds_read_b128 v[220:223], v150 offset:53248
	v_lshl_add_u64 v[224:225], v[66:67], 0, s[52:53]
	global_load_lds_dwordx4 v[224:225], off
	v_lshl_add_u64 v[226:227], v[64:65], 0, s[52:53]
	s_mov_b32 m0, s20
	s_nop 0
	global_load_lds_dwordx4 v[226:227], off
	v_lshl_add_u64 v[224:225], v[68:69], 0, s[52:53]
	s_mov_b32 m0, s21
	s_nop 0
	global_load_lds_dwordx4 v[224:225], off
	v_lshl_add_u64 v[226:227], v[70:71], 0, s[52:53]
	s_mov_b32 m0, s22
	s_nop 0
	global_load_lds_dwordx4 v[226:227], off
	v_lshl_add_u64 v[224:225], v[74:75], 0, s[52:53]
	s_mov_b32 m0, s23
	s_nop 0
	global_load_lds_dwordx4 v[224:225], off
	v_lshl_add_u64 v[226:227], v[72:73], 0, s[52:53]
	s_mov_b32 m0, s28
	s_nop 0
	global_load_lds_dwordx4 v[226:227], off
	v_lshl_add_u64 v[224:225], v[76:77], 0, s[52:53]
	s_mov_b32 m0, s42
	s_nop 0
	global_load_lds_dwordx4 v[224:225], off
	v_lshl_add_u64 v[226:227], v[78:79], 0, s[52:53]
	s_mov_b32 m0, s29
	s_nop 0
	global_load_lds_dwordx4 v[226:227], off
	s_waitcnt lgkmcnt(0)
	v_mfma_f32_32x32x16_bf16 v[48:63], v[208:211], v[216:219], v[48:63]
	s_mov_b32 m0, s16
	v_mfma_f32_32x32x16_bf16 v[32:47], v[208:211], v[220:223], v[32:47]
	v_mfma_f32_32x32x16_bf16 v[16:31], v[212:215], v[216:219], v[16:31]
	v_mfma_f32_32x32x16_bf16 v[0:15], v[212:215], v[220:223], v[0:15]
	ds_read_b128 v[208:211], v152 offset:32768
	ds_read_b128 v[212:215], v152 offset:36864
	ds_read_b128 v[216:219], v153 offset:49152
	ds_read_b128 v[220:223], v153 offset:53248
	s_waitcnt lgkmcnt(0)
	v_mfma_f32_32x32x16_bf16 v[48:63], v[208:211], v[216:219], v[48:63]
	v_mfma_f32_32x32x16_bf16 v[32:47], v[208:211], v[220:223], v[32:47]
	v_mfma_f32_32x32x16_bf16 v[16:31], v[212:215], v[216:219], v[16:31]
	v_mfma_f32_32x32x16_bf16 v[0:15], v[212:215], v[220:223], v[0:15]
	ds_read_b128 v[208:211], v155 offset:32768
	ds_read_b128 v[212:215], v155 offset:36864
	ds_read_b128 v[216:219], v156 offset:49152
	ds_read_b128 v[220:223], v156 offset:53248
	s_waitcnt lgkmcnt(0)
	v_mfma_f32_32x32x16_bf16 v[48:63], v[208:211], v[216:219], v[48:63]
	v_mfma_f32_32x32x16_bf16 v[32:47], v[208:211], v[220:223], v[32:47]
	v_mfma_f32_32x32x16_bf16 v[16:31], v[212:215], v[216:219], v[16:31]
	v_mfma_f32_32x32x16_bf16 v[0:15], v[212:215], v[220:223], v[0:15]
	ds_read_b128 v[208:211], v157 offset:32768
	ds_read_b128 v[212:215], v157 offset:36864
	ds_read_b128 v[216:219], v158 offset:49152
	ds_read_b128 v[220:223], v158 offset:53248
	s_waitcnt lgkmcnt(0)
	v_mfma_f32_32x32x16_bf16 v[48:63], v[208:211], v[216:219], v[48:63]
	v_mfma_f32_32x32x16_bf16 v[32:47], v[208:211], v[220:223], v[32:47]
	v_mfma_f32_32x32x16_bf16 v[16:31], v[212:215], v[216:219], v[16:31]
	v_mfma_f32_32x32x16_bf16 v[0:15], v[212:215], v[220:223], v[0:15]
	s_waitcnt vmcnt(0)
	s_barrier
; #define WAIT_V0() asm volatile("s_waitcnt vmcnt(0)" ::: "memory")
; DI void gemm_core(char* smem, int nk, const char* Ab, const char* Bb, const unsigned (&aoff)[4], const unsigned (&boff)[4],
;                   f32x16 (&acc)[2][2]) {
;     ...
;   auto stage = [&](int buf, int kt) __attribute__((always_inline)) {
;     const char* ak = Ab + kt * 128;
;     const char* bk = Bb + kt * 128;
;     char* sa = smem + buf * STAGE_B + w * 4096;
; #pragma unroll
;     for (int i = 0; i < 4; ++i) {
;       __builtin_amdgcn_global_load_lds((const unsigned*)(ak + aoff[i]), (unsigned*)(sa + i * 1024), 16, 0, 0);
;       __builtin_amdgcn_global_load_lds((const unsigned*)(bk + boff[i]), (unsigned*)(sa + 16384 + i * 1024), 16, 0, 0);
;     }
;   };
;   stage(0, 0);
;   WAIT_V0();
;   __syncthreads();
;   for (int kt = 0; kt < nk; ++kt) {
;     const int cur = kt & 1;
;     if (kt + 1 < nk) stage(cur ^ 1, kt + 1);
;     const char* sb = smem + cur * STAGE_B;
; #pragma unroll
;     for (int ks = 0; ks < 4; ++ks) {
;       bf16x8 af[2], bfr[2];
; #pragma unroll
;       for (int mb = 0; mb < 2; ++mb) af[mb] = *(const bf16x8*)(sb + a_base + mb * 4096 + xo[ks]);
; #pragma unroll
;       for (int nb = 0; nb < 2; ++nb) bfr[nb] = *(const bf16x8*)(sb + b_base + nb * 4096 + xo[ks]);
; #pragma unroll
;       for (int mb = 0; mb < 2; ++mb)
; #pragma unroll
;         for (int nb = 0; nb < 2; ++nb)
;           acc[mb][nb] = __builtin_amdgcn_mfma_f32_32x32x16_bf16(af[mb], bfr[nb], acc[mb][nb], 0, 0, 0);
;     }
;     WAIT_V0();
;     __syncthreads();
;   }
	ds_read_b128 v[208:211], v149
	ds_read_b128 v[212:215], v149 offset:4096
	ds_read_b128 v[216:219], v150 offset:16384
	ds_read_b128 v[220:223], v150 offset:20480
	v_lshl_add_u64 v[224:225], v[66:67], 0, s[54:55]
	global_load_lds_dwordx4 v[224:225], off
	v_lshl_add_u64 v[226:227], v[64:65], 0, s[54:55]
	s_mov_b32 m0, s17
	s_nop 0
	global_load_lds_dwordx4 v[226:227], off
	v_lshl_add_u64 v[224:225], v[68:69], 0, s[54:55]
	s_mov_b32 m0, s18
	s_nop 0
	global_load_lds_dwordx4 v[224:225], off
	v_lshl_add_u64 v[226:227], v[70:71], 0, s[54:55]
	s_mov_b32 m0, s0
	s_nop 0
	global_load_lds_dwordx4 v[226:227], off
	v_lshl_add_u64 v[224:225], v[74:75], 0, s[54:55]
	s_mov_b32 m0, s1
	s_nop 0
	global_load_lds_dwordx4 v[224:225], off
	v_lshl_add_u64 v[226:227], v[72:73], 0, s[54:55]
	s_mov_b32 m0, s10
	s_nop 0
	global_load_lds_dwordx4 v[226:227], off
	v_lshl_add_u64 v[224:225], v[76:77], 0, s[54:55]
	s_mov_b32 m0, s11
	s_nop 0
	global_load_lds_dwordx4 v[224:225], off
	v_lshl_add_u64 v[226:227], v[78:79], 0, s[54:55]
	s_mov_b32 m0, s15
	s_nop 0
	global_load_lds_dwordx4 v[226:227], off
	s_waitcnt lgkmcnt(0)
	v_mfma_f32_32x32x16_bf16 v[48:63], v[208:211], v[216:219], v[48:63]
	s_mov_b32 m0, s19
	v_mfma_f32_32x32x16_bf16 v[32:47], v[208:211], v[220:223], v[32:47]
	v_mfma_f32_32x32x16_bf16 v[16:31], v[212:215], v[216:219], v[16:31]
	v_mfma_f32_32x32x16_bf16 v[0:15], v[212:215], v[220:223], v[0:15]
	ds_read_b128 v[208:211], v152
	ds_read_b128 v[212:215], v152 offset:4096
	ds_read_b128 v[216:219], v153 offset:16384
	ds_read_b128 v[220:223], v153 offset:20480
	s_waitcnt lgkmcnt(0)
	v_mfma_f32_32x32x16_bf16 v[48:63], v[208:211], v[216:219], v[48:63]
	v_mfma_f32_32x32x16_bf16 v[32:47], v[208:211], v[220:223], v[32:47]
	v_mfma_f32_32x32x16_bf16 v[16:31], v[212:215], v[216:219], v[16:31]
	v_mfma_f32_32x32x16_bf16 v[0:15], v[212:215], v[220:223], v[0:15]
	ds_read_b128 v[208:211], v155
	ds_read_b128 v[212:215], v155 offset:4096
	ds_read_b128 v[216:219], v156 offset:16384
	ds_read_b128 v[220:223], v156 offset:20480
	s_waitcnt lgkmcnt(0)
	v_mfma_f32_32x32x16_bf16 v[48:63], v[208:211], v[216:219], v[48:63]
	v_mfma_f32_32x32x16_bf16 v[32:47], v[208:211], v[220:223], v[32:47]
	v_mfma_f32_32x32x16_bf16 v[16:31], v[212:215], v[216:219], v[16:31]
	v_mfma_f32_32x32x16_bf16 v[0:15], v[212:215], v[220:223], v[0:15]
	ds_read_b128 v[208:211], v157
	ds_read_b128 v[212:215], v157 offset:4096
	ds_read_b128 v[216:219], v158 offset:16384
	ds_read_b128 v[220:223], v158 offset:20480
	s_waitcnt lgkmcnt(0)
	v_mfma_f32_32x32x16_bf16 v[48:63], v[208:211], v[216:219], v[48:63]
	v_mfma_f32_32x32x16_bf16 v[32:47], v[208:211], v[220:223], v[32:47]
	v_mfma_f32_32x32x16_bf16 v[16:31], v[212:215], v[216:219], v[16:31]
	v_mfma_f32_32x32x16_bf16 v[0:15], v[212:215], v[220:223], v[0:15]
	s_waitcnt vmcnt(0)
	s_barrier
	ds_read_b128 v[208:211], v149 offset:32768
	ds_read_b128 v[212:215], v149 offset:36864
	ds_read_b128 v[216:219], v150 offset:49152
	ds_read_b128 v[220:223], v150 offset:53248
	v_lshl_add_u64 v[224:225], v[66:67], 0, s[56:57]
	global_load_lds_dwordx4 v[224:225], off
	v_lshl_add_u64 v[226:227], v[64:65], 0, s[56:57]
	s_mov_b32 m0, s20
	s_nop 0
	global_load_lds_dwordx4 v[226:227], off
	v_lshl_add_u64 v[224:225], v[68:69], 0, s[56:57]
	s_mov_b32 m0, s21
	s_nop 0
	global_load_lds_dwordx4 v[224:225], off
	v_lshl_add_u64 v[226:227], v[70:71], 0, s[56:57]
	s_mov_b32 m0, s22
	s_nop 0
	global_load_lds_dwordx4 v[226:227], off
	v_lshl_add_u64 v[224:225], v[74:75], 0, s[56:57]
	s_mov_b32 m0, s23
	s_nop 0
	global_load_lds_dwordx4 v[224:225], off
	v_lshl_add_u64 v[226:227], v[72:73], 0, s[56:57]
	s_mov_b32 m0, s28
	s_nop 0
	global_load_lds_dwordx4 v[226:227], off
	v_lshl_add_u64 v[224:225], v[76:77], 0, s[56:57]
	s_mov_b32 m0, s42
	s_nop 0
	global_load_lds_dwordx4 v[224:225], off
	v_lshl_add_u64 v[226:227], v[78:79], 0, s[56:57]
	s_mov_b32 m0, s29
	s_nop 0
	global_load_lds_dwordx4 v[226:227], off
	s_waitcnt lgkmcnt(0)
	v_mfma_f32_32x32x16_bf16 v[48:63], v[208:211], v[216:219], v[48:63]
	s_mov_b32 m0, s16
	v_mfma_f32_32x32x16_bf16 v[32:47], v[208:211], v[220:223], v[32:47]
	v_mfma_f32_32x32x16_bf16 v[16:31], v[212:215], v[216:219], v[16:31]
	v_mfma_f32_32x32x16_bf16 v[0:15], v[212:215], v[220:223], v[0:15]
	ds_read_b128 v[208:211], v152 offset:32768
	ds_read_b128 v[212:215], v152 offset:36864
	ds_read_b128 v[216:219], v153 offset:49152
	ds_read_b128 v[220:223], v153 offset:53248
	s_waitcnt lgkmcnt(0)
	v_mfma_f32_32x32x16_bf16 v[48:63], v[208:211], v[216:219], v[48:63]
	v_mfma_f32_32x32x16_bf16 v[32:47], v[208:211], v[220:223], v[32:47]
	v_mfma_f32_32x32x16_bf16 v[16:31], v[212:215], v[216:219], v[16:31]
	v_mfma_f32_32x32x16_bf16 v[0:15], v[212:215], v[220:223], v[0:15]
	ds_read_b128 v[208:211], v155 offset:32768
	ds_read_b128 v[212:215], v155 offset:36864
	ds_read_b128 v[216:219], v156 offset:49152
	ds_read_b128 v[220:223], v156 offset:53248
	s_waitcnt lgkmcnt(0)
	v_mfma_f32_32x32x16_bf16 v[48:63], v[208:211], v[216:219], v[48:63]
	v_mfma_f32_32x32x16_bf16 v[32:47], v[208:211], v[220:223], v[32:47]
	v_mfma_f32_32x32x16_bf16 v[16:31], v[212:215], v[216:219], v[16:31]
	v_mfma_f32_32x32x16_bf16 v[0:15], v[212:215], v[220:223], v[0:15]
	ds_read_b128 v[208:211], v157 offset:32768
	ds_read_b128 v[212:215], v157 offset:36864
	ds_read_b128 v[216:219], v158 offset:49152
	ds_read_b128 v[220:223], v158 offset:53248
	s_waitcnt lgkmcnt(0)
	v_mfma_f32_32x32x16_bf16 v[48:63], v[208:211], v[216:219], v[48:63]
	v_mfma_f32_32x32x16_bf16 v[32:47], v[208:211], v[220:223], v[32:47]
	v_mfma_f32_32x32x16_bf16 v[16:31], v[212:215], v[216:219], v[16:31]
	v_mfma_f32_32x32x16_bf16 v[0:15], v[212:215], v[220:223], v[0:15]
	s_waitcnt vmcnt(0)
	s_barrier
; #define WAIT_V0() asm volatile("s_waitcnt vmcnt(0)" ::: "memory")
; DI void gemm_core(char* smem, int nk, const char* Ab, const char* Bb, const unsigned (&aoff)[4], const unsigned (&boff)[4],
;                   f32x16 (&acc)[2][2]) {
;     ...
;   auto stage = [&](int buf, int kt) __attribute__((always_inline)) {
;     const char* ak = Ab + kt * 128;
;     const char* bk = Bb + kt * 128;
;     char* sa = smem + buf * STAGE_B + w * 4096;
; #pragma unroll
;     for (int i = 0; i < 4; ++i) {
;       __builtin_amdgcn_global_load_lds((const unsigned*)(ak + aoff[i]), (unsigned*)(sa + i * 1024), 16, 0, 0);
;       __builtin_amdgcn_global_load_lds((const unsigned*)(bk + boff[i]), (unsigned*)(sa + 16384 + i * 1024), 16, 0, 0);
;     }
;   };
;   stage(0, 0);
;   WAIT_V0();
;   __syncthreads();
;   for (int kt = 0; kt < nk; ++kt) {
;     const int cur = kt & 1;
;     if (kt + 1 < nk) stage(cur ^ 1, kt + 1);
;     const char* sb = smem + cur * STAGE_B;
; #pragma unroll
;     for (int ks = 0; ks < 4; ++ks) {
;       bf16x8 af[2], bfr[2];
; #pragma unroll
;       for (int mb = 0; mb < 2; ++mb) af[mb] = *(const bf16x8*)(sb + a_base + mb * 4096 + xo[ks]);
; #pragma unroll
;       for (int nb = 0; nb < 2; ++nb) bfr[nb] = *(const bf16x8*)(sb + b_base + nb * 4096 + xo[ks]);
; #pragma unroll
;       for (int mb = 0; mb < 2; ++mb)
; #pragma unroll
;         for (int nb = 0; nb < 2; ++nb)
;           acc[mb][nb] = __builtin_amdgcn_mfma_f32_32x32x16_bf16(af[mb], bfr[nb], acc[mb][nb], 0, 0, 0);
;     }
;     WAIT_V0();
;     __syncthreads();
;   }
	ds_read_b128 v[208:211], v149
	ds_read_b128 v[212:215], v149 offset:4096
	ds_read_b128 v[216:219], v150 offset:16384
	ds_read_b128 v[220:223], v150 offset:20480
	v_lshl_add_u64 v[224:225], v[66:67], 0, s[58:59]
	global_load_lds_dwordx4 v[224:225], off
	v_lshl_add_u64 v[226:227], v[64:65], 0, s[58:59]
	s_mov_b32 m0, s17
	s_nop 0
	global_load_lds_dwordx4 v[226:227], off
	v_lshl_add_u64 v[224:225], v[68:69], 0, s[58:59]
	s_mov_b32 m0, s18
	s_nop 0
	global_load_lds_dwordx4 v[224:225], off
	v_lshl_add_u64 v[226:227], v[70:71], 0, s[58:59]
	s_mov_b32 m0, s0
	s_nop 0
	global_load_lds_dwordx4 v[226:227], off
	v_lshl_add_u64 v[224:225], v[74:75], 0, s[58:59]
	s_mov_b32 m0, s1
	s_nop 0
	global_load_lds_dwordx4 v[224:225], off
	v_lshl_add_u64 v[226:227], v[72:73], 0, s[58:59]
	s_mov_b32 m0, s10
	s_nop 0
	global_load_lds_dwordx4 v[226:227], off
	v_lshl_add_u64 v[224:225], v[76:77], 0, s[58:59]
	s_mov_b32 m0, s11
	s_nop 0
	global_load_lds_dwordx4 v[224:225], off
	v_lshl_add_u64 v[226:227], v[78:79], 0, s[58:59]
	s_mov_b32 m0, s15
	s_nop 0
	global_load_lds_dwordx4 v[226:227], off
	s_waitcnt lgkmcnt(0)
	v_mfma_f32_32x32x16_bf16 v[48:63], v[208:211], v[216:219], v[48:63]
	s_mov_b32 m0, s19
	v_mfma_f32_32x32x16_bf16 v[32:47], v[208:211], v[220:223], v[32:47]
	v_mfma_f32_32x32x16_bf16 v[16:31], v[212:215], v[216:219], v[16:31]
	v_mfma_f32_32x32x16_bf16 v[0:15], v[212:215], v[220:223], v[0:15]
	ds_read_b128 v[208:211], v152
	ds_read_b128 v[212:215], v152 offset:4096
	ds_read_b128 v[216:219], v153 offset:16384
	ds_read_b128 v[220:223], v153 offset:20480
	s_waitcnt lgkmcnt(0)
	v_mfma_f32_32x32x16_bf16 v[48:63], v[208:211], v[216:219], v[48:63]
	v_mfma_f32_32x32x16_bf16 v[32:47], v[208:211], v[220:223], v[32:47]
	v_mfma_f32_32x32x16_bf16 v[16:31], v[212:215], v[216:219], v[16:31]
	v_mfma_f32_32x32x16_bf16 v[0:15], v[212:215], v[220:223], v[0:15]
	ds_read_b128 v[208:211], v155
	ds_read_b128 v[212:215], v155 offset:4096
	ds_read_b128 v[216:219], v156 offset:16384
	ds_read_b128 v[220:223], v156 offset:20480
	s_waitcnt lgkmcnt(0)
	v_mfma_f32_32x32x16_bf16 v[48:63], v[208:211], v[216:219], v[48:63]
	v_mfma_f32_32x32x16_bf16 v[32:47], v[208:211], v[220:223], v[32:47]
	v_mfma_f32_32x32x16_bf16 v[16:31], v[212:215], v[216:219], v[16:31]
	v_mfma_f32_32x32x16_bf16 v[0:15], v[212:215], v[220:223], v[0:15]
	ds_read_b128 v[208:211], v157
	ds_read_b128 v[212:215], v157 offset:4096
	ds_read_b128 v[216:219], v158 offset:16384
	ds_read_b128 v[220:223], v158 offset:20480
	s_waitcnt lgkmcnt(0)
	v_mfma_f32_32x32x16_bf16 v[48:63], v[208:211], v[216:219], v[48:63]
	v_mfma_f32_32x32x16_bf16 v[32:47], v[208:211], v[220:223], v[32:47]
	s_waitcnt vmcnt(0)
	s_barrier
	v_lshl_add_u64 v[208:209], v[66:67], 0, s[60:61]
	global_load_lds_dwordx4 v[208:209], off
	v_lshl_add_u64 v[208:209], v[64:65], 0, s[60:61]
	s_mov_b32 m0, s20
	v_lshl_add_u64 v[66:67], v[66:67], 0, s[62:63]
	global_load_lds_dwordx4 v[208:209], off
	v_lshl_add_u64 v[208:209], v[68:69], 0, s[60:61]
	s_mov_b32 m0, s21
	v_mfma_f32_32x32x16_bf16 v[16:31], v[212:215], v[216:219], v[16:31]
	global_load_lds_dwordx4 v[208:209], off
	v_lshl_add_u64 v[208:209], v[70:71], 0, s[60:61]
	s_mov_b32 m0, s22
	v_lshl_add_u64 v[64:65], v[64:65], 0, s[62:63]
	global_load_lds_dwordx4 v[208:209], off
	v_lshl_add_u64 v[208:209], v[74:75], 0, s[60:61]
	s_mov_b32 m0, s23
	v_mfma_f32_32x32x16_bf16 v[0:15], v[212:215], v[220:223], v[0:15]
	global_load_lds_dwordx4 v[208:209], off
	v_lshl_add_u64 v[208:209], v[72:73], 0, s[60:61]
	s_mov_b32 m0, s28
	s_movk_i32 s20, 0x3000
	global_load_lds_dwordx4 v[208:209], off
	v_lshl_add_u64 v[208:209], v[76:77], 0, s[60:61]
	s_mov_b32 m0, s42
	s_mov_b32 s21, 0x9000
	global_load_lds_dwordx4 v[208:209], off
	v_lshl_add_u64 v[208:209], v[78:79], 0, s[60:61]
	s_mov_b32 m0, s29
	s_mov_b32 s22, 0xa000
	global_load_lds_dwordx4 v[208:209], off
	ds_read_b128 v[208:211], v149 offset:32768
	ds_read_b128 v[212:215], v149 offset:36864
	ds_read_b128 v[216:219], v150 offset:49152
	ds_read_b128 v[220:223], v150 offset:53248
	s_waitcnt lgkmcnt(0)
	v_mfma_f32_32x32x16_bf16 v[48:63], v[208:211], v[216:219], v[48:63]
	s_mov_b32 m0, s16
	s_movk_i32 s16, 0x2000
	s_mov_b32 s23, 0xb000
	s_mov_b32 s28, 0x10000
	s_mov_b32 s29, 0x11000
	s_mov_b32 s42, 0x12000
	v_mfma_f32_32x32x16_bf16 v[32:47], v[208:211], v[220:223], v[32:47]
	v_mfma_f32_32x32x16_bf16 v[16:31], v[212:215], v[216:219], v[16:31]
	v_mfma_f32_32x32x16_bf16 v[0:15], v[212:215], v[220:223], v[0:15]
	ds_read_b128 v[208:211], v152 offset:32768
	ds_read_b128 v[212:215], v152 offset:36864
	ds_read_b128 v[216:219], v153 offset:49152
	ds_read_b128 v[220:223], v153 offset:53248
	s_waitcnt lgkmcnt(0)
	v_mfma_f32_32x32x16_bf16 v[48:63], v[208:211], v[216:219], v[48:63]
	v_mfma_f32_32x32x16_bf16 v[32:47], v[208:211], v[220:223], v[32:47]
	v_mfma_f32_32x32x16_bf16 v[16:31], v[212:215], v[216:219], v[16:31]
	v_mfma_f32_32x32x16_bf16 v[0:15], v[212:215], v[220:223], v[0:15]
	ds_read_b128 v[208:211], v155 offset:32768
	ds_read_b128 v[212:215], v155 offset:36864
	ds_read_b128 v[216:219], v156 offset:49152
	ds_read_b128 v[220:223], v156 offset:53248
	s_waitcnt lgkmcnt(0)
	v_mfma_f32_32x32x16_bf16 v[48:63], v[208:211], v[216:219], v[48:63]
	v_mfma_f32_32x32x16_bf16 v[32:47], v[208:211], v[220:223], v[32:47]
	v_mfma_f32_32x32x16_bf16 v[16:31], v[212:215], v[216:219], v[16:31]
	v_mfma_f32_32x32x16_bf16 v[0:15], v[212:215], v[220:223], v[0:15]
	ds_read_b128 v[208:211], v157 offset:32768
	ds_read_b128 v[212:215], v157 offset:36864
	ds_read_b128 v[216:219], v158 offset:49152
	ds_read_b128 v[220:223], v158 offset:53248
	s_waitcnt vmcnt(0)
	s_waitcnt vmcnt(0) lgkmcnt(0)
	s_barrier
; #define WAIT_V0() asm volatile("s_waitcnt vmcnt(0)" ::: "memory")
; DI void gemm_core(char* smem, int nk, const char* Ab, const char* Bb, const unsigned (&aoff)[4], const unsigned (&boff)[4],
;                   f32x16 (&acc)[2][2]) {
;     ...
;   auto stage = [&](int buf, int kt) __attribute__((always_inline)) {
;     const char* ak = Ab + kt * 128;
;     const char* bk = Bb + kt * 128;
;     char* sa = smem + buf * STAGE_B + w * 4096;
; #pragma unroll
;     for (int i = 0; i < 4; ++i) {
;       __builtin_amdgcn_global_load_lds((const unsigned*)(ak + aoff[i]), (unsigned*)(sa + i * 1024), 16, 0, 0);
;       __builtin_amdgcn_global_load_lds((const unsigned*)(bk + boff[i]), (unsigned*)(sa + 16384 + i * 1024), 16, 0, 0);
;     }
;   };
;   stage(0, 0);
;   WAIT_V0();
;   __syncthreads();
;   for (int kt = 0; kt < nk; ++kt) {
;     const int cur = kt & 1;
;     if (kt + 1 < nk) stage(cur ^ 1, kt + 1);
;     const char* sb = smem + cur * STAGE_B;
; #pragma unroll
;     for (int ks = 0; ks < 4; ++ks) {
;       bf16x8 af[2], bfr[2];
; #pragma unroll
;       for (int mb = 0; mb < 2; ++mb) af[mb] = *(const bf16x8*)(sb + a_base + mb * 4096 + xo[ks]);
; #pragma unroll
;       for (int nb = 0; nb < 2; ++nb) bfr[nb] = *(const bf16x8*)(sb + b_base + nb * 4096 + xo[ks]);
; #pragma unroll
;       for (int mb = 0; mb < 2; ++mb)
; #pragma unroll
;         for (int nb = 0; nb < 2; ++nb)
;           acc[mb][nb] = __builtin_amdgcn_mfma_f32_32x32x16_bf16(af[mb], bfr[nb], acc[mb][nb], 0, 0, 0);
;     }
;     WAIT_V0();
;     __syncthreads();
;   }
	global_load_lds_dwordx4 v[66:67], off
	s_mov_b32 m0, s17
	v_mfma_f32_32x32x16_bf16 v[48:63], v[208:211], v[216:219], v[48:63]
	global_load_lds_dwordx4 v[64:65], off
	v_lshl_add_u64 v[64:65], v[68:69], 0, s[62:63]
	s_mov_b32 m0, s18
	s_movk_i32 s17, 0x1000
	global_load_lds_dwordx4 v[64:65], off
	v_lshl_add_u64 v[64:65], v[70:71], 0, s[62:63]
	s_mov_b32 m0, s0
	v_mfma_f32_32x32x16_bf16 v[32:47], v[208:211], v[220:223], v[32:47]
	global_load_lds_dwordx4 v[64:65], off
	v_lshl_add_u64 v[64:65], v[74:75], 0, s[62:63]
	s_mov_b32 m0, s1
	s_mov_b32 s0, 0x13000
	global_load_lds_dwordx4 v[64:65], off
	v_lshl_add_u64 v[64:65], v[72:73], 0, s[62:63]
	s_mov_b32 m0, s10
	v_mfma_f32_32x32x16_bf16 v[16:31], v[212:215], v[216:219], v[16:31]
	global_load_lds_dwordx4 v[64:65], off
	v_lshl_add_u64 v[64:65], v[76:77], 0, s[62:63]
	s_mov_b32 m0, s11
	s_mov_b32 s1, 0x18000
	global_load_lds_dwordx4 v[64:65], off
	v_lshl_add_u64 v[64:65], v[78:79], 0, s[62:63]
	s_mov_b32 m0, s15
	v_mfma_f32_32x32x16_bf16 v[0:15], v[212:215], v[220:223], v[0:15]
	global_load_lds_dwordx4 v[64:65], off
	ds_read_b128 v[64:67], v149
	ds_read_b128 v[68:71], v149 offset:4096
	ds_read_b128 v[72:75], v150 offset:16384
	ds_read_b128 v[76:79], v150 offset:20480
	s_mov_b32 s10, 0x1b000
	v_readlane_b32 s18, v255, 3
	v_readlane_b32 s19, v255, 4
	s_waitcnt lgkmcnt(0)
	v_mfma_f32_32x32x16_bf16 v[48:63], v[64:67], v[72:75], v[48:63]
	v_mfma_f32_32x32x16_bf16 v[32:47], v[64:67], v[76:79], v[32:47]
	v_mfma_f32_32x32x16_bf16 v[16:31], v[68:71], v[72:75], v[16:31]
	v_mfma_f32_32x32x16_bf16 v[0:15], v[68:71], v[76:79], v[0:15]
	ds_read_b128 v[64:67], v152
	ds_read_b128 v[68:71], v152 offset:4096
	ds_read_b128 v[72:75], v153 offset:16384
	ds_read_b128 v[76:79], v153 offset:20480
	s_waitcnt lgkmcnt(0)
	v_mfma_f32_32x32x16_bf16 v[48:63], v[64:67], v[72:75], v[48:63]
	v_mfma_f32_32x32x16_bf16 v[32:47], v[64:67], v[76:79], v[32:47]
	v_mfma_f32_32x32x16_bf16 v[16:31], v[68:71], v[72:75], v[16:31]
	v_mfma_f32_32x32x16_bf16 v[0:15], v[68:71], v[76:79], v[0:15]
	ds_read_b128 v[64:67], v155
	ds_read_b128 v[68:71], v155 offset:4096
	ds_read_b128 v[72:75], v156 offset:16384
	ds_read_b128 v[76:79], v156 offset:20480
	s_waitcnt lgkmcnt(0)
	v_mfma_f32_32x32x16_bf16 v[48:63], v[64:67], v[72:75], v[48:63]
	v_mfma_f32_32x32x16_bf16 v[32:47], v[64:67], v[76:79], v[32:47]
	v_mfma_f32_32x32x16_bf16 v[16:31], v[68:71], v[72:75], v[16:31]
	v_mfma_f32_32x32x16_bf16 v[0:15], v[68:71], v[76:79], v[0:15]
	ds_read_b128 v[64:67], v157
	ds_read_b128 v[68:71], v157 offset:4096
	ds_read_b128 v[72:75], v158 offset:16384
	ds_read_b128 v[76:79], v158 offset:20480
	s_waitcnt lgkmcnt(0)
	v_mfma_f32_32x32x16_bf16 v[48:63], v[64:67], v[72:75], v[48:63]
	v_mfma_f32_32x32x16_bf16 v[32:47], v[64:67], v[76:79], v[32:47]
	v_mfma_f32_32x32x16_bf16 v[16:31], v[68:71], v[72:75], v[16:31]
	v_mfma_f32_32x32x16_bf16 v[0:15], v[68:71], v[76:79], v[0:15]
	s_waitcnt vmcnt(0)
	s_barrier
	ds_read_b128 v[64:67], v149 offset:32768
	ds_read_b128 v[68:71], v149 offset:36864
	ds_read_b128 v[72:75], v150 offset:49152
	ds_read_b128 v[76:79], v150 offset:53248
	s_waitcnt lgkmcnt(1)
	v_mfma_f32_32x32x16_bf16 v[48:63], v[64:67], v[72:75], v[48:63]
	s_waitcnt lgkmcnt(0)
	v_mfma_f32_32x32x16_bf16 v[32:47], v[64:67], v[76:79], v[32:47]
	v_mfma_f32_32x32x16_bf16 v[16:31], v[68:71], v[72:75], v[16:31]
	v_mfma_f32_32x32x16_bf16 v[0:15], v[68:71], v[76:79], v[0:15]
	ds_read_b128 v[64:67], v152 offset:32768
	ds_read_b128 v[68:71], v152 offset:36864
	ds_read_b128 v[72:75], v153 offset:49152
	ds_read_b128 v[76:79], v153 offset:53248
	s_waitcnt lgkmcnt(1)
	v_mfma_f32_32x32x16_bf16 v[48:63], v[64:67], v[72:75], v[48:63]
	s_waitcnt lgkmcnt(0)
	v_mfma_f32_32x32x16_bf16 v[32:47], v[64:67], v[76:79], v[32:47]
	v_mfma_f32_32x32x16_bf16 v[16:31], v[68:71], v[72:75], v[16:31]
	v_mfma_f32_32x32x16_bf16 v[0:15], v[68:71], v[76:79], v[0:15]
	ds_read_b128 v[64:67], v155 offset:32768
	ds_read_b128 v[68:71], v155 offset:36864
	ds_read_b128 v[72:75], v156 offset:49152
	ds_read_b128 v[76:79], v156 offset:53248
	s_waitcnt lgkmcnt(1)
	v_mfma_f32_32x32x16_bf16 v[48:63], v[64:67], v[72:75], v[48:63]
	s_waitcnt lgkmcnt(0)
	v_mfma_f32_32x32x16_bf16 v[32:47], v[64:67], v[76:79], v[32:47]
	v_mfma_f32_32x32x16_bf16 v[16:31], v[68:71], v[72:75], v[16:31]
	v_mfma_f32_32x32x16_bf16 v[0:15], v[68:71], v[76:79], v[0:15]
	ds_read_b128 v[64:67], v157 offset:32768
	ds_read_b128 v[68:71], v157 offset:36864
	ds_read_b128 v[72:75], v158 offset:49152
	ds_read_b128 v[76:79], v158 offset:53248
	s_waitcnt vmcnt(0)
	s_waitcnt lgkmcnt(0)
	s_barrier
; template <class T> DI T* uoff(T* base, unsigned byteoff) { return (T*)((char*)base + byteoff); }
; template <class T> DI const T* uoff(const T* base, unsigned byteoff) { return (const T*)((const char*)base + byteoff); }
; DI void phase_out(const Params& P, int layer, const float* xin, char* smem) {
;     ...
; #pragma unroll
;     for (int mb = 0; mb < 2; ++mb)
; #pragma unroll
;       for (int nb = 0; nb < 2; ++nb)
; #pragma unroll
;         for (int r = 0; r < 16; ++r)
;           (*uoff(P.out + ((mb * 32 + (r & 3) + 8 * (r >> 2)) * 1024 + nb * 32), obase_b)) = xr[mb][nb][r] + acc[mb][nb][r];
	v_mfma_f32_32x32x16_bf16 v[48:63], v[64:67], v[72:75], v[48:63]
	v_mfma_f32_32x32x16_bf16 v[32:47], v[64:67], v[76:79], v[32:47]
	v_lshl_add_u64 v[64:65], s[82:83], 0, v[136:137]
	s_nop 9
	v_add_f32_e32 v48, v147, v48
	global_store_dword v136, v48, s[82:83]
	v_add_co_u32_e32 v48, vcc, s17, v64
	v_add_f32_e32 v50, v145, v50
	v_add_f32_e32 v52, v144, v52
	v_mfma_f32_32x32x16_bf16 v[16:31], v[68:71], v[72:75], v[16:31]
	v_add_f32_e32 v54, v143, v54
	v_add_f32_e32 v56, v141, v56
	v_add_f32_e32 v32, v129, v32
	global_store_dword v136, v32, s[82:83] offset:128
	v_add_f32_e32 v32, v128, v33
	v_add_f32_e32 v58, v139, v58
	v_add_f32_e32 v60, v134, v60
	v_mfma_f32_32x32x16_bf16 v[0:15], v[68:71], v[76:79], v[0:15]
	v_add_f32_e32 v68, v148, v49
	v_addc_co_u32_e32 v49, vcc, 0, v65, vcc
	v_add_co_u32_e32 v66, vcc, s16, v64
	global_store_dword v[48:49], v32, off offset:128
	s_nop 0
	v_addc_co_u32_e32 v67, vcc, 0, v65, vcc
	global_store_dword v[66:67], v50, off
	v_add_co_u32_e32 v50, vcc, s20, v64
	global_store_dword v[66:67], v68, off offset:-4096
	v_add_f32_e32 v68, v146, v51
	v_addc_co_u32_e32 v51, vcc, 0, v65, vcc
	global_store_dword v[50:51], v68, off
	v_add_co_u32_e32 v68, vcc, s9, v64
	v_add_f32_e32 v32, v127, v34
	s_nop 0
	v_addc_co_u32_e32 v69, vcc, 0, v65, vcc
	v_add_co_u32_e32 v70, vcc, s21, v64
	global_store_dword v[66:67], v32, off offset:128
	s_nop 0
	v_addc_co_u32_e32 v71, vcc, 0, v65, vcc
	global_store_dword v[70:71], v52, off offset:-4096
	v_add_f32_e32 v52, v142, v53
	global_store_dword v[70:71], v52, off
	v_add_co_u32_e32 v52, vcc, s22, v64
	v_add_f32_e32 v32, v126, v35
	s_nop 0
	v_addc_co_u32_e32 v53, vcc, 0, v65, vcc
	v_add_co_u32_e32 v72, vcc, s23, v64
	global_store_dword v[50:51], v32, off offset:128
	s_nop 0
	v_addc_co_u32_e32 v73, vcc, 0, v65, vcc
	global_store_dword v[72:73], v54, off offset:-4096
	v_add_f32_e32 v54, v140, v55
	global_store_dword v[72:73], v54, off
	v_add_co_u32_e32 v54, vcc, s28, v64
	v_add_f32_e32 v32, v125, v36
	s_nop 0
	v_addc_co_u32_e32 v55, vcc, 0, v65, vcc
	v_add_co_u32_e32 v74, vcc, s29, v64
	global_store_dword v[68:69], v32, off offset:128
	s_nop 0
	v_addc_co_u32_e32 v75, vcc, 0, v65, vcc
	global_store_dword v[74:75], v56, off offset:-4096
	v_add_f32_e32 v56, v135, v57
	global_store_dword v[74:75], v56, off
	v_add_co_u32_e32 v56, vcc, s42, v64
	v_add_f32_e32 v32, v124, v37
	s_nop 0
	v_addc_co_u32_e32 v57, vcc, 0, v65, vcc
	v_add_co_u32_e32 v76, vcc, s0, v64
	global_store_dword v[70:71], v32, off offset:128
	s_nop 0
	v_addc_co_u32_e32 v77, vcc, 0, v65, vcc
	global_store_dword v[76:77], v58, off offset:-4096
	v_add_f32_e32 v58, v133, v59
	v_add_f32_e32 v32, v123, v38
	global_store_dword v[76:77], v58, off
	v_add_co_u32_e32 v58, vcc, s1, v64
	global_store_dword v[52:53], v32, off offset:128
	v_add_f32_e32 v32, v122, v39
	v_addc_co_u32_e32 v59, vcc, 0, v65, vcc
	global_store_dword v[72:73], v32, off offset:128
	v_add_f32_e32 v32, v121, v40
	v_add_co_u32_e32 v78, vcc, s2, v64
	global_store_dword v[54:55], v32, off offset:128
	v_add_f32_e32 v32, v120, v41
	v_addc_co_u32_e32 v79, vcc, 0, v65, vcc
	global_store_dword v[74:75], v32, off offset:128
	v_add_f32_e32 v32, v119, v42
	global_store_dword v[78:79], v60, off offset:-4096
	v_add_f32_e32 v60, v131, v61
	global_store_dword v[56:57], v32, off offset:128
	v_add_f32_e32 v32, v117, v43
	global_store_dword v[78:79], v60, off
	v_add_co_u32_e32 v60, vcc, s68, v64
	global_store_dword v[76:77], v32, off offset:128
	v_add_f32_e32 v32, v116, v44
	v_addc_co_u32_e32 v61, vcc, 0, v65, vcc
	global_store_dword v[58:59], v32, off offset:128
	v_add_f32_e32 v32, v115, v45
	v_add_f32_e32 v62, v132, v62
	v_add_co_u32_e32 v132, vcc, s10, v64
	global_store_dword v[78:79], v32, off offset:128
	v_add_f32_e32 v32, v114, v46
	v_addc_co_u32_e32 v133, vcc, 0, v65, vcc
	global_store_dword v[60:61], v32, off offset:128
	v_add_f32_e32 v32, v113, v47
	global_store_dword v[132:133], v32, off offset:128
	v_add_co_u32_e32 v32, vcc, s3, v64
	s_mov_b32 s0, 0x21000
	s_nop 0
; template <class T> DI T* uoff(T* base, unsigned byteoff) { return (T*)((char*)base + byteoff); }
; template <class T> DI const T* uoff(const T* base, unsigned byteoff) { return (const T*)((const char*)base + byteoff); }
; DI void phase_out(const Params& P, int layer, const float* xin, char* smem) {
;     ...
; #pragma unroll
;     for (int mb = 0; mb < 2; ++mb)
; #pragma unroll
;       for (int nb = 0; nb < 2; ++nb)
; #pragma unroll
;         for (int r = 0; r < 16; ++r)
;           (*uoff(P.out + ((mb * 32 + (r & 3) + 8 * (r >> 2)) * 1024 + nb * 32), obase_b)) = xr[mb][nb][r] + acc[mb][nb][r];
	v_addc_co_u32_e32 v33, vcc, 0, v65, vcc
	v_add_co_u32_e32 v34, vcc, s0, v64
	v_add_f32_e32 v16, v118, v16
	s_nop 0
	v_addc_co_u32_e32 v35, vcc, 0, v65, vcc
	global_store_dword v[34:35], v16, off offset:-4096
	v_add_f32_e32 v16, v111, v17
	global_store_dword v[34:35], v16, off
	v_add_co_u32_e32 v16, vcc, s6, v64
	s_mov_b32 s1, 0x23000
	s_nop 0
	v_addc_co_u32_e32 v17, vcc, 0, v65, vcc
	v_add_co_u32_e32 v36, vcc, s1, v64
	v_add_f32_e32 v18, v112, v18
	s_nop 0
	v_addc_co_u32_e32 v37, vcc, 0, v65, vcc
	s_mov_b32 s2, 0x28000
	global_store_dword v[36:37], v18, off offset:-4096
	v_add_f32_e32 v18, v109, v19
	global_store_dword v[36:37], v18, off
	v_add_co_u32_e32 v18, vcc, s2, v64
	v_add_f32_e32 v20, v110, v20
	s_nop 0
	v_addc_co_u32_e32 v19, vcc, 0, v65, vcc
	v_add_co_u32_e32 v38, vcc, s8, v64
	s_mov_b32 s3, 0x2a000
	s_nop 0
	v_addc_co_u32_e32 v39, vcc, 0, v65, vcc
	global_store_dword v[38:39], v20, off offset:-4096
	v_add_f32_e32 v20, v107, v21
	global_store_dword v[38:39], v20, off
	v_add_co_u32_e32 v20, vcc, s3, v64
	v_add_f32_e32 v22, v108, v22
	s_nop 0
	v_addc_co_u32_e32 v21, vcc, 0, v65, vcc
	v_add_co_u32_e32 v40, vcc, s64, v64
	s_mov_b32 s0, 0x30000
	s_nop 0
	v_addc_co_u32_e32 v41, vcc, 0, v65, vcc
	global_store_dword v[40:41], v22, off offset:-4096
	v_add_f32_e32 v22, v105, v23
	global_store_dword v[40:41], v22, off
	v_add_co_u32_e32 v22, vcc, s0, v64
	v_add_f32_e32 v24, v106, v24
	s_nop 0
	v_addc_co_u32_e32 v23, vcc, 0, v65, vcc
	v_add_co_u32_e32 v42, vcc, s65, v64
	s_mov_b32 s1, 0x32000
	s_nop 0
	v_addc_co_u32_e32 v43, vcc, 0, v65, vcc
	global_store_dword v[42:43], v24, off offset:-4096
	v_add_f32_e32 v24, v103, v25
	v_add_f32_e32 v0, v97, v0
	global_store_dword v[42:43], v24, off
	v_add_co_u32_e32 v24, vcc, s1, v64
	global_store_dword v[32:33], v0, off offset:128
	v_add_f32_e32 v0, v96, v1
	v_addc_co_u32_e32 v25, vcc, 0, v65, vcc
	global_store_dword v[34:35], v0, off offset:128
	v_add_f32_e32 v0, v95, v2
	v_add_co_u32_e32 v44, vcc, s66, v64
	global_store_dword v[16:17], v0, off offset:128
	v_add_f32_e32 v0, v94, v3
	v_add_f32_e32 v26, v104, v26
	v_addc_co_u32_e32 v45, vcc, 0, v65, vcc
	global_store_dword v[36:37], v0, off offset:128
	v_add_f32_e32 v0, v93, v4
	s_mov_b32 s2, 0x38000
	global_store_dword v[44:45], v26, off offset:-4096
	v_add_f32_e32 v26, v101, v27
	global_store_dword v[18:19], v0, off offset:128
	v_add_f32_e32 v0, v92, v5
	global_store_dword v[44:45], v26, off
	v_add_co_u32_e32 v26, vcc, s2, v64
	global_store_dword v[38:39], v0, off offset:128
	v_add_f32_e32 v0, v91, v6
	v_addc_co_u32_e32 v27, vcc, 0, v65, vcc
	global_store_dword v[20:21], v0, off offset:128
	v_add_f32_e32 v0, v90, v7
	v_add_co_u32_e32 v46, vcc, s67, v64
	global_store_dword v[40:41], v0, off offset:128
	v_add_f32_e32 v0, v89, v8
	v_add_f32_e32 v28, v102, v28
	v_addc_co_u32_e32 v47, vcc, 0, v65, vcc
	global_store_dword v[22:23], v0, off offset:128
	v_add_f32_e32 v0, v88, v9
	global_store_dword v[46:47], v28, off offset:-4096
	v_add_f32_e32 v28, v99, v29
	global_store_dword v[42:43], v0, off offset:128
	v_add_f32_e32 v0, v87, v10
	global_store_dword v[46:47], v28, off
	v_add_co_u32_e32 v28, vcc, s69, v64
	global_store_dword v[24:25], v0, off offset:128
	v_add_f32_e32 v0, v86, v11
	v_addc_co_u32_e32 v29, vcc, 0, v65, vcc
	global_store_dword v[44:45], v0, off offset:128
	v_add_f32_e32 v0, v85, v12
	v_add_co_u32_e32 v48, vcc, s71, v64
	global_store_dword v[26:27], v0, off offset:128
	v_add_f32_e32 v0, v84, v13
	v_add_f32_e32 v30, v100, v30
	v_addc_co_u32_e32 v49, vcc, 0, v65, vcc
	global_store_dword v[46:47], v0, off offset:128
	v_add_f32_e32 v0, v83, v14
	global_store_dword v[132:133], v62, off offset:-4096
	v_add_f32_e32 v62, v130, v63
	global_store_dword v[48:49], v30, off offset:-4096
	v_add_f32_e32 v30, v98, v31
	global_store_dword v[28:29], v0, off offset:128
	v_add_f32_e32 v0, v82, v15
	global_store_dword v[132:133], v62, off
	global_store_dword v[48:49], v30, off
	global_store_dword v[48:49], v0, off offset:128
	s_cbranch_scc0 .LBB0_43

; #define WAIT_V0() asm volatile("s_waitcnt vmcnt(0)" ::: "memory")
; DI void gemm_core(char* smem, int nk, const char* Ab, const char* Bb, const unsigned (&aoff)[4], const unsigned (&boff)[4],
;                   f32x16 (&acc)[2][2]) {
;     ...
;   for (int kt = 0; kt < nk; ++kt) {
;     const int cur = kt & 1;
;     if (kt + 1 < nk) stage(cur ^ 1, kt + 1);
;     const char* sb = smem + cur * STAGE_B;
; #pragma unroll
;     for (int ks = 0; ks < 4; ++ks) {
;       bf16x8 af[2], bfr[2];
; #pragma unroll
;       for (int mb = 0; mb < 2; ++mb) af[mb] = *(const bf16x8*)(sb + a_base + mb * 4096 + xo[ks]);
; #pragma unroll
;       for (int nb = 0; nb < 2; ++nb) bfr[nb] = *(const bf16x8*)(sb + b_base + nb * 4096 + xo[ks]);
; #pragma unroll
;       for (int mb = 0; mb < 2; ++mb)
; #pragma unroll
;         for (int nb = 0; nb < 2; ++nb)
;           acc[mb][nb] = __builtin_amdgcn_mfma_f32_32x32x16_bf16(af[mb], bfr[nb], acc[mb][nb], 0, 0, 0);
;     }
;     WAIT_V0();
;     __syncthreads();
;   }
; DI void phase_gemm_lat(const Params& P, int layer, char* smem) {
;     ...
;     gemm_tile(smem, isq ? 6 : 4, Z + (isq ? C_CQ : C_CKV), ZLD, m0, wl + (isq ? WO_UQ : WO_UKV), isq ? 384 : 256, n0, acc);
;     unsigned short* dst = isq ? QB : KV;
;     const int ldd = isq ? 768 : 1024;
.LBB0_414:
	s_and_b32 s22, s21, 0x8000
	s_xor_b32 s23, s22, 0x8000
	v_add_u32_e32 v87, s23, v86
	v_add_u32_e32 v90, 0x4000, v87
	v_readfirstlane_b32 s23, v87
	v_lshl_add_u64 v[88:89], v[64:65], 0, s[12:13]
	s_mov_b32 m0, s23
	v_readfirstlane_b32 s23, v90
	v_add_u32_e32 v90, 0x400, v87
	global_load_lds_dwordx4 v[88:89], off
	v_lshl_add_u64 v[88:89], v[72:73], 0, s[12:13]
	s_mov_b32 m0, s23
	v_readfirstlane_b32 s23, v90
	v_add_u32_e32 v90, 0x4400, v87
	global_load_lds_dwordx4 v[88:89], off
	v_lshl_add_u64 v[88:89], v[66:67], 0, s[12:13]
	s_mov_b32 m0, s23
	v_readfirstlane_b32 s23, v90
	v_add_u32_e32 v90, 0x800, v87
	global_load_lds_dwordx4 v[88:89], off
	v_lshl_add_u64 v[88:89], v[74:75], 0, s[12:13]
	s_mov_b32 m0, s23
	v_readfirstlane_b32 s23, v90
	v_add_u32_e32 v90, 0x4800, v87
	global_load_lds_dwordx4 v[88:89], off
	v_lshl_add_u64 v[88:89], v[68:69], 0, s[12:13]
	s_mov_b32 m0, s23
	v_readfirstlane_b32 s23, v90
	v_add_u32_e32 v90, 0xc00, v87
	global_load_lds_dwordx4 v[88:89], off
	v_lshl_add_u64 v[88:89], v[76:77], 0, s[12:13]
	s_mov_b32 m0, s23
	v_readfirstlane_b32 s23, v90
	v_add_u32_e32 v87, 0x4c00, v87
	global_load_lds_dwordx4 v[88:89], off
	v_lshl_add_u64 v[88:89], v[70:71], 0, s[12:13]
	s_mov_b32 m0, s23
	v_readfirstlane_b32 s23, v87
	global_load_lds_dwordx4 v[88:89], off
	v_lshl_add_u64 v[88:89], v[78:79], 0, s[12:13]
	s_mov_b32 m0, s23
	v_add_u32_e32 v87, s22, v84
	global_load_lds_dwordx4 v[88:89], off
	v_or_b32_e32 v104, s22, v85
	v_add_u32_e32 v92, v87, v83
	v_add_u32_e32 v100, v104, v83
	ds_read_b128 v[88:91], v92
	ds_read_b128 v[92:95], v92 offset:4096
	ds_read_b128 v[96:99], v100 offset:16384
	ds_read_b128 v[100:103], v100 offset:20480
	s_waitcnt lgkmcnt(0)
	v_mfma_f32_32x32x16_bf16 v[48:63], v[88:91], v[96:99], v[48:63]
	s_add_u32 s12, s12, 0x80
	s_addc_u32 s13, s13, 0
	s_add_i32 s21, s21, 0x8000
	s_cmp_lg_u32 s20, s12
	v_mfma_f32_32x32x16_bf16 v[32:47], v[88:91], v[100:103], v[32:47]
	v_mfma_f32_32x32x16_bf16 v[0:15], v[92:95], v[96:99], v[0:15]
	v_mfma_f32_32x32x16_bf16 v[16:31], v[92:95], v[100:103], v[16:31]
	v_add_u32_e32 v92, v87, v82
	v_add_u32_e32 v100, v104, v82
	ds_read_b128 v[88:91], v92
	ds_read_b128 v[92:95], v92 offset:4096
	ds_read_b128 v[96:99], v100 offset:16384
	ds_read_b128 v[100:103], v100 offset:20480
	s_waitcnt lgkmcnt(0)
	v_mfma_f32_32x32x16_bf16 v[48:63], v[88:91], v[96:99], v[48:63]
	v_mfma_f32_32x32x16_bf16 v[32:47], v[88:91], v[100:103], v[32:47]
	v_mfma_f32_32x32x16_bf16 v[0:15], v[92:95], v[96:99], v[0:15]
	v_mfma_f32_32x32x16_bf16 v[16:31], v[92:95], v[100:103], v[16:31]
	v_add_u32_e32 v92, v87, v81
	v_add_u32_e32 v100, v104, v81
	ds_read_b128 v[88:91], v92
	ds_read_b128 v[92:95], v92 offset:4096
	ds_read_b128 v[96:99], v100 offset:16384
	ds_read_b128 v[100:103], v100 offset:20480
	v_add_u32_e32 v87, v87, v80
	s_waitcnt lgkmcnt(0)
	v_mfma_f32_32x32x16_bf16 v[48:63], v[88:91], v[96:99], v[48:63]
	v_mfma_f32_32x32x16_bf16 v[32:47], v[88:91], v[100:103], v[32:47]
	v_mfma_f32_32x32x16_bf16 v[0:15], v[92:95], v[96:99], v[0:15]
	v_mfma_f32_32x32x16_bf16 v[16:31], v[92:95], v[100:103], v[16:31]
	ds_read_b128 v[88:91], v87
	ds_read_b128 v[92:95], v87 offset:4096
	v_add_u32_e32 v87, v104, v80
	ds_read_b128 v[96:99], v87 offset:16384
	ds_read_b128 v[100:103], v87 offset:20480
	s_waitcnt lgkmcnt(0)
	v_mfma_f32_32x32x16_bf16 v[48:63], v[88:91], v[96:99], v[48:63]
	v_mfma_f32_32x32x16_bf16 v[32:47], v[88:91], v[100:103], v[32:47]
	v_mfma_f32_32x32x16_bf16 v[0:15], v[92:95], v[96:99], v[0:15]
	v_mfma_f32_32x32x16_bf16 v[16:31], v[92:95], v[100:103], v[16:31]
	s_waitcnt vmcnt(0)
	s_barrier
	s_cbranch_scc1 .LBB0_414
	s_lshl_b32 s12, s19, 15
	s_add_i32 s12, s12, 0x8000
	s_and_b32 s12, s12, 0x8000
	v_add_u32_e32 v84, s12, v84
	v_or_b32_e32 v85, s12, v85
	v_add_u32_e32 v68, v84, v83
	v_add_u32_e32 v76, v85, v83
	ds_read_b128 v[64:67], v68
	ds_read_b128 v[68:71], v68 offset:4096
	ds_read_b128 v[72:75], v76 offset:16384
	ds_read_b128 v[76:79], v76 offset:20480
	s_waitcnt lgkmcnt(1)
	v_mfma_f32_32x32x16_bf16 v[48:63], v[64:67], v[72:75], v[48:63]
	s_and_b64 s[12:13], s[10:11], exec
	s_mov_b32 s12, 0x15000000
	s_cselect_b32 s12, s12, 0x3f00000
	s_add_u32 s19, s74, s12
	s_addc_u32 s20, s75, 0
	s_and_b64 s[10:11], s[10:11], exec
	s_movk_i32 s10, 0x300
	s_waitcnt lgkmcnt(0)
	v_mfma_f32_32x32x16_bf16 v[32:47], v[64:67], v[76:79], v[32:47]
	s_cselect_b32 s10, s10, 0x400
	v_mfma_f32_32x32x16_bf16 v[0:15], v[68:71], v[72:75], v[0:15]
	v_mfma_f32_32x32x16_bf16 v[16:31], v[68:71], v[76:79], v[16:31]
	v_add_u32_e32 v68, v84, v82
	v_add_u32_e32 v76, v85, v82
	ds_read_b128 v[64:67], v68
	ds_read_b128 v[68:71], v68 offset:4096
	ds_read_b128 v[72:75], v76 offset:16384
	ds_read_b128 v[76:79], v76 offset:20480
	s_waitcnt lgkmcnt(1)
	v_mfma_f32_32x32x16_bf16 v[48:63], v[64:67], v[72:75], v[48:63]
	s_waitcnt lgkmcnt(0)
	v_mfma_f32_32x32x16_bf16 v[32:47], v[64:67], v[76:79], v[32:47]
	v_mfma_f32_32x32x16_bf16 v[0:15], v[68:71], v[72:75], v[0:15]
	v_mfma_f32_32x32x16_bf16 v[16:31], v[68:71], v[76:79], v[16:31]
	v_add_u32_e32 v68, v84, v81
	v_add_u32_e32 v76, v85, v81
	ds_read_b128 v[64:67], v68
	ds_read_b128 v[68:71], v68 offset:4096
	ds_read_b128 v[72:75], v76 offset:16384
	ds_read_b128 v[76:79], v76 offset:20480
	s_waitcnt lgkmcnt(1)
	v_mfma_f32_32x32x16_bf16 v[48:63], v[64:67], v[72:75], v[48:63]
	s_waitcnt lgkmcnt(0)
	v_mfma_f32_32x32x16_bf16 v[32:47], v[64:67], v[76:79], v[32:47]
	v_mfma_f32_32x32x16_bf16 v[0:15], v[68:71], v[72:75], v[0:15]
	v_mfma_f32_32x32x16_bf16 v[16:31], v[68:71], v[76:79], v[16:31]
	v_add_u32_e32 v68, v84, v80
	v_add_u32_e32 v76, v85, v80
	ds_read_b128 v[64:67], v68
	ds_read_b128 v[68:71], v68 offset:4096
	ds_read_b128 v[72:75], v76 offset:16384
	ds_read_b128 v[76:79], v76 offset:20480
	s_waitcnt vmcnt(0)
	s_waitcnt lgkmcnt(0)
	s_barrier
; DI int ltid() { int t = threadIdx.x; asm volatile("" : "+v"(t)); return t; }
; template <class F>
; DI void epi_foreach(const f32x16 (&acc)[2][2], F f) {
;   const int lane = ltid() & 63, w = ltid() >> 6;
;   const int wm = w >> 1, wn = w & 1;
; #pragma unroll
;   for (int mb = 0; mb < 2; ++mb)
; #pragma unroll
;     for (int nb = 0; nb < 2; ++nb)
; #pragma unroll
;       for (int r = 0; r < 16; ++r) {
;         const int row = wm * 64 + mb * 32 + (r & 3) + 8 * (r >> 2) + 4 * (lane >> 5);
;         const int col = wn * 64 + nb * 32 + (lane & 31);
;         f(row, col, acc[mb][nb][r]);
;         if ((r & 7) == 7) __builtin_amdgcn_sched_barrier(0);
;       }
; DI void phase_gemm_lat(const Params& P, int layer, char* smem) {
;     ...
;     epi_foreach(acc, [&](int row, int col, float v) __attribute__((always_inline)) { Cs[row * 136 + col] = f2bf(v); });
	v_mfma_f32_32x32x16_bf16 v[48:63], v[64:67], v[72:75], v[48:63]
	v_mfma_f32_32x32x16_bf16 v[32:47], v[64:67], v[76:79], v[32:47]
	v_mov_b32_e32 v64, v161
	v_mov_b32_e32 v65, v161
	v_lshrrev_b32_e32 v67, 3, v64
	v_and_b32_e32 v67, 4, v67
	v_lshrrev_b32_e32 v66, 1, v65
	v_and_b32_e32 v64, 31, v64
	v_and_or_b32 v64, v65, 64, v64
	v_and_or_b32 v65, v66, s8, v67
	v_mul_lo_u32 v65, v65, s97
	s_nop 1
	v_cvt_pk_bf16_f32 v48, v48, s0
	v_lshl_add_u32 v64, v64, 1, v65
	ds_write_b16 v64, v48
	v_cvt_pk_bf16_f32 v48, v49, s0
	ds_write_b16 v64, v48 offset:272
	v_cvt_pk_bf16_f32 v48, v50, s0
	ds_write_b16 v64, v48 offset:544
	v_cvt_pk_bf16_f32 v48, v51, s0
	ds_write_b16 v64, v48 offset:816
	v_cvt_pk_bf16_f32 v48, v52, s0
	ds_write_b16 v64, v48 offset:2176
	v_cvt_pk_bf16_f32 v48, v53, s0
	ds_write_b16 v64, v48 offset:2448
	v_cvt_pk_bf16_f32 v48, v54, s0
	ds_write_b16 v64, v48 offset:2720
	v_cvt_pk_bf16_f32 v48, v55, s0
	v_mfma_f32_32x32x16_bf16 v[0:15], v[68:71], v[72:75], v[0:15]
	ds_write_b16 v64, v48 offset:2992
	v_mfma_f32_32x32x16_bf16 v[16:31], v[68:71], v[76:79], v[16:31]
	v_cvt_pk_bf16_f32 v48, v56, s0
	ds_write_b16 v64, v48 offset:4352
	v_cvt_pk_bf16_f32 v48, v57, s0
	ds_write_b16 v64, v48 offset:4624
	v_cvt_pk_bf16_f32 v48, v58, s0
	ds_write_b16 v64, v48 offset:4896
	v_cvt_pk_bf16_f32 v48, v59, s0
	ds_write_b16 v64, v48 offset:5168
	v_cvt_pk_bf16_f32 v48, v60, s0
	ds_write_b16 v64, v48 offset:6528
	v_cvt_pk_bf16_f32 v48, v61, s0
	ds_write_b16 v64, v48 offset:6800
	v_cvt_pk_bf16_f32 v48, v62, s0
	ds_write_b16 v64, v48 offset:7072
	v_cvt_pk_bf16_f32 v48, v63, s0
	ds_write_b16 v64, v48 offset:7344
	v_cvt_pk_bf16_f32 v32, v32, s0
	ds_write_b16 v64, v32 offset:64
	v_cvt_pk_bf16_f32 v32, v33, s0
	ds_write_b16 v64, v32 offset:336
	v_cvt_pk_bf16_f32 v32, v34, s0
	ds_write_b16 v64, v32 offset:608
	v_cvt_pk_bf16_f32 v32, v35, s0
	ds_write_b16 v64, v32 offset:880
	v_cvt_pk_bf16_f32 v32, v36, s0
	ds_write_b16 v64, v32 offset:2240
	v_cvt_pk_bf16_f32 v32, v37, s0
	ds_write_b16 v64, v32 offset:2512
	v_cvt_pk_bf16_f32 v32, v38, s0
	ds_write_b16 v64, v32 offset:2784
	v_cvt_pk_bf16_f32 v32, v39, s0
	ds_write_b16 v64, v32 offset:3056
	v_cvt_pk_bf16_f32 v32, v40, s0
	ds_write_b16 v64, v32 offset:4416
	v_cvt_pk_bf16_f32 v32, v41, s0
	ds_write_b16 v64, v32 offset:4688
	v_cvt_pk_bf16_f32 v32, v42, s0
	ds_write_b16 v64, v32 offset:4960
	v_cvt_pk_bf16_f32 v32, v43, s0
	ds_write_b16 v64, v32 offset:5232
	v_cvt_pk_bf16_f32 v32, v44, s0
	ds_write_b16 v64, v32 offset:6592
	v_cvt_pk_bf16_f32 v32, v45, s0
	ds_write_b16 v64, v32 offset:6864
	v_cvt_pk_bf16_f32 v32, v46, s0
	ds_write_b16 v64, v32 offset:7136
	v_cvt_pk_bf16_f32 v32, v47, s0
	ds_write_b16 v64, v32 offset:7408
	v_cvt_pk_bf16_f32 v0, v0, s0
	ds_write_b16 v64, v0 offset:8704
	v_cvt_pk_bf16_f32 v0, v1, s0
	ds_write_b16 v64, v0 offset:8976
	v_cvt_pk_bf16_f32 v0, v2, s0
	ds_write_b16 v64, v0 offset:9248
	v_cvt_pk_bf16_f32 v0, v3, s0
	ds_write_b16 v64, v0 offset:9520
	v_cvt_pk_bf16_f32 v0, v4, s0
	ds_write_b16 v64, v0 offset:10880
	v_cvt_pk_bf16_f32 v0, v5, s0
	ds_write_b16 v64, v0 offset:11152
	v_cvt_pk_bf16_f32 v0, v6, s0
	ds_write_b16 v64, v0 offset:11424
	v_cvt_pk_bf16_f32 v0, v7, s0
	ds_write_b16 v64, v0 offset:11696
	v_cvt_pk_bf16_f32 v0, v8, s0
	ds_write_b16 v64, v0 offset:13056
	v_cvt_pk_bf16_f32 v0, v9, s0
	ds_write_b16 v64, v0 offset:13328
	v_cvt_pk_bf16_f32 v0, v10, s0
	ds_write_b16 v64, v0 offset:13600
	v_cvt_pk_bf16_f32 v0, v11, s0
	ds_write_b16 v64, v0 offset:13872
	v_cvt_pk_bf16_f32 v0, v12, s0
	ds_write_b16 v64, v0 offset:15232
	v_cvt_pk_bf16_f32 v0, v13, s0
	ds_write_b16 v64, v0 offset:15504
	v_cvt_pk_bf16_f32 v0, v14, s0
	ds_write_b16 v64, v0 offset:15776
	v_cvt_pk_bf16_f32 v0, v15, s0
	ds_write_b16 v64, v0 offset:16048
	v_cvt_pk_bf16_f32 v0, v16, s0
	ds_write_b16 v64, v0 offset:8768
	v_cvt_pk_bf16_f32 v0, v17, s0
	ds_write_b16 v64, v0 offset:9040
	v_cvt_pk_bf16_f32 v0, v18, s0
	ds_write_b16 v64, v0 offset:9312
	v_cvt_pk_bf16_f32 v0, v19, s0
	ds_write_b16 v64, v0 offset:9584
	v_cvt_pk_bf16_f32 v0, v20, s0
	ds_write_b16 v64, v0 offset:10944
	v_cvt_pk_bf16_f32 v0, v21, s0
	ds_write_b16 v64, v0 offset:11216
	v_cvt_pk_bf16_f32 v0, v22, s0
	ds_write_b16 v64, v0 offset:11488
	v_cvt_pk_bf16_f32 v0, v23, s0
	ds_write_b16 v64, v0 offset:11760
	v_cvt_pk_bf16_f32 v0, v24, s0
	ds_write_b16 v64, v0 offset:13120
	v_cvt_pk_bf16_f32 v0, v25, s0
	ds_write_b16 v64, v0 offset:13392
	v_cvt_pk_bf16_f32 v0, v26, s0
	ds_write_b16 v64, v0 offset:13664
	v_cvt_pk_bf16_f32 v0, v27, s0
	ds_write_b16 v64, v0 offset:13936
	v_cvt_pk_bf16_f32 v0, v28, s0
	ds_write_b16 v64, v0 offset:15296
	v_cvt_pk_bf16_f32 v0, v29, s0
	ds_write_b16 v64, v0 offset:15568
	v_cvt_pk_bf16_f32 v0, v30, s0
	ds_write_b16 v64, v0 offset:15840
	v_cvt_pk_bf16_f32 v0, v31, s0
	ds_write_b16 v64, v0 offset:16112
	s_mul_hi_i32 s13, s10, s18
	s_mul_i32 s12, s10, s18
	s_lshl_b64 s[12:13], s[12:13], 1
	s_add_u32 s11, s19, s12
	s_addc_u32 s12, s20, s13
	s_lshl_b64 s[0:1], s[0:1], 1
	v_mov_b32_e32 v8, v161
	s_waitcnt lgkmcnt(0)
	s_barrier
; DI int ltid() { int t = threadIdx.x; asm volatile("" : "+v"(t)); return t; }
; DI void store_tile16(const unsigned short* Cs, unsigned short* dst, int ldd) {
;   const int tid = ltid();
; #pragma unroll
;   for (int i = 0; i < 8; ++i) {
;     const int idx = tid + 256 * i;
;     const int row = idx >> 4, c8 = (idx & 15) * 8;
;     *(u32x4*)(dst + (size_t)row * ldd + c8) = *(const u32x4*)(Cs + row * 136 + c8);
;   }
; }
; DI void phase_gemm_lat(const Params& P, int layer, char* smem) {
;     ...
;     store_tile16(Cs, dst + (size_t)m0 * ldd + n0, ldd);
;     __syncthreads();
	s_add_u32 s0, s11, s0
	s_addc_u32 s1, s12, s1
	v_lshlrev_b32_e32 v0, 4, v8
	v_and_b32_e32 v136, 0xf0, v0
	v_ashrrev_i32_e32 v6, 4, v8
	v_lshl_add_u64 v[4:5], s[0:1], 0, v[136:137]
	v_mad_u64_u32 v[0:1], s[0:1], v6, s97, v[136:137]
	ds_read_b128 v[0:3], v0
	v_mad_i64_i32 v[6:7], s[0:1], s10, v6, 0
	v_lshl_add_u64 v[6:7], v[6:7], 1, v[4:5]
	s_add_i32 s17, s17, s70
	s_waitcnt lgkmcnt(0)
	global_store_dwordx4 v[6:7], v[0:3], off
	s_cmpk_gt_i32 s17, 0xdff
	s_nop 0
	v_add_u32_e32 v0, 0x100, v8
	v_ashrrev_i32_e32 v6, 4, v0
	v_mad_u64_u32 v[0:1], s[0:1], v6, s97, v[136:137]
	ds_read_b128 v[0:3], v0
	v_mad_i64_i32 v[6:7], s[0:1], s10, v6, 0
	v_lshl_add_u64 v[6:7], v[6:7], 1, v[4:5]
	s_waitcnt lgkmcnt(0)
	global_store_dwordx4 v[6:7], v[0:3], off
	s_nop 1
	v_add_u32_e32 v0, 0x200, v8
	v_ashrrev_i32_e32 v6, 4, v0
	v_mad_u64_u32 v[0:1], s[0:1], v6, s97, v[136:137]
	ds_read_b128 v[0:3], v0
	v_mad_i64_i32 v[6:7], s[0:1], s10, v6, 0
	v_lshl_add_u64 v[6:7], v[6:7], 1, v[4:5]
	s_waitcnt lgkmcnt(0)
	global_store_dwordx4 v[6:7], v[0:3], off
	s_nop 1
	v_add_u32_e32 v0, 0x300, v8
	v_ashrrev_i32_e32 v6, 4, v0
	v_mad_u64_u32 v[0:1], s[0:1], v6, s97, v[136:137]
	ds_read_b128 v[0:3], v0
	v_mad_i64_i32 v[6:7], s[0:1], s10, v6, 0
	v_lshl_add_u64 v[6:7], v[6:7], 1, v[4:5]
	s_waitcnt lgkmcnt(0)
	global_store_dwordx4 v[6:7], v[0:3], off
	s_nop 1
	v_add_u32_e32 v0, 0x400, v8
	v_ashrrev_i32_e32 v6, 4, v0
	v_mad_u64_u32 v[0:1], s[0:1], v6, s97, v[136:137]
	ds_read_b128 v[0:3], v0
	v_mad_i64_i32 v[6:7], s[0:1], s10, v6, 0
	v_lshl_add_u64 v[6:7], v[6:7], 1, v[4:5]
	s_waitcnt lgkmcnt(0)
	global_store_dwordx4 v[6:7], v[0:3], off
	s_nop 1
	v_add_u32_e32 v0, 0x500, v8
	v_ashrrev_i32_e32 v6, 4, v0
	v_mad_u64_u32 v[0:1], s[0:1], v6, s97, v[136:137]
	ds_read_b128 v[0:3], v0
	v_mad_i64_i32 v[6:7], s[0:1], s10, v6, 0
	v_lshl_add_u64 v[6:7], v[6:7], 1, v[4:5]
	s_waitcnt lgkmcnt(0)
	global_store_dwordx4 v[6:7], v[0:3], off
	s_nop 1
	v_add_u32_e32 v0, 0x600, v8
	v_ashrrev_i32_e32 v6, 4, v0
	v_mad_u64_u32 v[0:1], s[0:1], v6, s97, v[136:137]
	ds_read_b128 v[0:3], v0
	v_mad_i64_i32 v[6:7], s[0:1], s10, v6, 0
	v_lshl_add_u64 v[6:7], v[6:7], 1, v[4:5]
	s_waitcnt lgkmcnt(0)
	global_store_dwordx4 v[6:7], v[0:3], off
	s_nop 1
	v_add_u32_e32 v0, 0x700, v8
	v_ashrrev_i32_e32 v6, 4, v0
	v_mad_u64_u32 v[0:1], s[0:1], v6, s97, v[136:137]
	ds_read_b128 v[0:3], v0
	v_mad_i64_i32 v[6:7], s[0:1], s10, v6, 0
	v_lshl_add_u64 v[4:5], v[6:7], 1, v[4:5]
	s_waitcnt lgkmcnt(0)
	global_store_dwordx4 v[4:5], v[0:3], off
	s_barrier
	s_cbranch_scc0 .LBB0_413
	v_readlane_b32 s18, v255, 3
	v_readlane_b32 s19, v255, 4

; #define WAIT_V0() asm volatile("s_waitcnt vmcnt(0)" ::: "memory")
; DI int glds_row(int i) { const int tid = ltid(); return ((tid >> 6) * 4 + i) * 8 + ((tid & 63) >> 3); }
; DI int glds_chunk(int row) { return (ltid() & 7) ^ ((row >> 1) & 7); }
; DI void gemm_core(char* smem, int nk, const char* Ab, const char* Bb, const unsigned (&aoff)[4], const unsigned (&boff)[4],
;                   f32x16 (&acc)[2][2]) {
;     ...
;   auto stage = [&](int buf, int kt) __attribute__((always_inline)) {
;     const char* ak = Ab + kt * 128;
;     const char* bk = Bb + kt * 128;
;     char* sa = smem + buf * STAGE_B + w * 4096;
; #pragma unroll
;     for (int i = 0; i < 4; ++i) {
;       __builtin_amdgcn_global_load_lds((const unsigned*)(ak + aoff[i]), (unsigned*)(sa + i * 1024), 16, 0, 0);
;       __builtin_amdgcn_global_load_lds((const unsigned*)(bk + boff[i]), (unsigned*)(sa + 16384 + i * 1024), 16, 0, 0);
;     }
;   };
;   stage(0, 0);
;   WAIT_V0();
;   __syncthreads();
; DI void gemm_tile(char* smem, int nk, const bf16* A, int lda, int m0, const bf16* Bt, int ldb, int n0, f32x16 (&acc)[2][2]) {
;   unsigned aoff[4], boff[4];
; #pragma unroll
;   for (int i = 0; i < 4; ++i) {
;     const int row = glds_row(i), ch = glds_chunk(row);
;     aoff[i] = (unsigned)((row * lda + ch * 8) * 2);
;     boff[i] = (unsigned)((row * ldb + ch * 8) * 2);
;   }
;   gemm_core(smem, nk, (const char*)(A + (size_t)m0 * lda), (const char*)(Bt + (size_t)n0 * ldb), aoff, boff, acc);
.LBB0_436:
	v_mov_b32_e32 v0, v161
	s_ashr_i32 s0, s14, 3
	v_lshrrev_b32_e32 v1, 1, v0
	v_lshrrev_b32_e32 v2, 3, v0
	v_bfe_u32 v0, v0, 3, 3
	v_and_or_b32 v0, v1, s9, v0
	v_mov_b32_e32 v1, v161
	v_bfe_u32 v2, v2, 1, 2
	v_xor_b32_e32 v1, v2, v1
	v_lshlrev_b32_e32 v0, 11, v0
	v_lshlrev_b32_e32 v1, 4, v1
	v_and_or_b32 v136, v1, s92, v0
	v_mov_b32_e32 v0, v161
	s_and_b32 s1, s0, 0xffffffc0
	v_ashrrev_i32_e32 v1, 1, v0
	v_and_b32_e32 v1, 0xffffffe0, v1
	v_bfe_u32 v0, v0, 3, 3
	v_or3_b32 v0, v0, v1, 8
	v_mov_b32_e32 v1, v161
	v_lshrrev_b32_e32 v2, 1, v0
	v_xor_b32_e32 v1, v2, v1
	v_lshlrev_b32_e32 v0, 11, v0
	v_lshlrev_b32_e32 v1, 4, v1
	v_and_or_b32 v0, v1, s92, v0
	v_mov_b32_e32 v1, v161
	s_lshl_b32 s10, s0, 1
	v_lshrrev_b32_e32 v2, 1, v1
	v_lshrrev_b32_e32 v3, 3, v1
	v_bfe_u32 v1, v1, 3, 3
	v_and_or_b32 v1, v2, s9, v1
	v_mov_b32_e32 v2, v161
	s_bfe_u32 s11, s0, 0x10005
	v_bfe_u32 v3, v3, 1, 2
	s_and_b32 s10, s10, 62
	s_or_b32 s1, s11, s1
	v_xor_b32_e32 v2, v3, v2
	s_or_b32 s1, s1, s10
	s_or_b32 s10, s0, 63
	v_lshlrev_b32_e32 v2, 4, v2
	s_cmpk_lt_i32 s10, 0x2c0
	v_lshlrev_b32_e32 v1, 11, v1
	v_and_b32_e32 v2, 0x70, v2
	s_cselect_b32 s1, s1, s0
	v_or3_b32 v2, v1, v2, s8
	v_mov_b32_e32 v1, v161
	s_mul_hi_i32 s10, s1, 0x2e8ba2e9
	s_lshr_b32 s11, s10, 31
	v_ashrrev_i32_e32 v3, 1, v1
	s_ashr_i32 s10, s10, 1
	v_and_b32_e32 v3, 0xffffffe0, v3
	v_bfe_u32 v1, v1, 3, 3
	s_and_b32 s0, s13, 0xc0
	s_add_i32 s10, s10, s11
	v_or3_b32 v1, v1, v3, 24
	v_mov_b32_e32 v3, v161
	s_add_i32 s15, s10, s0
	s_bfe_i32 s11, s14, 0x10002
	s_mul_i32 s10, s10, 11
	v_lshrrev_b32_e32 v4, 1, v1
	s_and_b32 s11, s11, 11
	s_sub_i32 s1, s1, s10
	v_xor_b32_e32 v3, v4, v3
	s_lshl_b32 s0, s15, 7
	s_add_i32 s1, s1, s11
	v_lshlrev_b32_e32 v1, 11, v1
	v_lshlrev_b32_e32 v3, 4, v3
	v_mov_b32_e32 v12, v161
	s_lshl_b32 s10, s1, 7
	v_and_or_b32 v4, v3, s92, v1
	s_ashr_i32 s1, s0, 31
	s_lshl_b64 s[16:17], s[0:1], 11
	v_and_b32_e32 v1, 31, v12
	v_lshrrev_b32_e32 v5, 1, v12
	v_and_or_b32 v1, v5, s6, v1
	s_add_u32 s16, s84, s16
	v_lshlrev_b32_e32 v112, 7, v1
	v_lshlrev_b32_e32 v1, 6, v12
	s_addc_u32 s17, s85, s17
	s_ashr_i32 s11, s10, 31
	v_and_b32_e32 v89, 0xfffff000, v1
	s_lshl_b64 s[18:19], s[10:11], 11
	v_add_u32_e32 v88, 0x4000, v89
	v_readfirstlane_b32 s20, v89
	s_add_u32 s18, s2, s18
	s_mov_b32 m0, s20
	v_readfirstlane_b32 s21, v88
	v_or_b32_e32 v90, 0x400, v89
	s_addc_u32 s19, s12, s19
	global_load_lds_dwordx4 v136, s[16:17]
	s_mov_b32 m0, s21
	v_readfirstlane_b32 s22, v90
	v_add_u32_e32 v91, 0x4400, v89
	global_load_lds_dwordx4 v136, s[18:19]
	s_mov_b32 m0, s22
	v_readfirstlane_b32 s23, v91
	v_or_b32_e32 v92, 0x800, v89
	global_load_lds_dwordx4 v0, s[16:17]
	s_mov_b32 m0, s23
	v_readfirstlane_b32 s28, v92
	v_add_u32_e32 v93, 0x4800, v89
	global_load_lds_dwordx4 v0, s[18:19]
	s_mov_b32 m0, s28
	v_readfirstlane_b32 s29, v93
	v_or_b32_e32 v94, 0xc00, v89
	global_load_lds_dwordx4 v2, s[16:17]
	s_mov_b32 m0, s29
	v_readfirstlane_b32 s40, v94
	v_add_u32_e32 v95, 0x4c00, v89
	v_lshrrev_b32_e32 v3, 5, v12
	v_bfe_u32 v99, v12, 1, 3
	global_load_lds_dwordx4 v2, s[18:19]
	s_mov_b32 m0, s40
	v_readfirstlane_b32 s41, v95
	v_add_u32_e32 v97, 0x8000, v89
	v_bitop3_b32 v3, v3, v99, 1 bitop3:0x6c
	v_lshl_add_u64 v[64:65], s[16:17], 0, v[136:137]
	v_mov_b32_e32 v1, v137
	global_load_lds_dwordx4 v4, s[16:17]
	s_mov_b32 m0, s41
	v_add_u32_e32 v96, 0xc000, v89
	v_readfirstlane_b32 s42, v97
	v_lshlrev_b32_e32 v6, 4, v3
	v_lshl_add_u64 v[66:67], s[18:19], 0, v[136:137]
	v_lshl_add_u64 v[68:69], s[16:17], 0, v[0:1]
	v_lshl_add_u64 v[70:71], s[18:19], 0, v[0:1]
	v_mov_b32_e32 v3, v137
	global_load_lds_dwordx4 v4, s[18:19]
	v_lshl_add_u64 v[0:1], v[64:65], 0, s[94:95]
	s_mov_b32 m0, s42
	v_readfirstlane_b32 s43, v96
	v_add_u32_e32 v98, 0x8400, v89
	v_lshl_add_u64 v[72:73], s[16:17], 0, v[2:3]
	v_lshl_add_u64 v[74:75], s[18:19], 0, v[2:3]
	global_load_lds_dwordx4 v[0:1], off
	v_lshl_add_u64 v[0:1], v[66:67], 0, s[94:95]
	s_mov_b32 m0, s43
	v_readfirstlane_b32 s44, v98
	v_add_u32_e32 v2, 0xc400, v89
	v_mov_b32_e32 v5, v137
	global_load_lds_dwordx4 v[0:1], off
	v_lshl_add_u64 v[0:1], v[68:69], 0, s[94:95]
	s_mov_b32 m0, s44
	v_readfirstlane_b32 s1, v2
	v_add_u32_e32 v2, 0x8800, v89
	v_lshl_add_u64 v[76:77], s[16:17], 0, v[4:5]
	global_load_lds_dwordx4 v[0:1], off
	v_lshl_add_u64 v[0:1], v[70:71], 0, s[94:95]
	s_mov_b32 m0, s1
	v_readfirstlane_b32 s16, v2
	v_add_u32_e32 v2, 0xc800, v89
	global_load_lds_dwordx4 v[0:1], off
	v_lshl_add_u64 v[0:1], v[72:73], 0, s[94:95]
	s_mov_b32 m0, s16
	v_readfirstlane_b32 s17, v2
	v_add_u32_e32 v2, 0x8c00, v89
	v_lshl_add_u64 v[78:79], s[18:19], 0, v[4:5]
	global_load_lds_dwordx4 v[0:1], off
	v_lshl_add_u64 v[0:1], v[74:75], 0, s[94:95]
	s_mov_b32 m0, s17
	v_readfirstlane_b32 s18, v2
	v_add_u32_e32 v2, 0xcc00, v89
	global_load_lds_dwordx4 v[0:1], off
	v_lshl_add_u64 v[0:1], v[76:77], 0, s[94:95]
	s_mov_b32 m0, s18
	v_readfirstlane_b32 s19, v2
	global_load_lds_dwordx4 v[0:1], off
	v_lshl_add_u64 v[0:1], v[78:79], 0, s[94:95]
	s_mov_b32 m0, s19
	v_or_b32_e32 v80, v112, v6
	global_load_lds_dwordx4 v[0:1], off
	s_waitcnt vmcnt(8)
	s_waitcnt vmcnt(8) lgkmcnt(0)
	s_barrier
; #define WAIT_V0() asm volatile("s_waitcnt vmcnt(0)" ::: "memory")
; DI void gemm_core(char* smem, int nk, const char* Ab, const char* Bb, const unsigned (&aoff)[4], const unsigned (&boff)[4],
;                   f32x16 (&acc)[2][2]) {
;     ...
;   for (int kt = 0; kt < nk; ++kt) {
;     const int cur = kt & 1;
;     if (kt + 1 < nk) stage(cur ^ 1, kt + 1);
;     const char* sb = smem + cur * STAGE_B;
; #pragma unroll
;     for (int ks = 0; ks < 4; ++ks) {
;       bf16x8 af[2], bfr[2];
; #pragma unroll
;       for (int mb = 0; mb < 2; ++mb) af[mb] = *(const bf16x8*)(sb + a_base + mb * 4096 + xo[ks]);
; #pragma unroll
;       for (int nb = 0; nb < 2; ++nb) bfr[nb] = *(const bf16x8*)(sb + b_base + nb * 4096 + xo[ks]);
; #pragma unroll
;       for (int mb = 0; mb < 2; ++mb)
; #pragma unroll
;         for (int nb = 0; nb < 2; ++nb)
;           acc[mb][nb] = __builtin_amdgcn_mfma_f32_32x32x16_bf16(af[mb], bfr[nb], acc[mb][nb], 0, 0, 0);
;     }
;     WAIT_V0();
;     __syncthreads();
;   }
	ds_read_b128 v[0:3], v80
	v_lshlrev_b32_e32 v4, 7, v12
	v_and_b32_e32 v113, 0x2f80, v4
	v_or_b32_e32 v82, v113, v6
	ds_read_b128 v[4:7], v82 offset:16384
	ds_read_b128 v[8:11], v82 offset:20480
	s_waitcnt lgkmcnt(0)
	v_mfma_f32_32x32x16_bf16 v[48:63], v[0:3], v[4:7], 0
	v_bfe_u32 v114, v12, 5, 1
	s_mov_b32 m0, s20
	v_mfma_f32_32x32x16_bf16 v[32:47], v[0:3], v[8:11], 0
	ds_read_b128 v[0:3], v80 offset:4096
	s_waitcnt lgkmcnt(0)
	v_mfma_f32_32x32x16_bf16 v[16:31], v[0:3], v[4:7], 0
	v_bitop3_b32 v4, v114, v99, 2 bitop3:0x36
	v_lshlrev_b32_e32 v83, 4, v4
	v_or_b32_e32 v81, v112, v83
	ds_read_b128 v[84:87], v81
	v_or_b32_e32 v83, v113, v83
	ds_read_b128 v[100:103], v83 offset:16384
	ds_read_b128 v[104:107], v83 offset:20480
	s_waitcnt lgkmcnt(0)
	v_mfma_f32_32x32x16_bf16 v[48:63], v[84:87], v[100:103], v[48:63]
	v_mfma_f32_32x32x16_bf16 v[32:47], v[84:87], v[104:107], v[32:47]
	ds_read_b128 v[84:87], v81 offset:4096
	v_mfma_f32_32x32x16_bf16 v[0:15], v[0:3], v[8:11], 0
	s_waitcnt lgkmcnt(0)
	v_mfma_f32_32x32x16_bf16 v[16:31], v[84:87], v[100:103], v[16:31]
	v_bitop3_b32 v100, v114, v99, 4 bitop3:0x36
	v_lshlrev_b32_e32 v108, 4, v100
	v_mfma_f32_32x32x16_bf16 v[0:15], v[84:87], v[104:107], v[0:15]
	v_or_b32_e32 v84, v112, v108
	ds_read_b128 v[100:103], v84
	v_or_b32_e32 v85, v113, v108
	ds_read_b128 v[104:107], v85 offset:16384
	ds_read_b128 v[108:111], v85 offset:20480
	v_bitop3_b32 v86, v114, v99, 6 bitop3:0x36
	v_lshlrev_b32_e32 v87, 4, v86
	s_waitcnt lgkmcnt(0)
	v_mfma_f32_32x32x16_bf16 v[48:63], v[100:103], v[104:107], v[48:63]
	v_or_b32_e32 v86, v112, v87
	v_or_b32_e32 v87, v113, v87
	v_mfma_f32_32x32x16_bf16 v[32:47], v[100:103], v[108:111], v[32:47]
	ds_read_b128 v[100:103], v84 offset:4096
	s_waitcnt lgkmcnt(0)
	v_mfma_f32_32x32x16_bf16 v[16:31], v[100:103], v[104:107], v[16:31]
	ds_read_b128 v[104:107], v87 offset:16384
	v_mfma_f32_32x32x16_bf16 v[0:15], v[100:103], v[108:111], v[0:15]
	ds_read_b128 v[100:103], v86
	ds_read_b128 v[108:111], v87 offset:20480
	s_waitcnt lgkmcnt(0)
	v_mfma_f32_32x32x16_bf16 v[48:63], v[100:103], v[104:107], v[48:63]
	v_mfma_f32_32x32x16_bf16 v[32:47], v[100:103], v[108:111], v[32:47]
	ds_read_b128 v[100:103], v86 offset:4096
	s_waitcnt lgkmcnt(0)
	v_mfma_f32_32x32x16_bf16 v[16:31], v[100:103], v[104:107], v[16:31]
	v_mfma_f32_32x32x16_bf16 v[0:15], v[100:103], v[108:111], v[0:15]
	s_waitcnt vmcnt(0)
	s_barrier
	ds_read_b128 v[100:103], v80 offset:32768
	ds_read_b128 v[104:107], v82 offset:49152
	ds_read_b128 v[108:111], v82 offset:53248
	v_lshl_add_u64 v[116:117], v[64:65], 0, s[36:37]
	global_load_lds_dwordx4 v[116:117], off
	v_lshl_add_u64 v[118:119], v[66:67], 0, s[36:37]
	s_mov_b32 m0, s21
	s_nop 0
	global_load_lds_dwordx4 v[118:119], off
	v_lshl_add_u64 v[116:117], v[68:69], 0, s[36:37]
	s_mov_b32 m0, s22
	s_nop 0
	global_load_lds_dwordx4 v[116:117], off
	v_lshl_add_u64 v[118:119], v[70:71], 0, s[36:37]
	s_mov_b32 m0, s23
	s_nop 0
	global_load_lds_dwordx4 v[118:119], off
	v_lshl_add_u64 v[116:117], v[72:73], 0, s[36:37]
	s_mov_b32 m0, s28
	s_nop 0
	global_load_lds_dwordx4 v[116:117], off
	v_lshl_add_u64 v[118:119], v[74:75], 0, s[36:37]
	s_mov_b32 m0, s29
	s_nop 0
	global_load_lds_dwordx4 v[118:119], off
	v_lshl_add_u64 v[116:117], v[76:77], 0, s[36:37]
	s_mov_b32 m0, s40
	s_nop 0
	global_load_lds_dwordx4 v[116:117], off
	v_lshl_add_u64 v[118:119], v[78:79], 0, s[36:37]
	s_mov_b32 m0, s41
	s_nop 0
	global_load_lds_dwordx4 v[118:119], off
	s_waitcnt lgkmcnt(0)
	v_mfma_f32_32x32x16_bf16 v[48:63], v[100:103], v[104:107], v[48:63]
	s_mov_b32 m0, s42
	v_mfma_f32_32x32x16_bf16 v[32:47], v[100:103], v[108:111], v[32:47]
	ds_read_b128 v[100:103], v80 offset:36864
	s_waitcnt lgkmcnt(0)
	v_mfma_f32_32x32x16_bf16 v[16:31], v[100:103], v[104:107], v[16:31]
	v_mfma_f32_32x32x16_bf16 v[0:15], v[100:103], v[108:111], v[0:15]
	ds_read_b128 v[100:103], v81 offset:32768
	ds_read_b128 v[104:107], v83 offset:49152
	ds_read_b128 v[108:111], v83 offset:53248
	s_waitcnt lgkmcnt(0)
	v_mfma_f32_32x32x16_bf16 v[48:63], v[100:103], v[104:107], v[48:63]
	v_mfma_f32_32x32x16_bf16 v[32:47], v[100:103], v[108:111], v[32:47]
	ds_read_b128 v[100:103], v81 offset:36864
	s_waitcnt lgkmcnt(0)
	v_mfma_f32_32x32x16_bf16 v[16:31], v[100:103], v[104:107], v[16:31]
	v_mfma_f32_32x32x16_bf16 v[0:15], v[100:103], v[108:111], v[0:15]
	ds_read_b128 v[100:103], v84 offset:32768
	ds_read_b128 v[104:107], v85 offset:49152
	ds_read_b128 v[108:111], v85 offset:53248
	s_waitcnt lgkmcnt(0)
	v_mfma_f32_32x32x16_bf16 v[48:63], v[100:103], v[104:107], v[48:63]
	v_mfma_f32_32x32x16_bf16 v[32:47], v[100:103], v[108:111], v[32:47]
	ds_read_b128 v[100:103], v84 offset:36864
	s_waitcnt lgkmcnt(0)
	v_mfma_f32_32x32x16_bf16 v[16:31], v[100:103], v[104:107], v[16:31]
	v_mfma_f32_32x32x16_bf16 v[0:15], v[100:103], v[108:111], v[0:15]
	ds_read_b128 v[100:103], v86 offset:32768
	ds_read_b128 v[104:107], v87 offset:49152
	ds_read_b128 v[108:111], v87 offset:53248
	s_waitcnt lgkmcnt(0)
	v_mfma_f32_32x32x16_bf16 v[48:63], v[100:103], v[104:107], v[48:63]
	v_mfma_f32_32x32x16_bf16 v[32:47], v[100:103], v[108:111], v[32:47]
	ds_read_b128 v[100:103], v86 offset:36864
	s_waitcnt lgkmcnt(0)
	v_mfma_f32_32x32x16_bf16 v[16:31], v[100:103], v[104:107], v[16:31]
	v_mfma_f32_32x32x16_bf16 v[0:15], v[100:103], v[108:111], v[0:15]
	s_waitcnt vmcnt(0)
	s_barrier
; #define WAIT_V0() asm volatile("s_waitcnt vmcnt(0)" ::: "memory")
; DI void gemm_core(char* smem, int nk, const char* Ab, const char* Bb, const unsigned (&aoff)[4], const unsigned (&boff)[4],
;                   f32x16 (&acc)[2][2]) {
;     ...
;   for (int kt = 0; kt < nk; ++kt) {
;     const int cur = kt & 1;
;     if (kt + 1 < nk) stage(cur ^ 1, kt + 1);
;     const char* sb = smem + cur * STAGE_B;
; #pragma unroll
;     for (int ks = 0; ks < 4; ++ks) {
;       bf16x8 af[2], bfr[2];
; #pragma unroll
;       for (int mb = 0; mb < 2; ++mb) af[mb] = *(const bf16x8*)(sb + a_base + mb * 4096 + xo[ks]);
; #pragma unroll
;       for (int nb = 0; nb < 2; ++nb) bfr[nb] = *(const bf16x8*)(sb + b_base + nb * 4096 + xo[ks]);
; #pragma unroll
;       for (int mb = 0; mb < 2; ++mb)
; #pragma unroll
;         for (int nb = 0; nb < 2; ++nb)
;           acc[mb][nb] = __builtin_amdgcn_mfma_f32_32x32x16_bf16(af[mb], bfr[nb], acc[mb][nb], 0, 0, 0);
;     }
;     WAIT_V0();
;     __syncthreads();
;   }
	ds_read_b128 v[100:103], v80
	ds_read_b128 v[104:107], v82 offset:16384
	ds_read_b128 v[108:111], v82 offset:20480
	v_lshl_add_u64 v[116:117], v[64:65], 0, s[38:39]
	global_load_lds_dwordx4 v[116:117], off
	v_lshl_add_u64 v[118:119], v[66:67], 0, s[38:39]
	s_mov_b32 m0, s43
	s_nop 0
	global_load_lds_dwordx4 v[118:119], off
	v_lshl_add_u64 v[116:117], v[68:69], 0, s[38:39]
	s_mov_b32 m0, s44
	s_nop 0
	global_load_lds_dwordx4 v[116:117], off
	v_lshl_add_u64 v[118:119], v[70:71], 0, s[38:39]
	s_mov_b32 m0, s1
	s_nop 0
	global_load_lds_dwordx4 v[118:119], off
	v_lshl_add_u64 v[116:117], v[72:73], 0, s[38:39]
	s_mov_b32 m0, s16
	s_nop 0
	global_load_lds_dwordx4 v[116:117], off
	v_lshl_add_u64 v[118:119], v[74:75], 0, s[38:39]
	s_mov_b32 m0, s17
	s_nop 0
	global_load_lds_dwordx4 v[118:119], off
	v_lshl_add_u64 v[116:117], v[76:77], 0, s[38:39]
	s_mov_b32 m0, s18
	s_nop 0
	global_load_lds_dwordx4 v[116:117], off
	v_lshl_add_u64 v[118:119], v[78:79], 0, s[38:39]
	s_mov_b32 m0, s19
	s_nop 0
	global_load_lds_dwordx4 v[118:119], off
	s_waitcnt lgkmcnt(0)
	v_mfma_f32_32x32x16_bf16 v[48:63], v[100:103], v[104:107], v[48:63]
	s_mov_b32 m0, s20
	v_mfma_f32_32x32x16_bf16 v[32:47], v[100:103], v[108:111], v[32:47]
	ds_read_b128 v[100:103], v80 offset:4096
	s_waitcnt lgkmcnt(0)
	v_mfma_f32_32x32x16_bf16 v[16:31], v[100:103], v[104:107], v[16:31]
	v_mfma_f32_32x32x16_bf16 v[0:15], v[100:103], v[108:111], v[0:15]
	ds_read_b128 v[100:103], v81
	ds_read_b128 v[104:107], v83 offset:16384
	ds_read_b128 v[108:111], v83 offset:20480
	s_waitcnt lgkmcnt(0)
	v_mfma_f32_32x32x16_bf16 v[48:63], v[100:103], v[104:107], v[48:63]
	v_mfma_f32_32x32x16_bf16 v[32:47], v[100:103], v[108:111], v[32:47]
	ds_read_b128 v[100:103], v81 offset:4096
	s_waitcnt lgkmcnt(0)
	v_mfma_f32_32x32x16_bf16 v[16:31], v[100:103], v[104:107], v[16:31]
	v_mfma_f32_32x32x16_bf16 v[0:15], v[100:103], v[108:111], v[0:15]
	ds_read_b128 v[100:103], v84
	ds_read_b128 v[104:107], v85 offset:16384
	ds_read_b128 v[108:111], v85 offset:20480
	s_waitcnt lgkmcnt(0)
	v_mfma_f32_32x32x16_bf16 v[48:63], v[100:103], v[104:107], v[48:63]
	v_mfma_f32_32x32x16_bf16 v[32:47], v[100:103], v[108:111], v[32:47]
	ds_read_b128 v[100:103], v84 offset:4096
	s_waitcnt lgkmcnt(0)
	v_mfma_f32_32x32x16_bf16 v[16:31], v[100:103], v[104:107], v[16:31]
	v_mfma_f32_32x32x16_bf16 v[0:15], v[100:103], v[108:111], v[0:15]
	ds_read_b128 v[100:103], v86
	ds_read_b128 v[104:107], v87 offset:16384
	ds_read_b128 v[108:111], v87 offset:20480
	s_waitcnt lgkmcnt(0)
	v_mfma_f32_32x32x16_bf16 v[48:63], v[100:103], v[104:107], v[48:63]
	v_mfma_f32_32x32x16_bf16 v[32:47], v[100:103], v[108:111], v[32:47]
	ds_read_b128 v[100:103], v86 offset:4096
	s_waitcnt lgkmcnt(0)
	v_mfma_f32_32x32x16_bf16 v[16:31], v[100:103], v[104:107], v[16:31]
	v_mfma_f32_32x32x16_bf16 v[0:15], v[100:103], v[108:111], v[0:15]
	s_waitcnt vmcnt(0)
	s_barrier
	ds_read_b128 v[100:103], v80 offset:32768
	ds_read_b128 v[104:107], v82 offset:49152
	ds_read_b128 v[108:111], v82 offset:53248
	v_lshl_add_u64 v[116:117], v[64:65], 0, s[30:31]
	global_load_lds_dwordx4 v[116:117], off
	v_lshl_add_u64 v[118:119], v[66:67], 0, s[30:31]
	s_mov_b32 m0, s21
	s_nop 0
	global_load_lds_dwordx4 v[118:119], off
	v_lshl_add_u64 v[116:117], v[68:69], 0, s[30:31]
	s_mov_b32 m0, s22
	s_nop 0
	global_load_lds_dwordx4 v[116:117], off
	v_lshl_add_u64 v[118:119], v[70:71], 0, s[30:31]
	s_mov_b32 m0, s23
	s_nop 0
	global_load_lds_dwordx4 v[118:119], off
	v_lshl_add_u64 v[116:117], v[72:73], 0, s[30:31]
	s_mov_b32 m0, s28
	s_nop 0
	global_load_lds_dwordx4 v[116:117], off
	v_lshl_add_u64 v[118:119], v[74:75], 0, s[30:31]
	s_mov_b32 m0, s29
	s_nop 0
	global_load_lds_dwordx4 v[118:119], off
	v_lshl_add_u64 v[116:117], v[76:77], 0, s[30:31]
	s_mov_b32 m0, s40
	s_nop 0
	global_load_lds_dwordx4 v[116:117], off
	v_lshl_add_u64 v[118:119], v[78:79], 0, s[30:31]
	s_mov_b32 m0, s41
	s_nop 0
	global_load_lds_dwordx4 v[118:119], off
	s_waitcnt lgkmcnt(0)
	v_mfma_f32_32x32x16_bf16 v[48:63], v[100:103], v[104:107], v[48:63]
	s_mov_b32 m0, s42
	v_mfma_f32_32x32x16_bf16 v[32:47], v[100:103], v[108:111], v[32:47]
	ds_read_b128 v[100:103], v80 offset:36864
	s_waitcnt lgkmcnt(0)
	v_mfma_f32_32x32x16_bf16 v[16:31], v[100:103], v[104:107], v[16:31]
	v_mfma_f32_32x32x16_bf16 v[0:15], v[100:103], v[108:111], v[0:15]
	ds_read_b128 v[100:103], v81 offset:32768
	ds_read_b128 v[104:107], v83 offset:49152
	ds_read_b128 v[108:111], v83 offset:53248
	s_waitcnt lgkmcnt(0)
	v_mfma_f32_32x32x16_bf16 v[48:63], v[100:103], v[104:107], v[48:63]
	v_mfma_f32_32x32x16_bf16 v[32:47], v[100:103], v[108:111], v[32:47]
	ds_read_b128 v[100:103], v81 offset:36864
	s_waitcnt lgkmcnt(0)
	v_mfma_f32_32x32x16_bf16 v[16:31], v[100:103], v[104:107], v[16:31]
	v_mfma_f32_32x32x16_bf16 v[0:15], v[100:103], v[108:111], v[0:15]
	ds_read_b128 v[100:103], v84 offset:32768
	ds_read_b128 v[104:107], v85 offset:49152
	ds_read_b128 v[108:111], v85 offset:53248
	s_waitcnt lgkmcnt(0)
	v_mfma_f32_32x32x16_bf16 v[48:63], v[100:103], v[104:107], v[48:63]
	v_mfma_f32_32x32x16_bf16 v[32:47], v[100:103], v[108:111], v[32:47]
	ds_read_b128 v[100:103], v84 offset:36864
	s_waitcnt lgkmcnt(0)
	v_mfma_f32_32x32x16_bf16 v[16:31], v[100:103], v[104:107], v[16:31]
	v_mfma_f32_32x32x16_bf16 v[0:15], v[100:103], v[108:111], v[0:15]
	ds_read_b128 v[100:103], v86 offset:32768
	ds_read_b128 v[104:107], v87 offset:49152
	ds_read_b128 v[108:111], v87 offset:53248
	s_waitcnt lgkmcnt(0)
	v_mfma_f32_32x32x16_bf16 v[48:63], v[100:103], v[104:107], v[48:63]
	v_mfma_f32_32x32x16_bf16 v[32:47], v[100:103], v[108:111], v[32:47]
	ds_read_b128 v[100:103], v86 offset:36864
	s_waitcnt lgkmcnt(0)
	v_mfma_f32_32x32x16_bf16 v[16:31], v[100:103], v[104:107], v[16:31]
	v_mfma_f32_32x32x16_bf16 v[0:15], v[100:103], v[108:111], v[0:15]
	s_waitcnt vmcnt(0)
	s_barrier
; #define WAIT_V0() asm volatile("s_waitcnt vmcnt(0)" ::: "memory")
; DI void gemm_core(char* smem, int nk, const char* Ab, const char* Bb, const unsigned (&aoff)[4], const unsigned (&boff)[4],
;                   f32x16 (&acc)[2][2]) {
;     ...
;   for (int kt = 0; kt < nk; ++kt) {
;     const int cur = kt & 1;
;     if (kt + 1 < nk) stage(cur ^ 1, kt + 1);
;     const char* sb = smem + cur * STAGE_B;
; #pragma unroll
;     for (int ks = 0; ks < 4; ++ks) {
;       bf16x8 af[2], bfr[2];
; #pragma unroll
;       for (int mb = 0; mb < 2; ++mb) af[mb] = *(const bf16x8*)(sb + a_base + mb * 4096 + xo[ks]);
; #pragma unroll
;       for (int nb = 0; nb < 2; ++nb) bfr[nb] = *(const bf16x8*)(sb + b_base + nb * 4096 + xo[ks]);
; #pragma unroll
;       for (int mb = 0; mb < 2; ++mb)
; #pragma unroll
;         for (int nb = 0; nb < 2; ++nb)
;           acc[mb][nb] = __builtin_amdgcn_mfma_f32_32x32x16_bf16(af[mb], bfr[nb], acc[mb][nb], 0, 0, 0);
;     }
;     WAIT_V0();
;     __syncthreads();
;   }
	ds_read_b128 v[100:103], v80
	ds_read_b128 v[104:107], v82 offset:16384
	ds_read_b128 v[108:111], v82 offset:20480
	v_lshl_add_u64 v[116:117], v[64:65], 0, s[46:47]
	global_load_lds_dwordx4 v[116:117], off
	v_lshl_add_u64 v[118:119], v[66:67], 0, s[46:47]
	s_mov_b32 m0, s43
	s_nop 0
	global_load_lds_dwordx4 v[118:119], off
	v_lshl_add_u64 v[116:117], v[68:69], 0, s[46:47]
	s_mov_b32 m0, s44
	s_nop 0
	global_load_lds_dwordx4 v[116:117], off
	v_lshl_add_u64 v[118:119], v[70:71], 0, s[46:47]
	s_mov_b32 m0, s1
	s_nop 0
	global_load_lds_dwordx4 v[118:119], off
	v_lshl_add_u64 v[116:117], v[72:73], 0, s[46:47]
	s_mov_b32 m0, s16
	s_nop 0
	global_load_lds_dwordx4 v[116:117], off
	v_lshl_add_u64 v[118:119], v[74:75], 0, s[46:47]
	s_mov_b32 m0, s17
	s_nop 0
	global_load_lds_dwordx4 v[118:119], off
	v_lshl_add_u64 v[116:117], v[76:77], 0, s[46:47]
	s_mov_b32 m0, s18
	s_nop 0
	global_load_lds_dwordx4 v[116:117], off
	v_lshl_add_u64 v[118:119], v[78:79], 0, s[46:47]
	s_mov_b32 m0, s19
	s_nop 0
	global_load_lds_dwordx4 v[118:119], off
	s_waitcnt lgkmcnt(0)
	v_mfma_f32_32x32x16_bf16 v[48:63], v[100:103], v[104:107], v[48:63]
	s_mov_b32 m0, s20
	v_mfma_f32_32x32x16_bf16 v[32:47], v[100:103], v[108:111], v[32:47]
	ds_read_b128 v[100:103], v80 offset:4096
	s_waitcnt lgkmcnt(0)
	v_mfma_f32_32x32x16_bf16 v[16:31], v[100:103], v[104:107], v[16:31]
	v_mfma_f32_32x32x16_bf16 v[0:15], v[100:103], v[108:111], v[0:15]
	ds_read_b128 v[100:103], v81
	ds_read_b128 v[104:107], v83 offset:16384
	ds_read_b128 v[108:111], v83 offset:20480
	s_waitcnt lgkmcnt(0)
	v_mfma_f32_32x32x16_bf16 v[48:63], v[100:103], v[104:107], v[48:63]
	v_mfma_f32_32x32x16_bf16 v[32:47], v[100:103], v[108:111], v[32:47]
	ds_read_b128 v[100:103], v81 offset:4096
	s_waitcnt lgkmcnt(0)
	v_mfma_f32_32x32x16_bf16 v[16:31], v[100:103], v[104:107], v[16:31]
	v_mfma_f32_32x32x16_bf16 v[0:15], v[100:103], v[108:111], v[0:15]
	ds_read_b128 v[100:103], v84
	ds_read_b128 v[104:107], v85 offset:16384
	ds_read_b128 v[108:111], v85 offset:20480
	s_waitcnt lgkmcnt(0)
	v_mfma_f32_32x32x16_bf16 v[48:63], v[100:103], v[104:107], v[48:63]
	v_mfma_f32_32x32x16_bf16 v[32:47], v[100:103], v[108:111], v[32:47]
	ds_read_b128 v[100:103], v84 offset:4096
	s_waitcnt lgkmcnt(0)
	v_mfma_f32_32x32x16_bf16 v[16:31], v[100:103], v[104:107], v[16:31]
	v_mfma_f32_32x32x16_bf16 v[0:15], v[100:103], v[108:111], v[0:15]
	ds_read_b128 v[100:103], v86
	ds_read_b128 v[104:107], v87 offset:16384
	ds_read_b128 v[108:111], v87 offset:20480
	s_waitcnt lgkmcnt(0)
	v_mfma_f32_32x32x16_bf16 v[48:63], v[100:103], v[104:107], v[48:63]
	v_mfma_f32_32x32x16_bf16 v[32:47], v[100:103], v[108:111], v[32:47]
	ds_read_b128 v[100:103], v86 offset:4096
	s_waitcnt lgkmcnt(0)
	v_mfma_f32_32x32x16_bf16 v[16:31], v[100:103], v[104:107], v[16:31]
	v_mfma_f32_32x32x16_bf16 v[0:15], v[100:103], v[108:111], v[0:15]
	s_waitcnt vmcnt(0)
	s_barrier
	ds_read_b128 v[100:103], v80 offset:32768
	ds_read_b128 v[104:107], v82 offset:49152
	ds_read_b128 v[108:111], v82 offset:53248
	v_lshl_add_u64 v[116:117], v[64:65], 0, s[48:49]
	global_load_lds_dwordx4 v[116:117], off
	v_lshl_add_u64 v[118:119], v[66:67], 0, s[48:49]
	s_mov_b32 m0, s21
	s_nop 0
	global_load_lds_dwordx4 v[118:119], off
	v_lshl_add_u64 v[116:117], v[68:69], 0, s[48:49]
	s_mov_b32 m0, s22
	s_nop 0
	global_load_lds_dwordx4 v[116:117], off
	v_lshl_add_u64 v[118:119], v[70:71], 0, s[48:49]
	s_mov_b32 m0, s23
	s_nop 0
	global_load_lds_dwordx4 v[118:119], off
	v_lshl_add_u64 v[116:117], v[72:73], 0, s[48:49]
	s_mov_b32 m0, s28
	s_nop 0
	global_load_lds_dwordx4 v[116:117], off
	v_lshl_add_u64 v[118:119], v[74:75], 0, s[48:49]
	s_mov_b32 m0, s29
	s_nop 0
	global_load_lds_dwordx4 v[118:119], off
	v_lshl_add_u64 v[116:117], v[76:77], 0, s[48:49]
	s_mov_b32 m0, s40
	s_nop 0
	global_load_lds_dwordx4 v[116:117], off
	v_lshl_add_u64 v[118:119], v[78:79], 0, s[48:49]
	s_mov_b32 m0, s41
	s_nop 0
	global_load_lds_dwordx4 v[118:119], off
	s_waitcnt lgkmcnt(0)
	v_mfma_f32_32x32x16_bf16 v[48:63], v[100:103], v[104:107], v[48:63]
	s_mov_b32 m0, s42
	v_readfirstlane_b32 s42, v93
	v_mfma_f32_32x32x16_bf16 v[32:47], v[100:103], v[108:111], v[32:47]
	ds_read_b128 v[100:103], v80 offset:36864
	s_waitcnt lgkmcnt(0)
	v_mfma_f32_32x32x16_bf16 v[16:31], v[100:103], v[104:107], v[16:31]
	v_mfma_f32_32x32x16_bf16 v[0:15], v[100:103], v[108:111], v[0:15]
	ds_read_b128 v[100:103], v81 offset:32768
	ds_read_b128 v[104:107], v83 offset:49152
	ds_read_b128 v[108:111], v83 offset:53248
	s_waitcnt lgkmcnt(0)
	v_mfma_f32_32x32x16_bf16 v[48:63], v[100:103], v[104:107], v[48:63]
	v_mfma_f32_32x32x16_bf16 v[32:47], v[100:103], v[108:111], v[32:47]
	ds_read_b128 v[100:103], v81 offset:36864
	s_waitcnt lgkmcnt(0)
	v_mfma_f32_32x32x16_bf16 v[16:31], v[100:103], v[104:107], v[16:31]
	v_mfma_f32_32x32x16_bf16 v[0:15], v[100:103], v[108:111], v[0:15]
	ds_read_b128 v[100:103], v84 offset:32768
	ds_read_b128 v[104:107], v85 offset:49152
	ds_read_b128 v[108:111], v85 offset:53248
	s_waitcnt lgkmcnt(0)
	v_mfma_f32_32x32x16_bf16 v[48:63], v[100:103], v[104:107], v[48:63]
	v_mfma_f32_32x32x16_bf16 v[32:47], v[100:103], v[108:111], v[32:47]
	ds_read_b128 v[100:103], v84 offset:36864
	s_waitcnt lgkmcnt(0)
	v_mfma_f32_32x32x16_bf16 v[16:31], v[100:103], v[104:107], v[16:31]
	v_mfma_f32_32x32x16_bf16 v[0:15], v[100:103], v[108:111], v[0:15]
	ds_read_b128 v[100:103], v86 offset:32768
	ds_read_b128 v[104:107], v87 offset:49152
	ds_read_b128 v[108:111], v87 offset:53248
	s_waitcnt lgkmcnt(0)
	v_mfma_f32_32x32x16_bf16 v[48:63], v[100:103], v[104:107], v[48:63]
	v_mfma_f32_32x32x16_bf16 v[32:47], v[100:103], v[108:111], v[32:47]
	ds_read_b128 v[100:103], v86 offset:36864
	s_waitcnt lgkmcnt(0)
	v_mfma_f32_32x32x16_bf16 v[16:31], v[100:103], v[104:107], v[16:31]
	v_mfma_f32_32x32x16_bf16 v[0:15], v[100:103], v[108:111], v[0:15]
	s_waitcnt vmcnt(0)
	s_barrier
; #define WAIT_V0() asm volatile("s_waitcnt vmcnt(0)" ::: "memory")
; DI void gemm_core(char* smem, int nk, const char* Ab, const char* Bb, const unsigned (&aoff)[4], const unsigned (&boff)[4],
;                   f32x16 (&acc)[2][2]) {
;     ...
;   for (int kt = 0; kt < nk; ++kt) {
;     const int cur = kt & 1;
;     if (kt + 1 < nk) stage(cur ^ 1, kt + 1);
;     const char* sb = smem + cur * STAGE_B;
; #pragma unroll
;     for (int ks = 0; ks < 4; ++ks) {
;       bf16x8 af[2], bfr[2];
; #pragma unroll
;       for (int mb = 0; mb < 2; ++mb) af[mb] = *(const bf16x8*)(sb + a_base + mb * 4096 + xo[ks]);
; #pragma unroll
;       for (int nb = 0; nb < 2; ++nb) bfr[nb] = *(const bf16x8*)(sb + b_base + nb * 4096 + xo[ks]);
; #pragma unroll
;       for (int mb = 0; mb < 2; ++mb)
; #pragma unroll
;         for (int nb = 0; nb < 2; ++nb)
;           acc[mb][nb] = __builtin_amdgcn_mfma_f32_32x32x16_bf16(af[mb], bfr[nb], acc[mb][nb], 0, 0, 0);
;     }
;     WAIT_V0();
;     __syncthreads();
;   }
	ds_read_b128 v[100:103], v80
	ds_read_b128 v[104:107], v82 offset:16384
	ds_read_b128 v[108:111], v82 offset:20480
	v_lshl_add_u64 v[116:117], v[64:65], 0, s[50:51]
	global_load_lds_dwordx4 v[116:117], off
	v_lshl_add_u64 v[118:119], v[66:67], 0, s[50:51]
	s_mov_b32 m0, s43
	v_readfirstlane_b32 s43, v94
	global_load_lds_dwordx4 v[118:119], off
	v_lshl_add_u64 v[116:117], v[68:69], 0, s[50:51]
	s_mov_b32 m0, s44
	v_readfirstlane_b32 s44, v95
	global_load_lds_dwordx4 v[116:117], off
	v_lshl_add_u64 v[118:119], v[70:71], 0, s[50:51]
	s_mov_b32 m0, s1
	s_nop 0
	global_load_lds_dwordx4 v[118:119], off
	v_lshl_add_u64 v[116:117], v[72:73], 0, s[50:51]
	s_mov_b32 m0, s16
	s_nop 0
	global_load_lds_dwordx4 v[116:117], off
	v_lshl_add_u64 v[118:119], v[74:75], 0, s[50:51]
	s_mov_b32 m0, s17
	s_nop 0
	global_load_lds_dwordx4 v[118:119], off
	v_lshl_add_u64 v[116:117], v[76:77], 0, s[50:51]
	s_mov_b32 m0, s18
	s_nop 0
	global_load_lds_dwordx4 v[116:117], off
	v_lshl_add_u64 v[118:119], v[78:79], 0, s[50:51]
	s_mov_b32 m0, s19
	s_nop 0
	global_load_lds_dwordx4 v[118:119], off
	s_waitcnt lgkmcnt(0)
	v_mfma_f32_32x32x16_bf16 v[48:63], v[100:103], v[104:107], v[48:63]
	s_mov_b32 m0, s20
	v_readfirstlane_b32 s20, v97
	v_mfma_f32_32x32x16_bf16 v[32:47], v[100:103], v[108:111], v[32:47]
	ds_read_b128 v[100:103], v80 offset:4096
	s_waitcnt lgkmcnt(0)
	v_mfma_f32_32x32x16_bf16 v[16:31], v[100:103], v[104:107], v[16:31]
	v_mfma_f32_32x32x16_bf16 v[0:15], v[100:103], v[108:111], v[0:15]
	ds_read_b128 v[100:103], v81
	ds_read_b128 v[104:107], v83 offset:16384
	ds_read_b128 v[108:111], v83 offset:20480
	s_waitcnt lgkmcnt(0)
	v_mfma_f32_32x32x16_bf16 v[48:63], v[100:103], v[104:107], v[48:63]
	v_mfma_f32_32x32x16_bf16 v[32:47], v[100:103], v[108:111], v[32:47]
	ds_read_b128 v[100:103], v81 offset:4096
	s_waitcnt lgkmcnt(0)
	v_mfma_f32_32x32x16_bf16 v[16:31], v[100:103], v[104:107], v[16:31]
	v_mfma_f32_32x32x16_bf16 v[0:15], v[100:103], v[108:111], v[0:15]
	ds_read_b128 v[100:103], v84
	ds_read_b128 v[104:107], v85 offset:16384
	ds_read_b128 v[108:111], v85 offset:20480
	s_waitcnt lgkmcnt(0)
	v_mfma_f32_32x32x16_bf16 v[48:63], v[100:103], v[104:107], v[48:63]
	v_mfma_f32_32x32x16_bf16 v[32:47], v[100:103], v[108:111], v[32:47]
	ds_read_b128 v[100:103], v84 offset:4096
	s_waitcnt lgkmcnt(0)
	v_mfma_f32_32x32x16_bf16 v[16:31], v[100:103], v[104:107], v[16:31]
	v_mfma_f32_32x32x16_bf16 v[0:15], v[100:103], v[108:111], v[0:15]
	ds_read_b128 v[100:103], v86
	ds_read_b128 v[104:107], v87 offset:16384
	ds_read_b128 v[108:111], v87 offset:20480
	s_waitcnt lgkmcnt(0)
	v_mfma_f32_32x32x16_bf16 v[48:63], v[100:103], v[104:107], v[48:63]
	v_mfma_f32_32x32x16_bf16 v[32:47], v[100:103], v[108:111], v[32:47]
	ds_read_b128 v[100:103], v86 offset:4096
	s_waitcnt lgkmcnt(0)
	v_mfma_f32_32x32x16_bf16 v[16:31], v[100:103], v[104:107], v[16:31]
	v_mfma_f32_32x32x16_bf16 v[0:15], v[100:103], v[108:111], v[0:15]
	s_waitcnt vmcnt(0)
	s_barrier
	v_lshl_add_u64 v[100:101], v[64:65], 0, s[52:53]
	global_load_lds_dwordx4 v[100:101], off
	v_lshl_add_u64 v[100:101], v[66:67], 0, s[52:53]
	s_mov_b32 m0, s21
	v_readfirstlane_b32 s21, v96
	global_load_lds_dwordx4 v[100:101], off
	v_lshl_add_u64 v[100:101], v[68:69], 0, s[52:53]
	s_mov_b32 m0, s22
	v_readfirstlane_b32 s22, v98
	global_load_lds_dwordx4 v[100:101], off
	v_lshl_add_u64 v[100:101], v[70:71], 0, s[52:53]
	s_mov_b32 m0, s23
	v_lshl_add_u64 v[96:97], v[68:69], 0, s[54:55]
	global_load_lds_dwordx4 v[100:101], off
	v_lshl_add_u64 v[100:101], v[72:73], 0, s[52:53]
	s_mov_b32 m0, s28
	v_readfirstlane_b32 s23, v89
	global_load_lds_dwordx4 v[100:101], off
	v_lshl_add_u64 v[100:101], v[74:75], 0, s[52:53]
	s_mov_b32 m0, s29
	v_readfirstlane_b32 s28, v88
	global_load_lds_dwordx4 v[100:101], off
	v_lshl_add_u64 v[100:101], v[76:77], 0, s[52:53]
	s_mov_b32 m0, s40
	v_readfirstlane_b32 s29, v90
	global_load_lds_dwordx4 v[100:101], off
	v_lshl_add_u64 v[100:101], v[78:79], 0, s[52:53]
	s_mov_b32 m0, s41
	v_lshl_add_u64 v[88:89], v[68:69], 0, s[56:57]
	global_load_lds_dwordx4 v[100:101], off
	ds_read_b128 v[100:103], v80 offset:32768
	ds_read_b128 v[104:107], v82 offset:49152
	ds_read_b128 v[108:111], v82 offset:53248
	s_waitcnt lgkmcnt(0)
	v_mfma_f32_32x32x16_bf16 v[48:63], v[100:103], v[104:107], v[48:63]
	s_mov_b32 m0, s20
	v_readfirstlane_b32 s40, v91
	v_readfirstlane_b32 s41, v92
	v_mfma_f32_32x32x16_bf16 v[32:47], v[100:103], v[108:111], v[32:47]
	ds_read_b128 v[100:103], v80 offset:36864
	s_waitcnt lgkmcnt(0)
	v_mfma_f32_32x32x16_bf16 v[16:31], v[100:103], v[104:107], v[16:31]
	v_mfma_f32_32x32x16_bf16 v[0:15], v[100:103], v[108:111], v[0:15]
	ds_read_b128 v[100:103], v81 offset:32768
	ds_read_b128 v[104:107], v83 offset:49152
	ds_read_b128 v[108:111], v83 offset:53248
	s_waitcnt lgkmcnt(0)
	v_mfma_f32_32x32x16_bf16 v[48:63], v[100:103], v[104:107], v[48:63]
	v_mfma_f32_32x32x16_bf16 v[32:47], v[100:103], v[108:111], v[32:47]
	ds_read_b128 v[100:103], v81 offset:36864
	s_waitcnt lgkmcnt(0)
	v_mfma_f32_32x32x16_bf16 v[16:31], v[100:103], v[104:107], v[16:31]
	v_mfma_f32_32x32x16_bf16 v[0:15], v[100:103], v[108:111], v[0:15]
	ds_read_b128 v[100:103], v84 offset:32768
	ds_read_b128 v[104:107], v85 offset:49152
	ds_read_b128 v[108:111], v85 offset:53248
	s_waitcnt lgkmcnt(0)
	v_mfma_f32_32x32x16_bf16 v[48:63], v[100:103], v[104:107], v[48:63]
	v_mfma_f32_32x32x16_bf16 v[32:47], v[100:103], v[108:111], v[32:47]
	ds_read_b128 v[100:103], v84 offset:36864
	s_waitcnt lgkmcnt(0)
	v_mfma_f32_32x32x16_bf16 v[16:31], v[100:103], v[104:107], v[16:31]
	v_mfma_f32_32x32x16_bf16 v[0:15], v[100:103], v[108:111], v[0:15]
	ds_read_b128 v[100:103], v86 offset:32768
	ds_read_b128 v[104:107], v87 offset:49152
	ds_read_b128 v[108:111], v87 offset:53248
	s_waitcnt lgkmcnt(0)
	v_mfma_f32_32x32x16_bf16 v[48:63], v[100:103], v[104:107], v[48:63]
	v_mfma_f32_32x32x16_bf16 v[32:47], v[100:103], v[108:111], v[32:47]
	ds_read_b128 v[100:103], v86 offset:36864
	s_waitcnt lgkmcnt(0)
	v_mfma_f32_32x32x16_bf16 v[16:31], v[100:103], v[104:107], v[16:31]
	v_mfma_f32_32x32x16_bf16 v[0:15], v[100:103], v[108:111], v[0:15]
	s_waitcnt vmcnt(0)
	s_barrier
; #define WAIT_V0() asm volatile("s_waitcnt vmcnt(0)" ::: "memory")
; DI void gemm_core(char* smem, int nk, const char* Ab, const char* Bb, const unsigned (&aoff)[4], const unsigned (&boff)[4],
;                   f32x16 (&acc)[2][2]) {
;     ...
;   for (int kt = 0; kt < nk; ++kt) {
;     const int cur = kt & 1;
;     if (kt + 1 < nk) stage(cur ^ 1, kt + 1);
;     const char* sb = smem + cur * STAGE_B;
; #pragma unroll
;     for (int ks = 0; ks < 4; ++ks) {
;       bf16x8 af[2], bfr[2];
; #pragma unroll
;       for (int mb = 0; mb < 2; ++mb) af[mb] = *(const bf16x8*)(sb + a_base + mb * 4096 + xo[ks]);
; #pragma unroll
;       for (int nb = 0; nb < 2; ++nb) bfr[nb] = *(const bf16x8*)(sb + b_base + nb * 4096 + xo[ks]);
; #pragma unroll
;       for (int mb = 0; mb < 2; ++mb)
; #pragma unroll
;         for (int nb = 0; nb < 2; ++nb)
;           acc[mb][nb] = __builtin_amdgcn_mfma_f32_32x32x16_bf16(af[mb], bfr[nb], acc[mb][nb], 0, 0, 0);
;     }
;     WAIT_V0();
;     __syncthreads();
;   }
	v_lshl_add_u64 v[100:101], v[64:65], 0, s[54:55]
	global_load_lds_dwordx4 v[100:101], off
	v_lshl_add_u64 v[100:101], v[66:67], 0, s[54:55]
	s_mov_b32 m0, s21
	s_nop 0
	global_load_lds_dwordx4 v[100:101], off
	s_mov_b32 m0, s22
	s_nop 0
	global_load_lds_dwordx4 v[96:97], off
	v_lshl_add_u64 v[96:97], v[70:71], 0, s[54:55]
	s_mov_b32 m0, s1
	s_nop 0
	global_load_lds_dwordx4 v[96:97], off
	v_lshl_add_u64 v[96:97], v[72:73], 0, s[54:55]
	s_mov_b32 m0, s16
	s_nop 0
	global_load_lds_dwordx4 v[96:97], off
	v_lshl_add_u64 v[96:97], v[74:75], 0, s[54:55]
	s_mov_b32 m0, s17
	s_nop 0
	global_load_lds_dwordx4 v[96:97], off
	v_lshl_add_u64 v[96:97], v[76:77], 0, s[54:55]
	s_mov_b32 m0, s18
	s_nop 0
	global_load_lds_dwordx4 v[96:97], off
	v_lshl_add_u64 v[96:97], v[78:79], 0, s[54:55]
	s_mov_b32 m0, s19
	s_nop 0
	global_load_lds_dwordx4 v[96:97], off
	ds_read_b128 v[96:99], v80
	ds_read_b128 v[100:103], v82 offset:16384
	ds_read_b128 v[104:107], v82 offset:20480
	s_waitcnt lgkmcnt(0)
	v_mfma_f32_32x32x16_bf16 v[48:63], v[96:99], v[100:103], v[48:63]
	s_mov_b32 m0, s23
	v_mfma_f32_32x32x16_bf16 v[32:47], v[96:99], v[104:107], v[32:47]
	ds_read_b128 v[96:99], v80 offset:4096
	s_waitcnt lgkmcnt(0)
	v_mfma_f32_32x32x16_bf16 v[16:31], v[96:99], v[100:103], v[16:31]
	v_mfma_f32_32x32x16_bf16 v[0:15], v[96:99], v[104:107], v[0:15]
	ds_read_b128 v[96:99], v81
	ds_read_b128 v[100:103], v83 offset:16384
	ds_read_b128 v[104:107], v83 offset:20480
	s_waitcnt lgkmcnt(0)
	v_mfma_f32_32x32x16_bf16 v[48:63], v[96:99], v[100:103], v[48:63]
	v_mfma_f32_32x32x16_bf16 v[32:47], v[96:99], v[104:107], v[32:47]
	ds_read_b128 v[96:99], v81 offset:4096
	s_waitcnt lgkmcnt(0)
	v_mfma_f32_32x32x16_bf16 v[16:31], v[96:99], v[100:103], v[16:31]
	v_mfma_f32_32x32x16_bf16 v[0:15], v[96:99], v[104:107], v[0:15]
	ds_read_b128 v[96:99], v84
	ds_read_b128 v[100:103], v85 offset:16384
	ds_read_b128 v[104:107], v85 offset:20480
	s_waitcnt lgkmcnt(0)
	v_mfma_f32_32x32x16_bf16 v[48:63], v[96:99], v[100:103], v[48:63]
	v_mfma_f32_32x32x16_bf16 v[32:47], v[96:99], v[104:107], v[32:47]
	ds_read_b128 v[96:99], v84 offset:4096
	s_waitcnt lgkmcnt(0)
	v_mfma_f32_32x32x16_bf16 v[16:31], v[96:99], v[100:103], v[16:31]
	v_mfma_f32_32x32x16_bf16 v[0:15], v[96:99], v[104:107], v[0:15]
	ds_read_b128 v[96:99], v86
	ds_read_b128 v[100:103], v87 offset:16384
	ds_read_b128 v[104:107], v87 offset:20480
	s_waitcnt lgkmcnt(0)
	v_mfma_f32_32x32x16_bf16 v[48:63], v[96:99], v[100:103], v[48:63]
	v_mfma_f32_32x32x16_bf16 v[32:47], v[96:99], v[104:107], v[32:47]
	ds_read_b128 v[96:99], v86 offset:4096
	s_waitcnt lgkmcnt(0)
	v_mfma_f32_32x32x16_bf16 v[16:31], v[96:99], v[100:103], v[16:31]
	v_mfma_f32_32x32x16_bf16 v[0:15], v[96:99], v[104:107], v[0:15]
	s_waitcnt vmcnt(0)
	s_barrier
	v_lshl_add_u64 v[96:97], v[64:65], 0, s[56:57]
	global_load_lds_dwordx4 v[96:97], off
	v_lshl_add_u64 v[96:97], v[66:67], 0, s[56:57]
	s_mov_b32 m0, s28
	s_nop 0
	global_load_lds_dwordx4 v[96:97], off
	s_mov_b32 m0, s29
	s_nop 0
	global_load_lds_dwordx4 v[88:89], off
	v_lshl_add_u64 v[88:89], v[70:71], 0, s[56:57]
	s_mov_b32 m0, s40
	s_nop 0
	global_load_lds_dwordx4 v[88:89], off
	v_lshl_add_u64 v[88:89], v[72:73], 0, s[56:57]
	s_mov_b32 m0, s41
	s_nop 0
	global_load_lds_dwordx4 v[88:89], off
	v_lshl_add_u64 v[88:89], v[74:75], 0, s[56:57]
	s_mov_b32 m0, s42
	s_nop 0
	global_load_lds_dwordx4 v[88:89], off
	v_lshl_add_u64 v[88:89], v[76:77], 0, s[56:57]
	s_mov_b32 m0, s43
	s_nop 0
	global_load_lds_dwordx4 v[88:89], off
	v_lshl_add_u64 v[88:89], v[78:79], 0, s[56:57]
	s_mov_b32 m0, s44
	s_nop 0
	global_load_lds_dwordx4 v[88:89], off
	ds_read_b128 v[88:91], v80 offset:32768
	ds_read_b128 v[92:95], v82 offset:49152
	ds_read_b128 v[96:99], v82 offset:53248
	s_waitcnt lgkmcnt(0)
	v_mfma_f32_32x32x16_bf16 v[48:63], v[88:91], v[92:95], v[48:63]
	s_mov_b32 m0, s20
	v_mfma_f32_32x32x16_bf16 v[32:47], v[88:91], v[96:99], v[32:47]
	ds_read_b128 v[88:91], v80 offset:36864
	s_waitcnt lgkmcnt(0)
	v_mfma_f32_32x32x16_bf16 v[16:31], v[88:91], v[92:95], v[16:31]
	v_mfma_f32_32x32x16_bf16 v[0:15], v[88:91], v[96:99], v[0:15]
	ds_read_b128 v[88:91], v81 offset:32768
	ds_read_b128 v[92:95], v83 offset:49152
	ds_read_b128 v[96:99], v83 offset:53248
	s_waitcnt lgkmcnt(0)
	v_mfma_f32_32x32x16_bf16 v[48:63], v[88:91], v[92:95], v[48:63]
	v_mfma_f32_32x32x16_bf16 v[32:47], v[88:91], v[96:99], v[32:47]
	ds_read_b128 v[88:91], v81 offset:36864
	s_waitcnt lgkmcnt(0)
	v_mfma_f32_32x32x16_bf16 v[16:31], v[88:91], v[92:95], v[16:31]
	v_mfma_f32_32x32x16_bf16 v[0:15], v[88:91], v[96:99], v[0:15]
	ds_read_b128 v[88:91], v84 offset:32768
	ds_read_b128 v[92:95], v85 offset:49152
	ds_read_b128 v[96:99], v85 offset:53248
	s_waitcnt lgkmcnt(0)
	v_mfma_f32_32x32x16_bf16 v[48:63], v[88:91], v[92:95], v[48:63]
	v_mfma_f32_32x32x16_bf16 v[32:47], v[88:91], v[96:99], v[32:47]
	ds_read_b128 v[88:91], v84 offset:36864
	s_waitcnt lgkmcnt(0)
	v_mfma_f32_32x32x16_bf16 v[16:31], v[88:91], v[92:95], v[16:31]
	v_mfma_f32_32x32x16_bf16 v[0:15], v[88:91], v[96:99], v[0:15]
	ds_read_b128 v[88:91], v86 offset:32768
	ds_read_b128 v[92:95], v87 offset:49152
	ds_read_b128 v[96:99], v87 offset:53248
	s_waitcnt lgkmcnt(0)
	v_mfma_f32_32x32x16_bf16 v[48:63], v[88:91], v[92:95], v[48:63]
	v_mfma_f32_32x32x16_bf16 v[32:47], v[88:91], v[96:99], v[32:47]
	ds_read_b128 v[88:91], v86 offset:36864
	s_waitcnt lgkmcnt(0)
	v_mfma_f32_32x32x16_bf16 v[16:31], v[88:91], v[92:95], v[16:31]
	v_mfma_f32_32x32x16_bf16 v[0:15], v[88:91], v[96:99], v[0:15]
	s_waitcnt vmcnt(0)
	s_barrier
; #define WAIT_V0() asm volatile("s_waitcnt vmcnt(0)" ::: "memory")
; DI void gemm_core(char* smem, int nk, const char* Ab, const char* Bb, const unsigned (&aoff)[4], const unsigned (&boff)[4],
;                   f32x16 (&acc)[2][2]) {
;     ...
;   for (int kt = 0; kt < nk; ++kt) {
;     const int cur = kt & 1;
;     if (kt + 1 < nk) stage(cur ^ 1, kt + 1);
;     const char* sb = smem + cur * STAGE_B;
; #pragma unroll
;     for (int ks = 0; ks < 4; ++ks) {
;       bf16x8 af[2], bfr[2];
; #pragma unroll
;       for (int mb = 0; mb < 2; ++mb) af[mb] = *(const bf16x8*)(sb + a_base + mb * 4096 + xo[ks]);
; #pragma unroll
;       for (int nb = 0; nb < 2; ++nb) bfr[nb] = *(const bf16x8*)(sb + b_base + nb * 4096 + xo[ks]);
; #pragma unroll
;       for (int mb = 0; mb < 2; ++mb)
; #pragma unroll
;         for (int nb = 0; nb < 2; ++nb)
;           acc[mb][nb] = __builtin_amdgcn_mfma_f32_32x32x16_bf16(af[mb], bfr[nb], acc[mb][nb], 0, 0, 0);
;     }
;     WAIT_V0();
;     __syncthreads();
;   }
	ds_read_b128 v[88:91], v80
	ds_read_b128 v[92:95], v82 offset:16384
	ds_read_b128 v[96:99], v82 offset:20480
	v_lshl_add_u64 v[116:117], v[64:65], 0, s[58:59]
	global_load_lds_dwordx4 v[116:117], off
	v_lshl_add_u64 v[118:119], v[66:67], 0, s[58:59]
	s_mov_b32 m0, s21
	s_nop 0
	global_load_lds_dwordx4 v[118:119], off
	v_lshl_add_u64 v[116:117], v[68:69], 0, s[58:59]
	s_mov_b32 m0, s22
	s_nop 0
	global_load_lds_dwordx4 v[116:117], off
	v_lshl_add_u64 v[118:119], v[70:71], 0, s[58:59]
	s_mov_b32 m0, s1
	s_nop 0
	global_load_lds_dwordx4 v[118:119], off
	v_lshl_add_u64 v[116:117], v[72:73], 0, s[58:59]
	s_mov_b32 m0, s16
	s_nop 0
	global_load_lds_dwordx4 v[116:117], off
	v_lshl_add_u64 v[118:119], v[74:75], 0, s[58:59]
	s_mov_b32 m0, s17
	s_nop 0
	global_load_lds_dwordx4 v[118:119], off
	v_lshl_add_u64 v[116:117], v[76:77], 0, s[58:59]
	s_mov_b32 m0, s18
	s_nop 0
	global_load_lds_dwordx4 v[116:117], off
	v_lshl_add_u64 v[118:119], v[78:79], 0, s[58:59]
	s_mov_b32 m0, s19
	s_nop 0
	global_load_lds_dwordx4 v[118:119], off
	s_waitcnt lgkmcnt(0)
	v_mfma_f32_32x32x16_bf16 v[48:63], v[88:91], v[92:95], v[48:63]
	s_mov_b32 m0, s23
	v_mfma_f32_32x32x16_bf16 v[32:47], v[88:91], v[96:99], v[32:47]
	ds_read_b128 v[88:91], v80 offset:4096
	s_waitcnt lgkmcnt(0)
	v_mfma_f32_32x32x16_bf16 v[16:31], v[88:91], v[92:95], v[16:31]
	v_mfma_f32_32x32x16_bf16 v[0:15], v[88:91], v[96:99], v[0:15]
	ds_read_b128 v[88:91], v81
	ds_read_b128 v[92:95], v83 offset:16384
	ds_read_b128 v[96:99], v83 offset:20480
	s_waitcnt lgkmcnt(0)
	v_mfma_f32_32x32x16_bf16 v[48:63], v[88:91], v[92:95], v[48:63]
	v_mfma_f32_32x32x16_bf16 v[32:47], v[88:91], v[96:99], v[32:47]
	ds_read_b128 v[88:91], v81 offset:4096
	s_waitcnt lgkmcnt(0)
	v_mfma_f32_32x32x16_bf16 v[16:31], v[88:91], v[92:95], v[16:31]
	v_mfma_f32_32x32x16_bf16 v[0:15], v[88:91], v[96:99], v[0:15]
	ds_read_b128 v[88:91], v84
	ds_read_b128 v[92:95], v85 offset:16384
	ds_read_b128 v[96:99], v85 offset:20480
	s_waitcnt lgkmcnt(0)
	v_mfma_f32_32x32x16_bf16 v[48:63], v[88:91], v[92:95], v[48:63]
	v_mfma_f32_32x32x16_bf16 v[32:47], v[88:91], v[96:99], v[32:47]
	ds_read_b128 v[88:91], v84 offset:4096
	s_waitcnt lgkmcnt(0)
	v_mfma_f32_32x32x16_bf16 v[16:31], v[88:91], v[92:95], v[16:31]
	v_mfma_f32_32x32x16_bf16 v[0:15], v[88:91], v[96:99], v[0:15]
	ds_read_b128 v[88:91], v86
	ds_read_b128 v[92:95], v87 offset:16384
	ds_read_b128 v[96:99], v87 offset:20480
	s_waitcnt lgkmcnt(0)
	v_mfma_f32_32x32x16_bf16 v[48:63], v[88:91], v[92:95], v[48:63]
	v_mfma_f32_32x32x16_bf16 v[32:47], v[88:91], v[96:99], v[32:47]
	ds_read_b128 v[88:91], v86 offset:4096
	s_waitcnt lgkmcnt(0)
	v_mfma_f32_32x32x16_bf16 v[16:31], v[88:91], v[92:95], v[16:31]
	v_mfma_f32_32x32x16_bf16 v[0:15], v[88:91], v[96:99], v[0:15]
	s_waitcnt vmcnt(0)
	s_barrier
	ds_read_b128 v[88:91], v80 offset:32768
	ds_read_b128 v[92:95], v82 offset:49152
	ds_read_b128 v[96:99], v82 offset:53248
	v_lshl_add_u64 v[116:117], v[64:65], 0, s[60:61]
	global_load_lds_dwordx4 v[116:117], off
	v_lshl_add_u64 v[118:119], v[66:67], 0, s[60:61]
	s_mov_b32 m0, s28
	s_nop 0
	global_load_lds_dwordx4 v[118:119], off
	v_lshl_add_u64 v[116:117], v[68:69], 0, s[60:61]
	s_mov_b32 m0, s29
	s_nop 0
	global_load_lds_dwordx4 v[116:117], off
	v_lshl_add_u64 v[118:119], v[70:71], 0, s[60:61]
	s_mov_b32 m0, s40
	s_nop 0
	global_load_lds_dwordx4 v[118:119], off
	v_lshl_add_u64 v[116:117], v[72:73], 0, s[60:61]
	s_mov_b32 m0, s41
	s_nop 0
	global_load_lds_dwordx4 v[116:117], off
	v_lshl_add_u64 v[118:119], v[74:75], 0, s[60:61]
	s_mov_b32 m0, s42
	s_nop 0
	global_load_lds_dwordx4 v[118:119], off
	v_lshl_add_u64 v[116:117], v[76:77], 0, s[60:61]
	s_mov_b32 m0, s43
	s_nop 0
	global_load_lds_dwordx4 v[116:117], off
	v_lshl_add_u64 v[118:119], v[78:79], 0, s[60:61]
	s_mov_b32 m0, s44
	s_nop 0
	global_load_lds_dwordx4 v[118:119], off
	s_waitcnt lgkmcnt(0)
	v_mfma_f32_32x32x16_bf16 v[48:63], v[88:91], v[92:95], v[48:63]
	s_mov_b32 m0, s20
	v_mfma_f32_32x32x16_bf16 v[32:47], v[88:91], v[96:99], v[32:47]
	ds_read_b128 v[88:91], v80 offset:36864
	s_waitcnt lgkmcnt(0)
	v_mfma_f32_32x32x16_bf16 v[16:31], v[88:91], v[92:95], v[16:31]
	v_mfma_f32_32x32x16_bf16 v[0:15], v[88:91], v[96:99], v[0:15]
	ds_read_b128 v[88:91], v81 offset:32768
	ds_read_b128 v[92:95], v83 offset:49152
	ds_read_b128 v[96:99], v83 offset:53248
	s_waitcnt lgkmcnt(0)
	v_mfma_f32_32x32x16_bf16 v[48:63], v[88:91], v[92:95], v[48:63]
	v_mfma_f32_32x32x16_bf16 v[32:47], v[88:91], v[96:99], v[32:47]
	ds_read_b128 v[88:91], v81 offset:36864
	s_waitcnt lgkmcnt(0)
	v_mfma_f32_32x32x16_bf16 v[16:31], v[88:91], v[92:95], v[16:31]
	v_mfma_f32_32x32x16_bf16 v[0:15], v[88:91], v[96:99], v[0:15]
	ds_read_b128 v[88:91], v84 offset:32768
	ds_read_b128 v[92:95], v85 offset:49152
	ds_read_b128 v[96:99], v85 offset:53248
	s_waitcnt lgkmcnt(0)
	v_mfma_f32_32x32x16_bf16 v[48:63], v[88:91], v[92:95], v[48:63]
	v_mfma_f32_32x32x16_bf16 v[32:47], v[88:91], v[96:99], v[32:47]
	ds_read_b128 v[88:91], v84 offset:36864
	s_waitcnt lgkmcnt(0)
	v_mfma_f32_32x32x16_bf16 v[16:31], v[88:91], v[92:95], v[16:31]
	v_mfma_f32_32x32x16_bf16 v[0:15], v[88:91], v[96:99], v[0:15]
	ds_read_b128 v[88:91], v86 offset:32768
	ds_read_b128 v[92:95], v87 offset:49152
	ds_read_b128 v[96:99], v87 offset:53248
	s_waitcnt lgkmcnt(0)
	v_mfma_f32_32x32x16_bf16 v[48:63], v[88:91], v[92:95], v[48:63]
	v_mfma_f32_32x32x16_bf16 v[32:47], v[88:91], v[96:99], v[32:47]
	ds_read_b128 v[88:91], v86 offset:36864
	s_waitcnt lgkmcnt(0)
	v_mfma_f32_32x32x16_bf16 v[16:31], v[88:91], v[92:95], v[16:31]
	v_mfma_f32_32x32x16_bf16 v[0:15], v[88:91], v[96:99], v[0:15]
	s_waitcnt vmcnt(0)
	s_barrier
; #define WAIT_V0() asm volatile("s_waitcnt vmcnt(0)" ::: "memory")
; DI void gemm_core(char* smem, int nk, const char* Ab, const char* Bb, const unsigned (&aoff)[4], const unsigned (&boff)[4],
;                   f32x16 (&acc)[2][2]) {
;     ...
;   for (int kt = 0; kt < nk; ++kt) {
;     const int cur = kt & 1;
;     if (kt + 1 < nk) stage(cur ^ 1, kt + 1);
;     const char* sb = smem + cur * STAGE_B;
; #pragma unroll
;     for (int ks = 0; ks < 4; ++ks) {
;       bf16x8 af[2], bfr[2];
; #pragma unroll
;       for (int mb = 0; mb < 2; ++mb) af[mb] = *(const bf16x8*)(sb + a_base + mb * 4096 + xo[ks]);
; #pragma unroll
;       for (int nb = 0; nb < 2; ++nb) bfr[nb] = *(const bf16x8*)(sb + b_base + nb * 4096 + xo[ks]);
; #pragma unroll
;       for (int mb = 0; mb < 2; ++mb)
; #pragma unroll
;         for (int nb = 0; nb < 2; ++nb)
;           acc[mb][nb] = __builtin_amdgcn_mfma_f32_32x32x16_bf16(af[mb], bfr[nb], acc[mb][nb], 0, 0, 0);
;     }
;     WAIT_V0();
;     __syncthreads();
;   }
	ds_read_b128 v[88:91], v80
	ds_read_b128 v[92:95], v82 offset:16384
	ds_read_b128 v[96:99], v82 offset:20480
	v_lshl_add_u64 v[116:117], v[64:65], 0, s[62:63]
	global_load_lds_dwordx4 v[116:117], off
	v_lshl_add_u64 v[118:119], v[66:67], 0, s[62:63]
	s_mov_b32 m0, s21
	s_nop 0
	global_load_lds_dwordx4 v[118:119], off
	v_lshl_add_u64 v[116:117], v[68:69], 0, s[62:63]
	s_mov_b32 m0, s22
	s_nop 0
	global_load_lds_dwordx4 v[116:117], off
	v_lshl_add_u64 v[118:119], v[70:71], 0, s[62:63]
	s_mov_b32 m0, s1
	s_nop 0
	global_load_lds_dwordx4 v[118:119], off
	v_lshl_add_u64 v[116:117], v[72:73], 0, s[62:63]
	s_mov_b32 m0, s16
	s_nop 0
	global_load_lds_dwordx4 v[116:117], off
	v_lshl_add_u64 v[118:119], v[74:75], 0, s[62:63]
	s_mov_b32 m0, s17
	s_nop 0
	global_load_lds_dwordx4 v[118:119], off
	v_lshl_add_u64 v[116:117], v[76:77], 0, s[62:63]
	s_mov_b32 m0, s18
	s_nop 0
	global_load_lds_dwordx4 v[116:117], off
	v_lshl_add_u64 v[118:119], v[78:79], 0, s[62:63]
	s_mov_b32 m0, s19
	s_nop 0
	global_load_lds_dwordx4 v[118:119], off
	s_waitcnt lgkmcnt(0)
	v_mfma_f32_32x32x16_bf16 v[48:63], v[88:91], v[92:95], v[48:63]
	s_mov_b32 m0, s23
	v_mfma_f32_32x32x16_bf16 v[32:47], v[88:91], v[96:99], v[32:47]
	ds_read_b128 v[88:91], v80 offset:4096
	s_waitcnt lgkmcnt(0)
	v_mfma_f32_32x32x16_bf16 v[16:31], v[88:91], v[92:95], v[16:31]
	v_mfma_f32_32x32x16_bf16 v[0:15], v[88:91], v[96:99], v[0:15]
	ds_read_b128 v[88:91], v81
	ds_read_b128 v[92:95], v83 offset:16384
	ds_read_b128 v[96:99], v83 offset:20480
	s_waitcnt lgkmcnt(0)
	v_mfma_f32_32x32x16_bf16 v[48:63], v[88:91], v[92:95], v[48:63]
	v_mfma_f32_32x32x16_bf16 v[32:47], v[88:91], v[96:99], v[32:47]
	ds_read_b128 v[88:91], v81 offset:4096
	s_waitcnt lgkmcnt(0)
	v_mfma_f32_32x32x16_bf16 v[16:31], v[88:91], v[92:95], v[16:31]
	v_mfma_f32_32x32x16_bf16 v[0:15], v[88:91], v[96:99], v[0:15]
	ds_read_b128 v[88:91], v84
	ds_read_b128 v[92:95], v85 offset:16384
	ds_read_b128 v[96:99], v85 offset:20480
	s_waitcnt lgkmcnt(0)
	v_mfma_f32_32x32x16_bf16 v[48:63], v[88:91], v[92:95], v[48:63]
	v_mfma_f32_32x32x16_bf16 v[32:47], v[88:91], v[96:99], v[32:47]
	ds_read_b128 v[88:91], v84 offset:4096
	s_waitcnt lgkmcnt(0)
	v_mfma_f32_32x32x16_bf16 v[16:31], v[88:91], v[92:95], v[16:31]
	v_mfma_f32_32x32x16_bf16 v[0:15], v[88:91], v[96:99], v[0:15]
	ds_read_b128 v[88:91], v86
	ds_read_b128 v[92:95], v87 offset:16384
	ds_read_b128 v[96:99], v87 offset:20480
	s_waitcnt lgkmcnt(0)
	v_mfma_f32_32x32x16_bf16 v[48:63], v[88:91], v[92:95], v[48:63]
	v_mfma_f32_32x32x16_bf16 v[32:47], v[88:91], v[96:99], v[32:47]
	ds_read_b128 v[88:91], v86 offset:4096
	s_waitcnt lgkmcnt(0)
	v_mfma_f32_32x32x16_bf16 v[16:31], v[88:91], v[92:95], v[16:31]
	v_mfma_f32_32x32x16_bf16 v[0:15], v[88:91], v[96:99], v[0:15]
	s_waitcnt vmcnt(0)
	s_barrier
	v_lshl_add_u64 v[88:89], v[64:65], 0, s[64:65]
	global_load_lds_dwordx4 v[88:89], off
	v_lshl_add_u64 v[88:89], v[66:67], 0, s[64:65]
	s_mov_b32 m0, s28
	v_lshl_add_u64 v[64:65], v[64:65], 0, s[66:67]
	global_load_lds_dwordx4 v[88:89], off
	v_lshl_add_u64 v[88:89], v[68:69], 0, s[64:65]
	s_mov_b32 m0, s29
	s_nop 0
	global_load_lds_dwordx4 v[88:89], off
	v_lshl_add_u64 v[88:89], v[70:71], 0, s[64:65]
	s_mov_b32 m0, s40
	s_nop 0
	global_load_lds_dwordx4 v[88:89], off
	v_lshl_add_u64 v[88:89], v[72:73], 0, s[64:65]
	s_mov_b32 m0, s41
	s_nop 0
	global_load_lds_dwordx4 v[88:89], off
	v_lshl_add_u64 v[88:89], v[74:75], 0, s[64:65]
	s_mov_b32 m0, s42
	s_nop 0
	global_load_lds_dwordx4 v[88:89], off
	v_lshl_add_u64 v[88:89], v[76:77], 0, s[64:65]
	s_mov_b32 m0, s43
	s_nop 0
	global_load_lds_dwordx4 v[88:89], off
	v_lshl_add_u64 v[88:89], v[78:79], 0, s[64:65]
	s_mov_b32 m0, s44
	s_nop 0
	global_load_lds_dwordx4 v[88:89], off
	ds_read_b128 v[88:91], v80 offset:32768
	ds_read_b128 v[92:95], v82 offset:49152
	ds_read_b128 v[96:99], v82 offset:53248
	s_waitcnt lgkmcnt(0)
	v_mfma_f32_32x32x16_bf16 v[48:63], v[88:91], v[92:95], v[48:63]
	s_mov_b32 m0, s20
	v_mfma_f32_32x32x16_bf16 v[32:47], v[88:91], v[96:99], v[32:47]
	ds_read_b128 v[88:91], v80 offset:36864
	s_waitcnt lgkmcnt(0)
	v_mfma_f32_32x32x16_bf16 v[16:31], v[88:91], v[92:95], v[16:31]
	v_mfma_f32_32x32x16_bf16 v[0:15], v[88:91], v[96:99], v[0:15]
	ds_read_b128 v[88:91], v81 offset:32768
	ds_read_b128 v[92:95], v83 offset:49152
	ds_read_b128 v[96:99], v83 offset:53248
	s_waitcnt lgkmcnt(0)
	v_mfma_f32_32x32x16_bf16 v[48:63], v[88:91], v[92:95], v[48:63]
	v_mfma_f32_32x32x16_bf16 v[32:47], v[88:91], v[96:99], v[32:47]
	ds_read_b128 v[88:91], v81 offset:36864
	s_waitcnt lgkmcnt(0)
	v_mfma_f32_32x32x16_bf16 v[16:31], v[88:91], v[92:95], v[16:31]
	v_mfma_f32_32x32x16_bf16 v[0:15], v[88:91], v[96:99], v[0:15]
	ds_read_b128 v[88:91], v84 offset:32768
	ds_read_b128 v[92:95], v85 offset:49152
	ds_read_b128 v[96:99], v85 offset:53248
	s_waitcnt lgkmcnt(0)
	v_mfma_f32_32x32x16_bf16 v[48:63], v[88:91], v[92:95], v[48:63]
	v_mfma_f32_32x32x16_bf16 v[32:47], v[88:91], v[96:99], v[32:47]
	ds_read_b128 v[88:91], v84 offset:36864
	s_waitcnt lgkmcnt(0)
	v_mfma_f32_32x32x16_bf16 v[16:31], v[88:91], v[92:95], v[16:31]
	v_mfma_f32_32x32x16_bf16 v[0:15], v[88:91], v[96:99], v[0:15]
	ds_read_b128 v[88:91], v86 offset:32768
	ds_read_b128 v[92:95], v87 offset:49152
	ds_read_b128 v[96:99], v87 offset:53248
	s_waitcnt lgkmcnt(0)
	v_mfma_f32_32x32x16_bf16 v[48:63], v[88:91], v[92:95], v[48:63]
	v_mfma_f32_32x32x16_bf16 v[32:47], v[88:91], v[96:99], v[32:47]
	ds_read_b128 v[88:91], v86 offset:36864
	s_waitcnt vmcnt(0)
	s_waitcnt vmcnt(0) lgkmcnt(0)
	s_barrier
; #define WAIT_V0() asm volatile("s_waitcnt vmcnt(0)" ::: "memory")
; DI void gemm_core(char* smem, int nk, const char* Ab, const char* Bb, const unsigned (&aoff)[4], const unsigned (&boff)[4],
;                   f32x16 (&acc)[2][2]) {
;     ...
;   for (int kt = 0; kt < nk; ++kt) {
;     const int cur = kt & 1;
;     if (kt + 1 < nk) stage(cur ^ 1, kt + 1);
;     const char* sb = smem + cur * STAGE_B;
; #pragma unroll
;     for (int ks = 0; ks < 4; ++ks) {
;       bf16x8 af[2], bfr[2];
; #pragma unroll
;       for (int mb = 0; mb < 2; ++mb) af[mb] = *(const bf16x8*)(sb + a_base + mb * 4096 + xo[ks]);
; #pragma unroll
;       for (int nb = 0; nb < 2; ++nb) bfr[nb] = *(const bf16x8*)(sb + b_base + nb * 4096 + xo[ks]);
; #pragma unroll
;       for (int mb = 0; mb < 2; ++mb)
; #pragma unroll
;         for (int nb = 0; nb < 2; ++nb)
;           acc[mb][nb] = __builtin_amdgcn_mfma_f32_32x32x16_bf16(af[mb], bfr[nb], acc[mb][nb], 0, 0, 0);
;     }
;     WAIT_V0();
;     __syncthreads();
;   }
; DI void phase_gemm_in(const Params& P, int layer, char* smem) {
;     ...
;     epi_foreach(acc, [&](int row, int col, float v) __attribute__((always_inline)) {
;       const int c = n0 + col;
;       Cs[row * 136 + col] = (c >= C_QI && c < C_CQ) ? f2h(v) : f2bf(v);
;     });
	global_load_lds_dwordx4 v[64:65], off
	v_lshl_add_u64 v[64:65], v[66:67], 0, s[66:67]
	s_mov_b32 m0, s21
	v_mfma_f32_32x32x16_bf16 v[16:31], v[88:91], v[92:95], v[16:31]
	global_load_lds_dwordx4 v[64:65], off
	v_lshl_add_u64 v[64:65], v[68:69], 0, s[66:67]
	s_mov_b32 m0, s22
	s_nop 0
	global_load_lds_dwordx4 v[64:65], off
	v_lshl_add_u64 v[64:65], v[70:71], 0, s[66:67]
	s_mov_b32 m0, s1
	v_mfma_f32_32x32x16_bf16 v[0:15], v[88:91], v[96:99], v[0:15]
	global_load_lds_dwordx4 v[64:65], off
	v_lshl_add_u64 v[64:65], v[72:73], 0, s[66:67]
	s_mov_b32 m0, s16
	v_mov_b32_e32 v96, v161
	global_load_lds_dwordx4 v[64:65], off
	v_lshl_add_u64 v[64:65], v[74:75], 0, s[66:67]
	s_mov_b32 m0, s17
	v_mov_b32_e32 v97, v161
	global_load_lds_dwordx4 v[64:65], off
	v_lshl_add_u64 v[64:65], v[76:77], 0, s[66:67]
	s_mov_b32 m0, s18
	s_add_i32 s1, s10, 0xfffffa00
	global_load_lds_dwordx4 v[64:65], off
	v_lshl_add_u64 v[64:65], v[78:79], 0, s[66:67]
	s_mov_b32 m0, s19
	s_nop 0
	global_load_lds_dwordx4 v[64:65], off
	ds_read_b128 v[64:67], v80
	ds_read_b128 v[68:71], v82 offset:16384
	ds_read_b128 v[72:75], v82 offset:20480
	s_waitcnt lgkmcnt(0)
	v_mfma_f32_32x32x16_bf16 v[48:63], v[64:67], v[68:71], v[48:63]
	v_mfma_f32_32x32x16_bf16 v[32:47], v[64:67], v[72:75], v[32:47]
	ds_read_b128 v[64:67], v80 offset:4096
	s_waitcnt lgkmcnt(0)
	v_mfma_f32_32x32x16_bf16 v[16:31], v[64:67], v[68:71], v[16:31]
	v_mfma_f32_32x32x16_bf16 v[0:15], v[64:67], v[72:75], v[0:15]
	ds_read_b128 v[64:67], v81
	ds_read_b128 v[68:71], v83 offset:16384
	ds_read_b128 v[72:75], v83 offset:20480
	s_waitcnt lgkmcnt(0)
	v_mfma_f32_32x32x16_bf16 v[48:63], v[64:67], v[68:71], v[48:63]
	v_mfma_f32_32x32x16_bf16 v[32:47], v[64:67], v[72:75], v[32:47]
	ds_read_b128 v[64:67], v81 offset:4096
	s_waitcnt lgkmcnt(0)
	v_mfma_f32_32x32x16_bf16 v[16:31], v[64:67], v[68:71], v[16:31]
	v_mfma_f32_32x32x16_bf16 v[0:15], v[64:67], v[72:75], v[0:15]
	ds_read_b128 v[64:67], v84
	ds_read_b128 v[68:71], v85 offset:16384
	ds_read_b128 v[72:75], v85 offset:20480
	s_waitcnt lgkmcnt(0)
	v_mfma_f32_32x32x16_bf16 v[48:63], v[64:67], v[68:71], v[48:63]
	v_mfma_f32_32x32x16_bf16 v[32:47], v[64:67], v[72:75], v[32:47]
	ds_read_b128 v[64:67], v84 offset:4096
	s_waitcnt lgkmcnt(0)
	v_mfma_f32_32x32x16_bf16 v[16:31], v[64:67], v[68:71], v[16:31]
	v_mfma_f32_32x32x16_bf16 v[0:15], v[64:67], v[72:75], v[0:15]
	ds_read_b128 v[64:67], v86
	ds_read_b128 v[68:71], v87 offset:16384
	ds_read_b128 v[72:75], v87 offset:20480
	s_waitcnt lgkmcnt(0)
	v_mfma_f32_32x32x16_bf16 v[48:63], v[64:67], v[68:71], v[48:63]
	v_mfma_f32_32x32x16_bf16 v[32:47], v[64:67], v[72:75], v[32:47]
	ds_read_b128 v[64:67], v86 offset:4096
	s_waitcnt lgkmcnt(0)
	v_mfma_f32_32x32x16_bf16 v[16:31], v[64:67], v[68:71], v[16:31]
	v_mfma_f32_32x32x16_bf16 v[0:15], v[64:67], v[72:75], v[0:15]
	s_waitcnt vmcnt(0)
	s_barrier
	ds_read_b128 v[64:67], v80 offset:32768
	ds_read_b128 v[68:71], v82 offset:49152
	ds_read_b128 v[72:75], v82 offset:53248
	s_waitcnt lgkmcnt(1)
	v_mfma_f32_32x32x16_bf16 v[48:63], v[64:67], v[68:71], v[48:63]
	s_waitcnt lgkmcnt(0)
	v_mfma_f32_32x32x16_bf16 v[32:47], v[64:67], v[72:75], v[32:47]
	ds_read_b128 v[64:67], v80 offset:36864
	s_waitcnt lgkmcnt(0)
	v_mfma_f32_32x32x16_bf16 v[16:31], v[64:67], v[68:71], v[16:31]
	v_mfma_f32_32x32x16_bf16 v[0:15], v[64:67], v[72:75], v[0:15]
	ds_read_b128 v[64:67], v81 offset:32768
	ds_read_b128 v[68:71], v83 offset:49152
	ds_read_b128 v[72:75], v83 offset:53248
	s_waitcnt lgkmcnt(1)
	v_mfma_f32_32x32x16_bf16 v[48:63], v[64:67], v[68:71], v[48:63]
	s_waitcnt lgkmcnt(0)
	v_mfma_f32_32x32x16_bf16 v[32:47], v[64:67], v[72:75], v[32:47]
	ds_read_b128 v[64:67], v81 offset:36864
	s_waitcnt lgkmcnt(0)
	v_mfma_f32_32x32x16_bf16 v[16:31], v[64:67], v[68:71], v[16:31]
	ds_read_b128 v[68:71], v84 offset:32768
	ds_read_b128 v[76:79], v84 offset:36864
	v_mfma_f32_32x32x16_bf16 v[0:15], v[64:67], v[72:75], v[0:15]
	ds_read_b128 v[64:67], v85 offset:49152
	ds_read_b128 v[72:75], v85 offset:53248
	ds_read_b128 v[80:83], v86 offset:32768
	ds_read_b128 v[88:91], v86 offset:36864
	ds_read_b128 v[92:95], v87 offset:49152
	ds_read_b128 v[84:87], v87 offset:53248
	s_waitcnt vmcnt(0)
	s_waitcnt lgkmcnt(0)
	s_barrier
	v_mfma_f32_32x32x16_bf16 v[48:63], v[68:71], v[64:67], v[48:63]
	v_mfma_f32_32x32x16_bf16 v[48:63], v[80:83], v[92:95], v[48:63]
	v_mfma_f32_32x32x16_bf16 v[32:47], v[68:71], v[72:75], v[32:47]
	v_lshrrev_b32_e32 v69, 3, v96
	v_lshrrev_b32_e32 v68, 1, v97
	v_and_b32_e32 v69, 4, v69
	v_and_b32_e32 v70, 31, v96
	v_and_or_b32 v68, v68, s7, v69
	s_nop 5
	v_cvt_f16_f32_e32 v69, v48
	v_and_or_b32 v70, v97, 64, v70
	v_or_b32_e32 v71, s1, v70
	v_cmp_gt_u32_e64 s[40:41], s45, v71
	v_cvt_pk_bf16_f32 v48, v48, s0
	v_mfma_f32_32x32x16_bf16 v[16:31], v[76:79], v[64:67], v[16:31]
	v_cndmask_b32_e64 v69, v48, v69, s[40:41]
	v_mul_lo_u32 v48, v68, s97
	v_cvt_f16_f32_e32 v68, v49
	v_cvt_pk_bf16_f32 v49, v49, s0
	v_lshl_add_u32 v48, v70, 1, v48
	v_cvt_f16_f32_e32 v64, v51
	v_cndmask_b32_e64 v49, v49, v68, s[40:41]
	ds_write_b16 v48, v49 offset:272
	v_cvt_f16_f32_e32 v49, v50
	v_cvt_pk_bf16_f32 v50, v50, s0
	v_mfma_f32_32x32x16_bf16 v[0:15], v[76:79], v[72:75], v[0:15]
	ds_write_b16 v48, v69
	v_cndmask_b32_e64 v49, v50, v49, s[40:41]
	ds_write_b16 v48, v49 offset:544
	v_cvt_pk_bf16_f32 v49, v51, s0
	v_cndmask_b32_e64 v49, v49, v64, s[40:41]
	ds_write_b16 v48, v49 offset:816
	v_cvt_f16_f32_e32 v49, v52
	v_cvt_f16_f32_e32 v51, v53
	v_cvt_pk_bf16_f32 v50, v52, s0
	v_mfma_f32_32x32x16_bf16 v[32:47], v[80:83], v[84:87], v[32:47]
	v_cndmask_b32_e64 v49, v50, v49, s[40:41]
	v_cvt_f16_f32_e32 v50, v54
	ds_write_b16 v48, v49 offset:2176
; DI int ltid() { int t = threadIdx.x; asm volatile("" : "+v"(t)); return t; }
; template <class F>
; DI void epi_foreach(const f32x16 (&acc)[2][2], F f) {
;   const int lane = ltid() & 63, w = ltid() >> 6;
;   const int wm = w >> 1, wn = w & 1;
; #pragma unroll
;   for (int mb = 0; mb < 2; ++mb)
; #pragma unroll
;     for (int nb = 0; nb < 2; ++nb)
; #pragma unroll
;       for (int r = 0; r < 16; ++r) {
;         const int row = wm * 64 + mb * 32 + (r & 3) + 8 * (r >> 2) + 4 * (lane >> 5);
;         const int col = wn * 64 + nb * 32 + (lane & 31);
;         f(row, col, acc[mb][nb][r]);
;         if ((r & 7) == 7) __builtin_amdgcn_sched_barrier(0);
;       }
; DI void phase_gemm_in(const Params& P, int layer, char* smem) {
;     ...
;     epi_foreach(acc, [&](int row, int col, float v) __attribute__((always_inline)) {
;       const int c = n0 + col;
;       Cs[row * 136 + col] = (c >= C_QI && c < C_CQ) ? f2h(v) : f2bf(v);
;     });
	v_cvt_pk_bf16_f32 v49, v53, s0
	v_cndmask_b32_e64 v49, v49, v51, s[40:41]
	v_cvt_f16_f32_e32 v51, v55
	ds_write_b16 v48, v49 offset:2448
	v_cvt_pk_bf16_f32 v49, v54, s0
	v_cndmask_b32_e64 v49, v49, v50, s[40:41]
	ds_write_b16 v48, v49 offset:2720
	v_cvt_pk_bf16_f32 v49, v55, s0
	v_cndmask_b32_e64 v49, v49, v51, s[40:41]
	v_mfma_f32_32x32x16_bf16 v[16:31], v[88:91], v[92:95], v[16:31]
	ds_write_b16 v48, v49 offset:2992
	v_mfma_f32_32x32x16_bf16 v[0:15], v[88:91], v[84:87], v[0:15]
	v_cvt_f16_f32_e32 v49, v56
	v_cvt_pk_bf16_f32 v50, v56, s0
	v_cndmask_b32_e64 v49, v50, v49, s[40:41]
	ds_write_b16 v48, v49 offset:4352
	v_cvt_f16_f32_e32 v49, v57
	v_cvt_pk_bf16_f32 v50, v57, s0
	v_cndmask_b32_e64 v49, v50, v49, s[40:41]
	ds_write_b16 v48, v49 offset:4624
	v_cvt_f16_f32_e32 v49, v58
	v_cvt_pk_bf16_f32 v50, v58, s0
	v_cndmask_b32_e64 v49, v50, v49, s[40:41]
	ds_write_b16 v48, v49 offset:4896
	v_cvt_f16_f32_e32 v49, v59
	v_cvt_pk_bf16_f32 v50, v59, s0
	v_cndmask_b32_e64 v49, v50, v49, s[40:41]
	ds_write_b16 v48, v49 offset:5168
	v_cvt_f16_f32_e32 v49, v60
	v_cvt_pk_bf16_f32 v50, v60, s0
	v_cndmask_b32_e64 v49, v50, v49, s[40:41]
	ds_write_b16 v48, v49 offset:6528
	v_cvt_f16_f32_e32 v49, v61
	v_cvt_pk_bf16_f32 v50, v61, s0
	v_cndmask_b32_e64 v49, v50, v49, s[40:41]
	ds_write_b16 v48, v49 offset:6800
	v_cvt_f16_f32_e32 v49, v62
	v_cvt_pk_bf16_f32 v50, v62, s0
	v_cndmask_b32_e64 v49, v50, v49, s[40:41]
	ds_write_b16 v48, v49 offset:7072
	v_cvt_f16_f32_e32 v49, v63
	v_cvt_pk_bf16_f32 v50, v63, s0
	v_cndmask_b32_e64 v49, v50, v49, s[40:41]
	ds_write_b16 v48, v49 offset:7344
	s_add_i32 s1, s10, 0xfffffa20
	v_or_b32_e32 v49, s1, v70
	v_cmp_gt_u32_e32 vcc, s45, v49
	v_cvt_f16_f32_e32 v49, v32
	v_cvt_pk_bf16_f32 v32, v32, s0
	v_cndmask_b32_e32 v32, v32, v49, vcc
	ds_write_b16 v48, v32 offset:64
	v_cvt_f16_f32_e32 v32, v33
	v_cvt_pk_bf16_f32 v33, v33, s0
	v_cndmask_b32_e32 v32, v33, v32, vcc
	ds_write_b16 v48, v32 offset:336
	v_cvt_f16_f32_e32 v32, v34
	v_cvt_pk_bf16_f32 v33, v34, s0
	v_cndmask_b32_e32 v32, v33, v32, vcc
	ds_write_b16 v48, v32 offset:608
	v_cvt_f16_f32_e32 v32, v35
	v_cvt_pk_bf16_f32 v33, v35, s0
	v_cndmask_b32_e32 v32, v33, v32, vcc
	ds_write_b16 v48, v32 offset:880
	v_cvt_f16_f32_e32 v32, v36
	v_cvt_pk_bf16_f32 v33, v36, s0
	v_cndmask_b32_e32 v32, v33, v32, vcc
	ds_write_b16 v48, v32 offset:2240
	v_cvt_f16_f32_e32 v32, v37
	v_cvt_pk_bf16_f32 v33, v37, s0
	v_cndmask_b32_e32 v32, v33, v32, vcc
	ds_write_b16 v48, v32 offset:2512
	v_cvt_f16_f32_e32 v32, v38
	v_cvt_pk_bf16_f32 v33, v38, s0
	v_cndmask_b32_e32 v32, v33, v32, vcc
	ds_write_b16 v48, v32 offset:2784
	v_cvt_f16_f32_e32 v32, v39
	v_cvt_pk_bf16_f32 v33, v39, s0
	v_cndmask_b32_e32 v32, v33, v32, vcc
	ds_write_b16 v48, v32 offset:3056
	v_cvt_f16_f32_e32 v32, v40
	v_cvt_pk_bf16_f32 v33, v40, s0
	v_cndmask_b32_e32 v32, v33, v32, vcc
	ds_write_b16 v48, v32 offset:4416
	v_cvt_f16_f32_e32 v32, v41
	v_cvt_pk_bf16_f32 v33, v41, s0
	v_cndmask_b32_e32 v32, v33, v32, vcc
	ds_write_b16 v48, v32 offset:4688
	v_cvt_f16_f32_e32 v32, v42
	v_cvt_pk_bf16_f32 v33, v42, s0
	v_cndmask_b32_e32 v32, v33, v32, vcc
	ds_write_b16 v48, v32 offset:4960
	v_cvt_f16_f32_e32 v32, v43
	v_cvt_pk_bf16_f32 v33, v43, s0
	v_cndmask_b32_e32 v32, v33, v32, vcc
	ds_write_b16 v48, v32 offset:5232
	v_cvt_f16_f32_e32 v32, v44
	v_cvt_pk_bf16_f32 v33, v44, s0
	v_cndmask_b32_e32 v32, v33, v32, vcc
	ds_write_b16 v48, v32 offset:6592
	v_cvt_f16_f32_e32 v32, v45
	v_cvt_pk_bf16_f32 v33, v45, s0
	v_cndmask_b32_e32 v32, v33, v32, vcc
	ds_write_b16 v48, v32 offset:6864
	v_cvt_f16_f32_e32 v32, v46
	v_cvt_pk_bf16_f32 v33, v46, s0
	v_cndmask_b32_e32 v32, v33, v32, vcc
	ds_write_b16 v48, v32 offset:7136
	v_cvt_f16_f32_e32 v32, v47
	v_cvt_pk_bf16_f32 v33, v47, s0
	v_cndmask_b32_e32 v32, v33, v32, vcc
	ds_write_b16 v48, v32 offset:7408
	v_cvt_f16_f32_e32 v32, v16
	v_cvt_pk_bf16_f32 v16, v16, s0
	v_cndmask_b32_e64 v16, v16, v32, s[40:41]
	ds_write_b16 v48, v16 offset:8704
	v_cvt_f16_f32_e32 v16, v17
	v_cvt_pk_bf16_f32 v17, v17, s0
	v_cndmask_b32_e64 v16, v17, v16, s[40:41]
	ds_write_b16 v48, v16 offset:8976
	v_cvt_f16_f32_e32 v16, v18
	v_cvt_pk_bf16_f32 v17, v18, s0
	v_cndmask_b32_e64 v16, v17, v16, s[40:41]
	ds_write_b16 v48, v16 offset:9248
	v_cvt_f16_f32_e32 v16, v19
	v_cvt_pk_bf16_f32 v17, v19, s0
	v_cndmask_b32_e64 v16, v17, v16, s[40:41]
	ds_write_b16 v48, v16 offset:9520
	v_cvt_f16_f32_e32 v16, v20
	v_cvt_pk_bf16_f32 v17, v20, s0
	v_cndmask_b32_e64 v16, v17, v16, s[40:41]
	ds_write_b16 v48, v16 offset:10880
	v_cvt_f16_f32_e32 v16, v21
	v_cvt_pk_bf16_f32 v17, v21, s0
	v_cndmask_b32_e64 v16, v17, v16, s[40:41]
	ds_write_b16 v48, v16 offset:11152
	v_cvt_f16_f32_e32 v16, v22
	v_cvt_pk_bf16_f32 v17, v22, s0
	v_cndmask_b32_e64 v16, v17, v16, s[40:41]
	ds_write_b16 v48, v16 offset:11424
	v_cvt_f16_f32_e32 v16, v23
	v_cvt_pk_bf16_f32 v17, v23, s0
	v_cndmask_b32_e64 v16, v17, v16, s[40:41]
	ds_write_b16 v48, v16 offset:11696
	v_cvt_f16_f32_e32 v16, v24
	v_cvt_pk_bf16_f32 v17, v24, s0
	v_cndmask_b32_e64 v16, v17, v16, s[40:41]
	ds_write_b16 v48, v16 offset:13056
	v_cvt_f16_f32_e32 v16, v25
	v_cvt_pk_bf16_f32 v17, v25, s0
	v_cndmask_b32_e64 v16, v17, v16, s[40:41]
	ds_write_b16 v48, v16 offset:13328
	v_cvt_f16_f32_e32 v16, v26
	v_cvt_pk_bf16_f32 v17, v26, s0
; DI int ltid() { int t = threadIdx.x; asm volatile("" : "+v"(t)); return t; }
; DI void store_tile16(const unsigned short* Cs, unsigned short* dst, int ldd) {
;   const int tid = ltid();
; #pragma unroll
;   for (int i = 0; i < 8; ++i) {
;     const int idx = tid + 256 * i;
;     const int row = idx >> 4, c8 = (idx & 15) * 8;
;     *(u32x4*)(dst + (size_t)row * ldd + c8) = *(const u32x4*)(Cs + row * 136 + c8);
;   }
; DI void phase_gemm_in(const Params& P, int layer, char* smem) {
;     ...
;     epi_foreach(acc, [&](int row, int col, float v) __attribute__((always_inline)) {
;       const int c = n0 + col;
;       Cs[row * 136 + col] = (c >= C_QI && c < C_CQ) ? f2h(v) : f2bf(v);
;     });
;     __syncthreads();
;     store_tile16(Cs, Z + (size_t)m0 * ZLD + n0, ZLD);
;     __syncthreads();
	v_cndmask_b32_e64 v16, v17, v16, s[40:41]
	ds_write_b16 v48, v16 offset:13600
	v_cvt_f16_f32_e32 v16, v27
	v_cvt_pk_bf16_f32 v17, v27, s0
	v_cndmask_b32_e64 v16, v17, v16, s[40:41]
	ds_write_b16 v48, v16 offset:13872
	v_cvt_f16_f32_e32 v16, v28
	v_cvt_pk_bf16_f32 v17, v28, s0
	v_cndmask_b32_e64 v16, v17, v16, s[40:41]
	ds_write_b16 v48, v16 offset:15232
	v_cvt_f16_f32_e32 v16, v29
	v_cvt_pk_bf16_f32 v17, v29, s0
	v_cndmask_b32_e64 v16, v17, v16, s[40:41]
	ds_write_b16 v48, v16 offset:15504
	v_cvt_f16_f32_e32 v16, v30
	v_cvt_pk_bf16_f32 v17, v30, s0
	v_cndmask_b32_e64 v16, v17, v16, s[40:41]
	ds_write_b16 v48, v16 offset:15776
	v_cvt_f16_f32_e32 v16, v31
	v_cvt_pk_bf16_f32 v17, v31, s0
	v_cndmask_b32_e64 v16, v17, v16, s[40:41]
	ds_write_b16 v48, v16 offset:16048
	v_cvt_f16_f32_e32 v16, v0
	v_cvt_pk_bf16_f32 v0, v0, s0
	v_cndmask_b32_e32 v0, v0, v16, vcc
	ds_write_b16 v48, v0 offset:8768
	v_cvt_f16_f32_e32 v0, v1
	v_cvt_pk_bf16_f32 v1, v1, s0
	v_cndmask_b32_e32 v0, v1, v0, vcc
	ds_write_b16 v48, v0 offset:9040
	v_cvt_f16_f32_e32 v0, v2
	v_cvt_pk_bf16_f32 v1, v2, s0
	v_cndmask_b32_e32 v0, v1, v0, vcc
	ds_write_b16 v48, v0 offset:9312
	v_cvt_f16_f32_e32 v0, v3
	v_cvt_pk_bf16_f32 v1, v3, s0
	v_cndmask_b32_e32 v0, v1, v0, vcc
	ds_write_b16 v48, v0 offset:9584
	v_cvt_f16_f32_e32 v0, v4
	v_cvt_pk_bf16_f32 v1, v4, s0
	v_cndmask_b32_e32 v0, v1, v0, vcc
	ds_write_b16 v48, v0 offset:10944
	v_cvt_f16_f32_e32 v0, v5
	v_cvt_pk_bf16_f32 v1, v5, s0
	v_cndmask_b32_e32 v0, v1, v0, vcc
	ds_write_b16 v48, v0 offset:11216
	v_cvt_f16_f32_e32 v0, v6
	v_cvt_pk_bf16_f32 v1, v6, s0
	v_cndmask_b32_e32 v0, v1, v0, vcc
	ds_write_b16 v48, v0 offset:11488
	v_cvt_f16_f32_e32 v0, v7
	v_cvt_pk_bf16_f32 v1, v7, s0
	v_cndmask_b32_e32 v0, v1, v0, vcc
	ds_write_b16 v48, v0 offset:11760
	v_cvt_f16_f32_e32 v0, v8
	v_cvt_pk_bf16_f32 v1, v8, s0
	v_cndmask_b32_e32 v0, v1, v0, vcc
	ds_write_b16 v48, v0 offset:13120
	v_cvt_f16_f32_e32 v0, v9
	v_cvt_pk_bf16_f32 v1, v9, s0
	v_cndmask_b32_e32 v0, v1, v0, vcc
	ds_write_b16 v48, v0 offset:13392
	v_cvt_f16_f32_e32 v0, v10
	v_cvt_pk_bf16_f32 v1, v10, s0
	v_cndmask_b32_e32 v0, v1, v0, vcc
	ds_write_b16 v48, v0 offset:13664
	v_cvt_f16_f32_e32 v0, v11
	v_cvt_pk_bf16_f32 v1, v11, s0
	v_cndmask_b32_e32 v0, v1, v0, vcc
	ds_write_b16 v48, v0 offset:13936
	v_cvt_f16_f32_e32 v0, v12
	v_cvt_pk_bf16_f32 v1, v12, s0
	v_cndmask_b32_e32 v0, v1, v0, vcc
	ds_write_b16 v48, v0 offset:15296
	v_cvt_f16_f32_e32 v0, v13
	v_cvt_pk_bf16_f32 v1, v13, s0
	v_cndmask_b32_e32 v0, v1, v0, vcc
	ds_write_b16 v48, v0 offset:15568
	v_cvt_f16_f32_e32 v0, v14
	v_cvt_pk_bf16_f32 v1, v14, s0
	v_cndmask_b32_e32 v0, v1, v0, vcc
	ds_write_b16 v48, v0 offset:15840
	v_cvt_f16_f32_e32 v0, v15
	v_cvt_pk_bf16_f32 v1, v15, s0
	v_cndmask_b32_e32 v0, v1, v0, vcc
	ds_write_b16 v48, v0 offset:16112
	s_mul_i32 s15, s15, 0xb0000
	s_mul_hi_i32 s0, s0, 0x1600
	s_add_u32 s15, s86, s15
	s_addc_u32 s16, s87, s0
	s_lshl_b64 s[0:1], s[10:11], 1
	v_mov_b32_e32 v8, v161
	s_waitcnt lgkmcnt(0)
	s_barrier
	s_add_u32 s0, s15, s0
	s_addc_u32 s1, s16, s1
	v_lshlrev_b32_e32 v0, 4, v8
	v_and_b32_e32 v136, 0xf0, v0
	v_ashrrev_i32_e32 v6, 4, v8
	v_lshl_add_u64 v[4:5], s[0:1], 0, v[136:137]
	v_mad_u64_u32 v[0:1], s[0:1], v6, s97, v[136:137]
	ds_read_b128 v[0:3], v0
	v_mad_i64_i32 v[6:7], s[0:1], v6, s33, v[4:5]
	s_add_i32 s14, s14, s70
	s_add_i32 s13, s13, s3
	s_waitcnt lgkmcnt(0)
	global_store_dwordx4 v[6:7], v[0:3], off
	s_cmpk_gt_i32 s14, 0x15ff
	s_nop 0
	v_add_u32_e32 v0, 0x100, v8
	v_ashrrev_i32_e32 v6, 4, v0
	v_mad_u64_u32 v[0:1], s[0:1], v6, s97, v[136:137]
	ds_read_b128 v[0:3], v0
	v_mad_i64_i32 v[6:7], s[0:1], v6, s33, v[4:5]
	s_waitcnt lgkmcnt(0)
	global_store_dwordx4 v[6:7], v[0:3], off
	s_nop 1
	v_add_u32_e32 v0, 0x200, v8
	v_ashrrev_i32_e32 v6, 4, v0
	v_mad_u64_u32 v[0:1], s[0:1], v6, s97, v[136:137]
	ds_read_b128 v[0:3], v0
	v_mad_i64_i32 v[6:7], s[0:1], v6, s33, v[4:5]
	s_waitcnt lgkmcnt(0)
	global_store_dwordx4 v[6:7], v[0:3], off
	s_nop 1
	v_add_u32_e32 v0, 0x300, v8
	v_ashrrev_i32_e32 v6, 4, v0
	v_mad_u64_u32 v[0:1], s[0:1], v6, s97, v[136:137]
	ds_read_b128 v[0:3], v0
	v_mad_i64_i32 v[6:7], s[0:1], v6, s33, v[4:5]
	s_waitcnt lgkmcnt(0)
	global_store_dwordx4 v[6:7], v[0:3], off
	s_nop 1
	v_add_u32_e32 v0, 0x400, v8
	v_ashrrev_i32_e32 v6, 4, v0
	v_mad_u64_u32 v[0:1], s[0:1], v6, s97, v[136:137]
	ds_read_b128 v[0:3], v0
	v_mad_i64_i32 v[6:7], s[0:1], v6, s33, v[4:5]
	s_waitcnt lgkmcnt(0)
	global_store_dwordx4 v[6:7], v[0:3], off
	s_nop 1
	v_add_u32_e32 v0, 0x500, v8
	v_ashrrev_i32_e32 v6, 4, v0
	v_mad_u64_u32 v[0:1], s[0:1], v6, s97, v[136:137]
	ds_read_b128 v[0:3], v0
	v_mad_i64_i32 v[6:7], s[0:1], v6, s33, v[4:5]
	s_waitcnt lgkmcnt(0)
	global_store_dwordx4 v[6:7], v[0:3], off
	s_nop 1
	v_add_u32_e32 v0, 0x600, v8
	v_ashrrev_i32_e32 v6, 4, v0
	v_mad_u64_u32 v[0:1], s[0:1], v6, s97, v[136:137]
	ds_read_b128 v[0:3], v0
	v_mad_i64_i32 v[6:7], s[0:1], v6, s33, v[4:5]
	s_waitcnt lgkmcnt(0)
	global_store_dwordx4 v[6:7], v[0:3], off
	s_nop 1
	v_add_u32_e32 v0, 0x700, v8
	v_ashrrev_i32_e32 v6, 4, v0
	v_mad_u64_u32 v[0:1], s[0:1], v6, s97, v[136:137]
	ds_read_b128 v[0:3], v0
	v_mad_i64_i32 v[4:5], s[0:1], v6, s33, v[4:5]
	s_waitcnt lgkmcnt(0)
	global_store_dwordx4 v[4:5], v[0:3], off
	s_barrier
	s_cbranch_scc0 .LBB0_436
